# v49 + priority flip pair after every 4 MFMAs in all six GEMM K-loops (was every 8)
# speedup vs baseline: 1.0107x; 1.0031x over previous
; #define PG8_LDA(dst, b, h) do { if constexpr (FP8) { _Pragma("unroll") for (int m = 0; m < 4; ++m) dst##8[m] = PG8_LD8(PG8_SA(b, h), aoff, aoff1, m); } \
;         else { _Pragma("unroll") for (int m = 0; m < 4; ++m) _Pragma("unroll") for (int k = 0; k < 2; ++k) dst[m][k] = *(const LAS bf16x8*)(lds + PG8_SA(b, h) + (k ? aoff1 : aoff) + m * 2048); } } while (0)
; #define PG8_LDB(dst, b, h) do { if constexpr (FP8) { dst##8[0] = PG8_LD8(PG8_SB(b, h), boff, boff1, 0); dst##8[1] = PG8_LD8(PG8_SB(b, h), boff, boff1, 1); } \
;         else { _Pragma("unroll") for (int n = 0; n < 2; ++n) _Pragma("unroll") for (int k = 0; k < 2; ++k) dst[n][k] = *(const LAS bf16x8*)(lds + PG8_SB(b, h) + (k ? boff1 : boff) + n * 2048); } } while (0)
; #define PG8_WAIT_V(n) asm volatile("s_waitcnt vmcnt(" #n ")" ::: "memory")
; #define PG8_WAIT_L(n) asm volatile("s_waitcnt lgkmcnt(" #n ")" ::: "memory")
; #define PG8_BAR __builtin_amdgcn_s_barrier()
; #define PG8_SCHED __builtin_amdgcn_sched_barrier(0)
; #define PG8_S1 PG8_STAGE(PG8_SA(1, 1), a1 + hstepA, voffA)
; #define PG8_S2 do { PG8_STAGE(PG8_SB(0, 0), b2, voffB); PG8_STAGE(PG8_SB(0, 1), b2 + hstepB, voffB); PG8_STAGE(PG8_SA(0, 0), a2, voffA); } while (0)
; template <class Epi, class SchedT, bool ALIGN_EPI, bool SP2, bool FP8 = false>
; __device__ __forceinline__ void gemm_phase(LAS unsigned char* lds, const Gemm g, const SchedT& S, const Epi& E, const int wid) {
;     ...
;         const char* nA = has_next ? (const char*)g.A + (size_t)nxt.pm * tstepA + (size_t)nxt.aoff * 2 : cA; const char* nB = has_next ? (const char*)g.Bt + (size_t)nxt.pn * tstepB + (size_t)nxt.boff * 2 : cB;
;         const int nt = cur.nt;
;         for (int t = 0; t < nt; t += 2) {
;             const bool last = (t == nt - 2);
;             const char* a1 = cA + (size_t)(t + 1) * kstep;
;             const char* a2 = last ? nA : cA + (size_t)(t + 2) * kstep; const char* b2 = last ? nB : cB + (size_t)(t + 2) * kstep;
;             const char* a3 = a2 + kstep; const char* b3 = b2 + kstep;
;             if constexpr (SP2) {
;     ...
;             PG8_LDB(B0, 0, 0); PG8_LDB(B1, 0, 1); PG8_SCHED; PG8_LDA(At, 0, 0); PG8_S1;
;             PG8_WAIT_V(8); PG8_WAIT_L(0); PG8_BAR; PG8_MMAP(0, 0, 0); PG8_BAR; PG8_SCHED;
;             PG8_LDA(At, 0, 1); PG8_S2;
;             PG8_WAIT_V(8); PG8_WAIT_L(0); PG8_BAR; PG8_MMAP(1, 0, 1); PG8_BAR; PG8_SCHED;
.LBB0_237:
	s_ashr_i32 s47, s46, 31
	s_lshl_b64 s[8:9], s[46:47], 18
	s_add_u32 s50, s4, s8
	s_addc_u32 s51, s5, s9
	s_cmp_lt_i32 s22, 1
	s_cbranch_scc1 .LBB0_245
	s_and_b64 s[8:9], s[68:69], exec
	s_cselect_b32 s8, s51, s67
	s_cselect_b32 s9, s50, s66
	s_add_i32 s20, s22, -2
	s_add_u32 s52, s52, 0x90080
	s_addc_u32 s53, s53, 0
	s_add_u32 s21, s66, 0x100
	s_addc_u32 s24, s67, 0
	s_mov_b32 s31, 0
	ds_read_b128 v[130:133], v143
	ds_read_b128 v[134:137], v143 offset:16
	ds_read_b128 v[148:151], v143 offset:2048
	ds_read_b128 v[152:155], v143 offset:2064
	ds_read_b128 v[156:159], v144
	ds_read_b128 v[160:163], v144 offset:16
	ds_read_b128 v[164:167], v144 offset:2048
	ds_read_b128 v[168:171], v144 offset:2064
	s_add_i32 s30, s31, 2
	s_add_u32 s6, s52, 0xfff70080
	s_addc_u32 s7, s53, -1
	s_cmp_eq_u32 s20, s31
	s_cselect_b32 s67, s49, s7
	s_cselect_b32 s66, s48, s6
	v_mov_b32_e32 v128, v138
	ds_read_b128 v[172:175], v145
	ds_read_b128 v[176:179], v145 offset:16
	ds_read_b128 v[180:183], v145 offset:2048
	ds_read_b128 v[184:187], v145 offset:2064
	ds_read_b128 v[188:191], v145 offset:4096
	ds_read_b128 v[192:195], v145 offset:4112
	ds_read_b128 v[196:199], v145 offset:6144
	ds_read_b128 v[200:203], v145 offset:6160
	s_cselect_b32 s69, s8, s24
	s_cselect_b32 s68, s9, s21
	s_add_i32 m0, s87, 0xc000
	s_nop 0
	global_load_lds_dwordx4 v128, s[52:53]
	v_mov_b32_e32 v128, v140
	s_add_i32 m0, s87, 0xe000
	s_nop 0
	global_load_lds_dwordx4 v128, s[52:53]
	s_waitcnt vmcnt(8)
	s_waitcnt lgkmcnt(0)
	s_setprio 1
	s_barrier
	v_mfma_scale_f32_16x16x128_f8f6f4 v[124:127], v[130:137], v[172:179], 0, v146, v146 op_sel_hi:[0,0,0]
	v_mfma_scale_f32_16x16x128_f8f6f4 v[108:111], v[156:163], v[172:179], 0, v146, v146 op_sel_hi:[0,0,0]
	v_mfma_scale_f32_16x16x128_f8f6f4 v[120:123], v[148:155], v[172:179], 0, v146, v146 op_sel_hi:[0,0,0]
	v_mfma_scale_f32_16x16x128_f8f6f4 v[100:103], v[164:171], v[172:179], 0, v146, v146 op_sel_hi:[0,0,0]
	s_setprio 0
	s_setprio 1
	v_mfma_scale_f32_16x16x128_f8f6f4 v[116:119], v[130:137], v[180:187], 0, v146, v146 op_sel_hi:[0,0,0]
	v_mfma_scale_f32_16x16x128_f8f6f4 v[112:115], v[148:155], v[180:187], 0, v146, v146 op_sel_hi:[0,0,0]
	v_mfma_scale_f32_16x16x128_f8f6f4 v[104:107], v[130:137], v[188:195], 0, v146, v146 op_sel_hi:[0,0,0]
	v_mfma_scale_f32_16x16x128_f8f6f4 v[60:63], v[164:171], v[196:203], 0, v146, v146 op_sel_hi:[0,0,0]
	s_setprio 0
	s_setprio 1
	v_mfma_scale_f32_16x16x128_f8f6f4 v[172:175], v[156:163], v[180:187], 0, v146, v146 op_sel_hi:[0,0,0]
	v_mfma_scale_f32_16x16x128_f8f6f4 v[176:179], v[164:171], v[180:187], 0, v146, v146 op_sel_hi:[0,0,0]
	v_mfma_scale_f32_16x16x128_f8f6f4 v[180:183], v[156:163], v[188:195], 0, v146, v146 op_sel_hi:[0,0,0]
	v_mfma_scale_f32_16x16x128_f8f6f4 v[184:187], v[148:155], v[188:195], 0, v146, v146 op_sel_hi:[0,0,0]
	s_setprio 0
	s_setprio 1
	v_mfma_scale_f32_16x16x128_f8f6f4 v[188:191], v[164:171], v[188:195], 0, v146, v146 op_sel_hi:[0,0,0]
	v_mfma_scale_f32_16x16x128_f8f6f4 v[192:195], v[130:137], v[196:203], 0, v146, v146 op_sel_hi:[0,0,0]
	v_mfma_scale_f32_16x16x128_f8f6f4 v[204:207], v[156:163], v[196:203], 0, v146, v146 op_sel_hi:[0,0,0]
	v_mfma_scale_f32_16x16x128_f8f6f4 v[208:211], v[148:155], v[196:203], 0, v146, v146 op_sel_hi:[0,0,0]
	s_barrier
	s_setprio 0
	v_mov_b32_e32 v128, v139
	s_add_i32 s6, s94, s86
	s_nop 1
	ds_read_b128 v[68:71], v145 offset:16384
	ds_read_b128 v[72:75], v145 offset:16400
	ds_read_b128 v[76:79], v145 offset:18432
	ds_read_b128 v[80:83], v145 offset:18448
	ds_read_b128 v[84:87], v145 offset:20480
	ds_read_b128 v[88:91], v145 offset:20496
	ds_read_b128 v[92:95], v145 offset:22528
	ds_read_b128 v[96:99], v145 offset:22544
	s_mov_b32 m0, s6
	s_nop 0
	global_load_lds_dwordx4 v128, s[68:69]
	v_mov_b32_e32 v128, v141
	s_add_i32 m0, s6, 0x2000
	s_add_u32 s38, s68, 0x20000
	global_load_lds_dwordx4 v128, s[68:69]
	s_addc_u32 s39, s69, 0
	v_mov_b32_e32 v128, v139
	s_add_i32 s6, s95, s86
	s_mov_b32 m0, s6
	s_nop 0
	global_load_lds_dwordx4 v128, s[38:39]
	v_mov_b32_e32 v128, v141
	s_add_i32 m0, s6, 0x2000
	s_nop 0
	global_load_lds_dwordx4 v128, s[38:39]
	v_mov_b32_e32 v128, v138
	s_mov_b32 m0, s87
	s_nop 0
	global_load_lds_dwordx4 v128, s[66:67]
	v_mov_b32_e32 v128, v140
	s_mov_b32 m0, s88
	s_nop 0
	global_load_lds_dwordx4 v128, s[66:67]
	s_waitcnt vmcnt(8)
	s_waitcnt lgkmcnt(0)
	s_setprio 1
	s_barrier
	v_mfma_scale_f32_16x16x128_f8f6f4 v[64:67], v[130:137], v[68:75], 0, v146, v146 op_sel_hi:[0,0,0]
	v_mfma_scale_f32_16x16x128_f8f6f4 v[44:47], v[156:163], v[68:75], 0, v146, v146 op_sel_hi:[0,0,0]
	v_mfma_scale_f32_16x16x128_f8f6f4 v[56:59], v[148:155], v[68:75], 0, v146, v146 op_sel_hi:[0,0,0]
	v_mfma_scale_f32_16x16x128_f8f6f4 v[52:55], v[130:137], v[76:83], 0, v146, v146 op_sel_hi:[0,0,0]
	s_setprio 0
	s_setprio 1
	v_mfma_scale_f32_16x16x128_f8f6f4 v[48:51], v[148:155], v[76:83], 0, v146, v146 op_sel_hi:[0,0,0]
	v_mfma_scale_f32_16x16x128_f8f6f4 v[40:43], v[130:137], v[84:91], 0, v146, v146 op_sel_hi:[0,0,0]
	v_mfma_scale_f32_16x16x128_f8f6f4 v[196:199], v[164:171], v[68:75], 0, v146, v146 op_sel_hi:[0,0,0]
	v_mfma_scale_f32_16x16x128_f8f6f4 v[200:203], v[156:163], v[76:83], 0, v146, v146 op_sel_hi:[0,0,0]
	s_setprio 0
	s_setprio 1
	v_mfma_scale_f32_16x16x128_f8f6f4 v[212:215], v[164:171], v[76:83], 0, v146, v146 op_sel_hi:[0,0,0]
	v_mfma_scale_f32_16x16x128_f8f6f4 v[216:219], v[156:163], v[84:91], 0, v146, v146 op_sel_hi:[0,0,0]
	v_mfma_scale_f32_16x16x128_f8f6f4 v[220:223], v[148:155], v[84:91], 0, v146, v146 op_sel_hi:[0,0,0]
	v_mfma_scale_f32_16x16x128_f8f6f4 v[224:227], v[164:171], v[84:91], 0, v146, v146 op_sel_hi:[0,0,0]
	s_setprio 0
	s_setprio 1
	v_mfma_scale_f32_16x16x128_f8f6f4 v[228:231], v[130:137], v[92:99], 0, v146, v146 op_sel_hi:[0,0,0]
	v_mfma_scale_f32_16x16x128_f8f6f4 v[232:235], v[156:163], v[92:99], 0, v146, v146 op_sel_hi:[0,0,0]
	v_mfma_scale_f32_16x16x128_f8f6f4 v[236:239], v[148:155], v[92:99], 0, v146, v146 op_sel_hi:[0,0,0]
	v_mfma_scale_f32_16x16x128_f8f6f4 v[240:243], v[164:171], v[92:99], 0, v146, v146 op_sel_hi:[0,0,0]
	s_barrier
; #define PG8_LDA(dst, b, h) do { if constexpr (FP8) { _Pragma("unroll") for (int m = 0; m < 4; ++m) dst##8[m] = PG8_LD8(PG8_SA(b, h), aoff, aoff1, m); } \
;         else { _Pragma("unroll") for (int m = 0; m < 4; ++m) _Pragma("unroll") for (int k = 0; k < 2; ++k) dst[m][k] = *(const LAS bf16x8*)(lds + PG8_SA(b, h) + (k ? aoff1 : aoff) + m * 2048); } } while (0)
; #define PG8_LDB(dst, b, h) do { if constexpr (FP8) { dst##8[0] = PG8_LD8(PG8_SB(b, h), boff, boff1, 0); dst##8[1] = PG8_LD8(PG8_SB(b, h), boff, boff1, 1); } \
;         else { _Pragma("unroll") for (int n = 0; n < 2; ++n) _Pragma("unroll") for (int k = 0; k < 2; ++k) dst[n][k] = *(const LAS bf16x8*)(lds + PG8_SB(b, h) + (k ? boff1 : boff) + n * 2048); } } while (0)
; #define PG8_WAIT_V(n) asm volatile("s_waitcnt vmcnt(" #n ")" ::: "memory")
; #define PG8_WAIT_L(n) asm volatile("s_waitcnt lgkmcnt(" #n ")" ::: "memory")
; #define PG8_BAR __builtin_amdgcn_s_barrier()
; #define PG8_SCHED __builtin_amdgcn_sched_barrier(0)
; #define PG8_S3 PG8_STAGE(PG8_SA(0, 1), a2 + hstepA, voffA)
; #define PG8_S4 do { PG8_STAGE(PG8_SB(1, 0), b3, voffB); PG8_STAGE(PG8_SB(1, 1), b3 + hstepB, voffB); PG8_STAGE(PG8_SA(1, 0), a3, voffA); } while (0)
; template <class Epi, class SchedT, bool ALIGN_EPI, bool SP2, bool FP8 = false>
; __device__ __forceinline__ void gemm_phase(LAS unsigned char* lds, const Gemm g, const SchedT& S, const Epi& E, const int wid) {
;     ...
;             PG8_LDB(B0, 1, 0); PG8_LDB(B1, 1, 1); PG8_SCHED; PG8_LDA(At, 1, 0); PG8_S3;
;             PG8_WAIT_V(8); PG8_WAIT_L(0); PG8_BAR; PG8_MMAP(0, 1, 0); PG8_BAR; PG8_SCHED;
;             PG8_LDA(At, 1, 1); PG8_S4;
;             PG8_WAIT_V(8); PG8_WAIT_L(0); PG8_BAR; PG8_MMAP(1, 1, 1); PG8_BAR; PG8_SCHED;
	s_setprio 0
	s_add_i32 s6, 0, 0x18000
	v_add_u32_e32 v8, s6, v142
	s_add_i32 s7, 0, 0x1c000
	s_nop 1
	ds_read_b128 v[0:3], v8
	ds_read_b128 v[4:7], v8 offset:16
	ds_read_b128 v[130:133], v8 offset:2048
	ds_read_b128 v[134:137], v8 offset:2064
	v_add_u32_e32 v8, s7, v142
	ds_read_b128 v[148:151], v8
	ds_read_b128 v[152:155], v8 offset:16
	ds_read_b128 v[156:159], v8 offset:2048
	ds_read_b128 v[160:163], v8 offset:2064
	s_add_u32 s38, s66, 0x90000
	v_mov_b32_e32 v68, v138
	s_mov_b32 m0, s89
	ds_read_b128 v[8:11], v145 offset:32768
	ds_read_b128 v[12:15], v145 offset:32784
	ds_read_b128 v[16:19], v145 offset:34816
	ds_read_b128 v[20:23], v145 offset:34832
	ds_read_b128 v[24:27], v145 offset:36864
	ds_read_b128 v[28:31], v145 offset:36880
	ds_read_b128 v[32:35], v145 offset:38912
	ds_read_b128 v[36:39], v145 offset:38928
	s_addc_u32 s39, s67, 0
	s_nop 0
	global_load_lds_dwordx4 v68, s[38:39]
	v_mov_b32_e32 v68, v140
	s_mov_b32 m0, s90
	s_nop 0
	global_load_lds_dwordx4 v68, s[38:39]
	s_waitcnt vmcnt(8)
	s_waitcnt lgkmcnt(0)
	s_setprio 1
	s_barrier
	v_mfma_scale_f32_16x16x128_f8f6f4 v[124:127], v[0:7], v[8:15], v[124:127], v146, v146 op_sel_hi:[0,0,0]
	v_mfma_scale_f32_16x16x128_f8f6f4 v[108:111], v[148:155], v[8:15], v[108:111], v146, v146 op_sel_hi:[0,0,0]
	v_mfma_scale_f32_16x16x128_f8f6f4 v[120:123], v[130:137], v[8:15], v[120:123], v146, v146 op_sel_hi:[0,0,0]
	v_mfma_scale_f32_16x16x128_f8f6f4 v[100:103], v[156:163], v[8:15], v[100:103], v146, v146 op_sel_hi:[0,0,0]
	s_setprio 0
	s_setprio 1
	v_mfma_scale_f32_16x16x128_f8f6f4 v[116:119], v[0:7], v[16:23], v[116:119], v146, v146 op_sel_hi:[0,0,0]
	v_mfma_scale_f32_16x16x128_f8f6f4 v[92:95], v[148:155], v[16:23], v[172:175], v146, v146 op_sel_hi:[0,0,0]
	v_mfma_scale_f32_16x16x128_f8f6f4 v[112:115], v[130:137], v[16:23], v[112:115], v146, v146 op_sel_hi:[0,0,0]
	v_mfma_scale_f32_16x16x128_f8f6f4 v[84:87], v[156:163], v[16:23], v[176:179], v146, v146 op_sel_hi:[0,0,0]
	s_setprio 0
	s_setprio 1
	v_mfma_scale_f32_16x16x128_f8f6f4 v[104:107], v[0:7], v[24:31], v[104:107], v146, v146 op_sel_hi:[0,0,0]
	v_mfma_scale_f32_16x16x128_f8f6f4 v[76:79], v[148:155], v[24:31], v[180:183], v146, v146 op_sel_hi:[0,0,0]
	v_mfma_scale_f32_16x16x128_f8f6f4 v[96:99], v[130:137], v[24:31], v[184:187], v146, v146 op_sel_hi:[0,0,0]
	v_mfma_scale_f32_16x16x128_f8f6f4 v[72:75], v[156:163], v[24:31], v[188:191], v146, v146 op_sel_hi:[0,0,0]
	s_setprio 0
	s_setprio 1
	v_mfma_scale_f32_16x16x128_f8f6f4 v[88:91], v[0:7], v[32:39], v[192:195], v146, v146 op_sel_hi:[0,0,0]
	v_mfma_scale_f32_16x16x128_f8f6f4 v[68:71], v[148:155], v[32:39], v[204:207], v146, v146 op_sel_hi:[0,0,0]
	v_mfma_scale_f32_16x16x128_f8f6f4 v[80:83], v[130:137], v[32:39], v[208:211], v146, v146 op_sel_hi:[0,0,0]
	v_mfma_scale_f32_16x16x128_f8f6f4 v[60:63], v[156:163], v[32:39], v[60:63], v146, v146 op_sel_hi:[0,0,0]
	s_barrier
	s_setprio 0
	v_mov_b32_e32 v128, v139
	ds_read_b128 v[8:11], v145 offset:49152
	ds_read_b128 v[12:15], v145 offset:49168
	ds_read_b128 v[16:19], v145 offset:51200
	ds_read_b128 v[20:23], v145 offset:51216
	ds_read_b128 v[164:167], v145 offset:53248
	ds_read_b128 v[168:171], v145 offset:53264
	ds_read_b128 v[172:175], v145 offset:55296
	ds_read_b128 v[176:179], v145 offset:55312
	s_add_i32 s6, s6, s86
	v_lshl_add_u64 v[24:25], s[68:69], 0, v[128:129]
	v_lshl_add_u64 v[24:25], v[24:25], 0, s[40:41]
	s_mov_b32 m0, s6
	v_mov_b32_e32 v128, v141
	global_load_lds_dwordx4 v[24:25], off
	s_add_i32 m0, s6, 0x2000
	v_lshl_add_u64 v[24:25], s[68:69], 0, v[128:129]
	v_lshl_add_u64 v[24:25], v[24:25], 0, s[40:41]
	s_add_u32 s38, s68, 0x20080
	global_load_lds_dwordx4 v[24:25], off
	s_addc_u32 s39, s69, 0
	v_mov_b32_e32 v24, v139
	s_add_i32 s6, s7, s86
	s_mov_b32 m0, s6
	v_mov_b32_e32 v128, v138
	global_load_lds_dwordx4 v24, s[38:39]
	v_mov_b32_e32 v24, v141
	s_add_i32 m0, s6, 0x2000
	s_nop 0
	global_load_lds_dwordx4 v24, s[38:39]
	s_mov_b32 m0, s92
	v_lshl_add_u64 v[24:25], s[66:67], 0, v[128:129]
	v_lshl_add_u64 v[24:25], v[24:25], 0, s[40:41]
	v_mov_b32_e32 v128, v140
	global_load_lds_dwordx4 v[24:25], off
	s_mov_b32 m0, s93
	v_lshl_add_u64 v[24:25], s[66:67], 0, v[128:129]
	v_lshl_add_u64 v[24:25], v[24:25], 0, s[40:41]
	global_load_lds_dwordx4 v[24:25], off
	s_waitcnt vmcnt(8)
	s_waitcnt lgkmcnt(0)
	s_setprio 1
	s_barrier
	v_mfma_scale_f32_16x16x128_f8f6f4 v[64:67], v[0:7], v[8:15], v[64:67], v146, v146 op_sel_hi:[0,0,0]
	v_mfma_scale_f32_16x16x128_f8f6f4 v[44:47], v[148:155], v[8:15], v[44:47], v146, v146 op_sel_hi:[0,0,0]
	v_mfma_scale_f32_16x16x128_f8f6f4 v[56:59], v[130:137], v[8:15], v[56:59], v146, v146 op_sel_hi:[0,0,0]
	v_mfma_scale_f32_16x16x128_f8f6f4 v[36:39], v[156:163], v[8:15], v[196:199], v146, v146 op_sel_hi:[0,0,0]
	s_setprio 0
	s_setprio 1
	v_mfma_scale_f32_16x16x128_f8f6f4 v[52:55], v[0:7], v[16:23], v[52:55], v146, v146 op_sel_hi:[0,0,0]
	v_mfma_scale_f32_16x16x128_f8f6f4 v[28:31], v[148:155], v[16:23], v[200:203], v146, v146 op_sel_hi:[0,0,0]
	v_mfma_scale_f32_16x16x128_f8f6f4 v[48:51], v[130:137], v[16:23], v[48:51], v146, v146 op_sel_hi:[0,0,0]
	v_mfma_scale_f32_16x16x128_f8f6f4 v[20:23], v[156:163], v[16:23], v[212:215], v146, v146 op_sel_hi:[0,0,0]
	s_setprio 0
	s_setprio 1
	v_mfma_scale_f32_16x16x128_f8f6f4 v[40:43], v[0:7], v[164:171], v[40:43], v146, v146 op_sel_hi:[0,0,0]
	v_mfma_scale_f32_16x16x128_f8f6f4 v[12:15], v[148:155], v[164:171], v[216:219], v146, v146 op_sel_hi:[0,0,0]
	v_mfma_scale_f32_16x16x128_f8f6f4 v[32:35], v[130:137], v[164:171], v[220:223], v146, v146 op_sel_hi:[0,0,0]
	v_mfma_scale_f32_16x16x128_f8f6f4 v[8:11], v[156:163], v[164:171], v[224:227], v146, v146 op_sel_hi:[0,0,0]
	s_setprio 0
	s_setprio 1
	v_mfma_scale_f32_16x16x128_f8f6f4 v[24:27], v[0:7], v[172:179], v[228:231], v146, v146 op_sel_hi:[0,0,0]
	v_mfma_scale_f32_16x16x128_f8f6f4 v[4:7], v[148:155], v[172:179], v[232:235], v146, v146 op_sel_hi:[0,0,0]
	v_mfma_scale_f32_16x16x128_f8f6f4 v[16:19], v[130:137], v[172:179], v[236:239], v146, v146 op_sel_hi:[0,0,0]
	v_mfma_scale_f32_16x16x128_f8f6f4 v[0:3], v[156:163], v[172:179], v[240:243], v146, v146 op_sel_hi:[0,0,0]
	s_barrier
	s_setprio 0
	s_add_u32 s52, s52, 0x100
	s_addc_u32 s53, s53, 0
	s_add_u32 s21, s21, 0x100
	s_addc_u32 s24, s24, 0
	s_cmp_ge_i32 s30, s22
	s_mov_b32 s31, s30
	s_cbranch_scc1 .Lpeel_exit_lbb0_239
; #define PG8_LDA(dst, b, h) do { if constexpr (FP8) { _Pragma("unroll") for (int m = 0; m < 4; ++m) dst##8[m] = PG8_LD8(PG8_SA(b, h), aoff, aoff1, m); } \
;         else { _Pragma("unroll") for (int m = 0; m < 4; ++m) _Pragma("unroll") for (int k = 0; k < 2; ++k) dst[m][k] = *(const LAS bf16x8*)(lds + PG8_SA(b, h) + (k ? aoff1 : aoff) + m * 2048); } } while (0)
; #define PG8_LDB(dst, b, h) do { if constexpr (FP8) { dst##8[0] = PG8_LD8(PG8_SB(b, h), boff, boff1, 0); dst##8[1] = PG8_LD8(PG8_SB(b, h), boff, boff1, 1); } \
;         else { _Pragma("unroll") for (int n = 0; n < 2; ++n) _Pragma("unroll") for (int k = 0; k < 2; ++k) dst[n][k] = *(const LAS bf16x8*)(lds + PG8_SB(b, h) + (k ? boff1 : boff) + n * 2048); } } while (0)
; #define PG8_WAIT_V(n) asm volatile("s_waitcnt vmcnt(" #n ")" ::: "memory")
; #define PG8_WAIT_L(n) asm volatile("s_waitcnt lgkmcnt(" #n ")" ::: "memory")
; #define PG8_BAR __builtin_amdgcn_s_barrier()
; #define PG8_SCHED __builtin_amdgcn_sched_barrier(0)
; #define PG8_S1 PG8_STAGE(PG8_SA(1, 1), a1 + hstepA, voffA)
; #define PG8_S2 do { PG8_STAGE(PG8_SB(0, 0), b2, voffB); PG8_STAGE(PG8_SB(0, 1), b2 + hstepB, voffB); PG8_STAGE(PG8_SA(0, 0), a2, voffA); } while (0)
; template <class Epi, class SchedT, bool ALIGN_EPI, bool SP2, bool FP8 = false>
; __device__ __forceinline__ void gemm_phase(LAS unsigned char* lds, const Gemm g, const SchedT& S, const Epi& E, const int wid) {
;     ...
;         for (int t = 0; t < nt; t += 2) {
;             const bool last = (t == nt - 2);
;             const char* a1 = cA + (size_t)(t + 1) * kstep;
;             const char* a2 = last ? nA : cA + (size_t)(t + 2) * kstep; const char* b2 = last ? nB : cB + (size_t)(t + 2) * kstep;
;             const char* a3 = a2 + kstep; const char* b3 = b2 + kstep;
;             if constexpr (SP2) {
;     ...
;             PG8_LDB(B0, 0, 0); PG8_LDB(B1, 0, 1); PG8_SCHED; PG8_LDA(At, 0, 0); PG8_S1;
;             PG8_WAIT_V(8); PG8_WAIT_L(0); PG8_BAR; PG8_MMAP(0, 0, 0); PG8_BAR; PG8_SCHED;
;             PG8_LDA(At, 0, 1); PG8_S2;
;             PG8_WAIT_V(8); PG8_WAIT_L(0); PG8_BAR; PG8_MMAP(1, 0, 1); PG8_BAR; PG8_SCHED;
.LBB0_239:
	ds_read_b128 v[130:133], v143
	ds_read_b128 v[134:137], v143 offset:16
	ds_read_b128 v[148:151], v143 offset:2048
	ds_read_b128 v[152:155], v143 offset:2064
	ds_read_b128 v[156:159], v144
	ds_read_b128 v[160:163], v144 offset:16
	ds_read_b128 v[164:167], v144 offset:2048
	ds_read_b128 v[168:171], v144 offset:2064
	s_add_i32 s30, s31, 2
	s_add_u32 s6, s52, 0xfff70080
	s_addc_u32 s7, s53, -1
	s_cmp_eq_u32 s20, s31
	s_cselect_b32 s67, s49, s7
	s_cselect_b32 s66, s48, s6
	v_mov_b32_e32 v128, v138
	ds_read_b128 v[172:175], v145
	ds_read_b128 v[176:179], v145 offset:16
	ds_read_b128 v[180:183], v145 offset:2048
	ds_read_b128 v[184:187], v145 offset:2064
	ds_read_b128 v[188:191], v145 offset:4096
	ds_read_b128 v[192:195], v145 offset:4112
	ds_read_b128 v[196:199], v145 offset:6144
	ds_read_b128 v[200:203], v145 offset:6160
	s_cselect_b32 s69, s8, s24
	s_cselect_b32 s68, s9, s21
	s_add_i32 m0, s87, 0xc000
	s_nop 0
	global_load_lds_dwordx4 v128, s[52:53]
	v_mov_b32_e32 v128, v140
	s_add_i32 m0, s87, 0xe000
	s_nop 0
	global_load_lds_dwordx4 v128, s[52:53]
	s_waitcnt vmcnt(8)
	s_waitcnt lgkmcnt(0)
	s_setprio 1
	s_barrier
	v_mfma_scale_f32_16x16x128_f8f6f4 v[124:127], v[130:137], v[172:179], v[124:127], v146, v146 op_sel_hi:[0,0,0]
	v_mfma_scale_f32_16x16x128_f8f6f4 v[108:111], v[156:163], v[172:179], v[108:111], v146, v146 op_sel_hi:[0,0,0]
	v_mfma_scale_f32_16x16x128_f8f6f4 v[120:123], v[148:155], v[172:179], v[120:123], v146, v146 op_sel_hi:[0,0,0]
	v_mfma_scale_f32_16x16x128_f8f6f4 v[100:103], v[164:171], v[172:179], v[100:103], v146, v146 op_sel_hi:[0,0,0]
	s_setprio 0
	s_setprio 1
	v_mfma_scale_f32_16x16x128_f8f6f4 v[116:119], v[130:137], v[180:187], v[116:119], v146, v146 op_sel_hi:[0,0,0]
	v_mfma_scale_f32_16x16x128_f8f6f4 v[112:115], v[148:155], v[180:187], v[112:115], v146, v146 op_sel_hi:[0,0,0]
	v_mfma_scale_f32_16x16x128_f8f6f4 v[104:107], v[130:137], v[188:195], v[104:107], v146, v146 op_sel_hi:[0,0,0]
	v_mfma_scale_f32_16x16x128_f8f6f4 v[60:63], v[164:171], v[196:203], v[60:63], v146, v146 op_sel_hi:[0,0,0]
	s_setprio 0
	s_setprio 1
	v_mfma_scale_f32_16x16x128_f8f6f4 v[172:175], v[156:163], v[180:187], v[92:95], v146, v146 op_sel_hi:[0,0,0]
	v_mfma_scale_f32_16x16x128_f8f6f4 v[176:179], v[164:171], v[180:187], v[84:87], v146, v146 op_sel_hi:[0,0,0]
	v_mfma_scale_f32_16x16x128_f8f6f4 v[180:183], v[156:163], v[188:195], v[76:79], v146, v146 op_sel_hi:[0,0,0]
	v_mfma_scale_f32_16x16x128_f8f6f4 v[184:187], v[148:155], v[188:195], v[96:99], v146, v146 op_sel_hi:[0,0,0]
	s_setprio 0
	s_setprio 1
	v_mfma_scale_f32_16x16x128_f8f6f4 v[188:191], v[164:171], v[188:195], v[72:75], v146, v146 op_sel_hi:[0,0,0]
	v_mfma_scale_f32_16x16x128_f8f6f4 v[192:195], v[130:137], v[196:203], v[88:91], v146, v146 op_sel_hi:[0,0,0]
	v_mfma_scale_f32_16x16x128_f8f6f4 v[204:207], v[156:163], v[196:203], v[68:71], v146, v146 op_sel_hi:[0,0,0]
	v_mfma_scale_f32_16x16x128_f8f6f4 v[208:211], v[148:155], v[196:203], v[80:83], v146, v146 op_sel_hi:[0,0,0]
	s_barrier
	s_setprio 0
	v_mov_b32_e32 v128, v139
	s_add_i32 s6, s94, s86
	s_nop 1
	ds_read_b128 v[68:71], v145 offset:16384
	ds_read_b128 v[72:75], v145 offset:16400
	ds_read_b128 v[76:79], v145 offset:18432
	ds_read_b128 v[80:83], v145 offset:18448
	ds_read_b128 v[84:87], v145 offset:20480
	ds_read_b128 v[88:91], v145 offset:20496
	ds_read_b128 v[92:95], v145 offset:22528
	ds_read_b128 v[96:99], v145 offset:22544
	s_mov_b32 m0, s6
	s_nop 0
	global_load_lds_dwordx4 v128, s[68:69]
	v_mov_b32_e32 v128, v141
	s_add_i32 m0, s6, 0x2000
	s_add_u32 s38, s68, 0x20000
	global_load_lds_dwordx4 v128, s[68:69]
	s_addc_u32 s39, s69, 0
	v_mov_b32_e32 v128, v139
	s_add_i32 s6, s95, s86
	s_mov_b32 m0, s6
	s_nop 0
	global_load_lds_dwordx4 v128, s[38:39]
	v_mov_b32_e32 v128, v141
	s_add_i32 m0, s6, 0x2000
	s_nop 0
	global_load_lds_dwordx4 v128, s[38:39]
	v_mov_b32_e32 v128, v138
	s_mov_b32 m0, s87
	s_nop 0
	global_load_lds_dwordx4 v128, s[66:67]
	v_mov_b32_e32 v128, v140
	s_mov_b32 m0, s88
	s_nop 0
	global_load_lds_dwordx4 v128, s[66:67]
	s_waitcnt vmcnt(8)
	s_waitcnt lgkmcnt(0)
	s_setprio 1
	s_barrier
	v_mfma_scale_f32_16x16x128_f8f6f4 v[64:67], v[130:137], v[68:75], v[64:67], v146, v146 op_sel_hi:[0,0,0]
	v_mfma_scale_f32_16x16x128_f8f6f4 v[44:47], v[156:163], v[68:75], v[44:47], v146, v146 op_sel_hi:[0,0,0]
	v_mfma_scale_f32_16x16x128_f8f6f4 v[56:59], v[148:155], v[68:75], v[56:59], v146, v146 op_sel_hi:[0,0,0]
	v_mfma_scale_f32_16x16x128_f8f6f4 v[52:55], v[130:137], v[76:83], v[52:55], v146, v146 op_sel_hi:[0,0,0]
	s_setprio 0
	s_setprio 1
	v_mfma_scale_f32_16x16x128_f8f6f4 v[48:51], v[148:155], v[76:83], v[48:51], v146, v146 op_sel_hi:[0,0,0]
	v_mfma_scale_f32_16x16x128_f8f6f4 v[40:43], v[130:137], v[84:91], v[40:43], v146, v146 op_sel_hi:[0,0,0]
	v_mfma_scale_f32_16x16x128_f8f6f4 v[196:199], v[164:171], v[68:75], v[36:39], v146, v146 op_sel_hi:[0,0,0]
	v_mfma_scale_f32_16x16x128_f8f6f4 v[200:203], v[156:163], v[76:83], v[28:31], v146, v146 op_sel_hi:[0,0,0]
	s_setprio 0
	s_setprio 1
	v_mfma_scale_f32_16x16x128_f8f6f4 v[212:215], v[164:171], v[76:83], v[20:23], v146, v146 op_sel_hi:[0,0,0]
	v_mfma_scale_f32_16x16x128_f8f6f4 v[216:219], v[156:163], v[84:91], v[12:15], v146, v146 op_sel_hi:[0,0,0]
	v_mfma_scale_f32_16x16x128_f8f6f4 v[220:223], v[148:155], v[84:91], v[32:35], v146, v146 op_sel_hi:[0,0,0]
	v_mfma_scale_f32_16x16x128_f8f6f4 v[224:227], v[164:171], v[84:91], v[8:11], v146, v146 op_sel_hi:[0,0,0]
	s_setprio 0
	s_setprio 1
	v_mfma_scale_f32_16x16x128_f8f6f4 v[228:231], v[130:137], v[92:99], v[24:27], v146, v146 op_sel_hi:[0,0,0]
	v_mfma_scale_f32_16x16x128_f8f6f4 v[232:235], v[156:163], v[92:99], v[4:7], v146, v146 op_sel_hi:[0,0,0]
	v_mfma_scale_f32_16x16x128_f8f6f4 v[236:239], v[148:155], v[92:99], v[16:19], v146, v146 op_sel_hi:[0,0,0]
	v_mfma_scale_f32_16x16x128_f8f6f4 v[240:243], v[164:171], v[92:99], v[0:3], v146, v146 op_sel_hi:[0,0,0]
	s_barrier
; #define PG8_LDA(dst, b, h) do { if constexpr (FP8) { _Pragma("unroll") for (int m = 0; m < 4; ++m) dst##8[m] = PG8_LD8(PG8_SA(b, h), aoff, aoff1, m); } \
;         else { _Pragma("unroll") for (int m = 0; m < 4; ++m) _Pragma("unroll") for (int k = 0; k < 2; ++k) dst[m][k] = *(const LAS bf16x8*)(lds + PG8_SA(b, h) + (k ? aoff1 : aoff) + m * 2048); } } while (0)
; #define PG8_LDB(dst, b, h) do { if constexpr (FP8) { dst##8[0] = PG8_LD8(PG8_SB(b, h), boff, boff1, 0); dst##8[1] = PG8_LD8(PG8_SB(b, h), boff, boff1, 1); } \
;         else { _Pragma("unroll") for (int n = 0; n < 2; ++n) _Pragma("unroll") for (int k = 0; k < 2; ++k) dst[n][k] = *(const LAS bf16x8*)(lds + PG8_SB(b, h) + (k ? boff1 : boff) + n * 2048); } } while (0)
; #define PG8_WAIT_V(n) asm volatile("s_waitcnt vmcnt(" #n ")" ::: "memory")
; #define PG8_WAIT_L(n) asm volatile("s_waitcnt lgkmcnt(" #n ")" ::: "memory")
; #define PG8_BAR __builtin_amdgcn_s_barrier()
; #define PG8_SCHED __builtin_amdgcn_sched_barrier(0)
; #define PG8_S3 PG8_STAGE(PG8_SA(0, 1), a2 + hstepA, voffA)
; #define PG8_S4 do { PG8_STAGE(PG8_SB(1, 0), b3, voffB); PG8_STAGE(PG8_SB(1, 1), b3 + hstepB, voffB); PG8_STAGE(PG8_SA(1, 0), a3, voffA); } while (0)
; template <class Epi, class SchedT, bool ALIGN_EPI, bool SP2, bool FP8 = false>
; __device__ __forceinline__ void gemm_phase(LAS unsigned char* lds, const Gemm g, const SchedT& S, const Epi& E, const int wid) {
;     ...
;             PG8_LDB(B0, 1, 0); PG8_LDB(B1, 1, 1); PG8_SCHED; PG8_LDA(At, 1, 0); PG8_S3;
;             PG8_WAIT_V(8); PG8_WAIT_L(0); PG8_BAR; PG8_MMAP(0, 1, 0); PG8_BAR; PG8_SCHED;
;             PG8_LDA(At, 1, 1); PG8_S4;
;             PG8_WAIT_V(8); PG8_WAIT_L(0); PG8_BAR; PG8_MMAP(1, 1, 1); PG8_BAR; PG8_SCHED;
	s_setprio 0
	s_add_i32 s6, 0, 0x18000
	v_add_u32_e32 v8, s6, v142
	s_add_i32 s7, 0, 0x1c000
	s_nop 1
	ds_read_b128 v[0:3], v8
	ds_read_b128 v[4:7], v8 offset:16
	ds_read_b128 v[130:133], v8 offset:2048
	ds_read_b128 v[134:137], v8 offset:2064
	v_add_u32_e32 v8, s7, v142
	ds_read_b128 v[148:151], v8
	ds_read_b128 v[152:155], v8 offset:16
	ds_read_b128 v[156:159], v8 offset:2048
	ds_read_b128 v[160:163], v8 offset:2064
	s_add_u32 s38, s66, 0x90000
	v_mov_b32_e32 v68, v138
	s_mov_b32 m0, s89
	ds_read_b128 v[8:11], v145 offset:32768
	ds_read_b128 v[12:15], v145 offset:32784
	ds_read_b128 v[16:19], v145 offset:34816
	ds_read_b128 v[20:23], v145 offset:34832
	ds_read_b128 v[24:27], v145 offset:36864
	ds_read_b128 v[28:31], v145 offset:36880
	ds_read_b128 v[32:35], v145 offset:38912
	ds_read_b128 v[36:39], v145 offset:38928
	s_addc_u32 s39, s67, 0
	s_nop 0
	global_load_lds_dwordx4 v68, s[38:39]
	v_mov_b32_e32 v68, v140
	s_mov_b32 m0, s90
	s_nop 0
	global_load_lds_dwordx4 v68, s[38:39]
	s_waitcnt vmcnt(8)
	s_waitcnt lgkmcnt(0)
	s_setprio 1
	s_barrier
	v_mfma_scale_f32_16x16x128_f8f6f4 v[124:127], v[0:7], v[8:15], v[124:127], v146, v146 op_sel_hi:[0,0,0]
	v_mfma_scale_f32_16x16x128_f8f6f4 v[108:111], v[148:155], v[8:15], v[108:111], v146, v146 op_sel_hi:[0,0,0]
	v_mfma_scale_f32_16x16x128_f8f6f4 v[120:123], v[130:137], v[8:15], v[120:123], v146, v146 op_sel_hi:[0,0,0]
	v_mfma_scale_f32_16x16x128_f8f6f4 v[100:103], v[156:163], v[8:15], v[100:103], v146, v146 op_sel_hi:[0,0,0]
	s_setprio 0
	s_setprio 1
	v_mfma_scale_f32_16x16x128_f8f6f4 v[116:119], v[0:7], v[16:23], v[116:119], v146, v146 op_sel_hi:[0,0,0]
	v_mfma_scale_f32_16x16x128_f8f6f4 v[92:95], v[148:155], v[16:23], v[172:175], v146, v146 op_sel_hi:[0,0,0]
	v_mfma_scale_f32_16x16x128_f8f6f4 v[112:115], v[130:137], v[16:23], v[112:115], v146, v146 op_sel_hi:[0,0,0]
	v_mfma_scale_f32_16x16x128_f8f6f4 v[84:87], v[156:163], v[16:23], v[176:179], v146, v146 op_sel_hi:[0,0,0]
	s_setprio 0
	s_setprio 1
	v_mfma_scale_f32_16x16x128_f8f6f4 v[104:107], v[0:7], v[24:31], v[104:107], v146, v146 op_sel_hi:[0,0,0]
	v_mfma_scale_f32_16x16x128_f8f6f4 v[76:79], v[148:155], v[24:31], v[180:183], v146, v146 op_sel_hi:[0,0,0]
	v_mfma_scale_f32_16x16x128_f8f6f4 v[96:99], v[130:137], v[24:31], v[184:187], v146, v146 op_sel_hi:[0,0,0]
	v_mfma_scale_f32_16x16x128_f8f6f4 v[72:75], v[156:163], v[24:31], v[188:191], v146, v146 op_sel_hi:[0,0,0]
	s_setprio 0
	s_setprio 1
	v_mfma_scale_f32_16x16x128_f8f6f4 v[88:91], v[0:7], v[32:39], v[192:195], v146, v146 op_sel_hi:[0,0,0]
	v_mfma_scale_f32_16x16x128_f8f6f4 v[68:71], v[148:155], v[32:39], v[204:207], v146, v146 op_sel_hi:[0,0,0]
	v_mfma_scale_f32_16x16x128_f8f6f4 v[80:83], v[130:137], v[32:39], v[208:211], v146, v146 op_sel_hi:[0,0,0]
	v_mfma_scale_f32_16x16x128_f8f6f4 v[60:63], v[156:163], v[32:39], v[60:63], v146, v146 op_sel_hi:[0,0,0]
	s_barrier
	s_setprio 0
	v_mov_b32_e32 v128, v139
	ds_read_b128 v[8:11], v145 offset:49152
	ds_read_b128 v[12:15], v145 offset:49168
	ds_read_b128 v[16:19], v145 offset:51200
	ds_read_b128 v[20:23], v145 offset:51216
	ds_read_b128 v[164:167], v145 offset:53248
	ds_read_b128 v[168:171], v145 offset:53264
	ds_read_b128 v[172:175], v145 offset:55296
	ds_read_b128 v[176:179], v145 offset:55312
	s_add_i32 s6, s6, s86
	v_lshl_add_u64 v[24:25], s[68:69], 0, v[128:129]
	v_lshl_add_u64 v[24:25], v[24:25], 0, s[40:41]
	s_mov_b32 m0, s6
	v_mov_b32_e32 v128, v141
	global_load_lds_dwordx4 v[24:25], off
	s_add_i32 m0, s6, 0x2000
	v_lshl_add_u64 v[24:25], s[68:69], 0, v[128:129]
	v_lshl_add_u64 v[24:25], v[24:25], 0, s[40:41]
	s_add_u32 s38, s68, 0x20080
	global_load_lds_dwordx4 v[24:25], off
	s_addc_u32 s39, s69, 0
	v_mov_b32_e32 v24, v139
	s_add_i32 s6, s7, s86
	s_mov_b32 m0, s6
	v_mov_b32_e32 v128, v138
	global_load_lds_dwordx4 v24, s[38:39]
	v_mov_b32_e32 v24, v141
	s_add_i32 m0, s6, 0x2000
	s_nop 0
	global_load_lds_dwordx4 v24, s[38:39]
	s_mov_b32 m0, s92
	v_lshl_add_u64 v[24:25], s[66:67], 0, v[128:129]
	v_lshl_add_u64 v[24:25], v[24:25], 0, s[40:41]
	v_mov_b32_e32 v128, v140
	global_load_lds_dwordx4 v[24:25], off
	s_mov_b32 m0, s93
	v_lshl_add_u64 v[24:25], s[66:67], 0, v[128:129]
	v_lshl_add_u64 v[24:25], v[24:25], 0, s[40:41]
	global_load_lds_dwordx4 v[24:25], off
	s_waitcnt vmcnt(8)
	s_waitcnt lgkmcnt(0)
	s_setprio 1
	s_barrier
	v_mfma_scale_f32_16x16x128_f8f6f4 v[64:67], v[0:7], v[8:15], v[64:67], v146, v146 op_sel_hi:[0,0,0]
	v_mfma_scale_f32_16x16x128_f8f6f4 v[44:47], v[148:155], v[8:15], v[44:47], v146, v146 op_sel_hi:[0,0,0]
	v_mfma_scale_f32_16x16x128_f8f6f4 v[56:59], v[130:137], v[8:15], v[56:59], v146, v146 op_sel_hi:[0,0,0]
	v_mfma_scale_f32_16x16x128_f8f6f4 v[36:39], v[156:163], v[8:15], v[196:199], v146, v146 op_sel_hi:[0,0,0]
	s_setprio 0
	s_setprio 1
	v_mfma_scale_f32_16x16x128_f8f6f4 v[52:55], v[0:7], v[16:23], v[52:55], v146, v146 op_sel_hi:[0,0,0]
	v_mfma_scale_f32_16x16x128_f8f6f4 v[28:31], v[148:155], v[16:23], v[200:203], v146, v146 op_sel_hi:[0,0,0]
	v_mfma_scale_f32_16x16x128_f8f6f4 v[48:51], v[130:137], v[16:23], v[48:51], v146, v146 op_sel_hi:[0,0,0]
	v_mfma_scale_f32_16x16x128_f8f6f4 v[20:23], v[156:163], v[16:23], v[212:215], v146, v146 op_sel_hi:[0,0,0]
	s_setprio 0
	s_setprio 1
	v_mfma_scale_f32_16x16x128_f8f6f4 v[40:43], v[0:7], v[164:171], v[40:43], v146, v146 op_sel_hi:[0,0,0]
	v_mfma_scale_f32_16x16x128_f8f6f4 v[12:15], v[148:155], v[164:171], v[216:219], v146, v146 op_sel_hi:[0,0,0]
	v_mfma_scale_f32_16x16x128_f8f6f4 v[32:35], v[130:137], v[164:171], v[220:223], v146, v146 op_sel_hi:[0,0,0]
	v_mfma_scale_f32_16x16x128_f8f6f4 v[8:11], v[156:163], v[164:171], v[224:227], v146, v146 op_sel_hi:[0,0,0]
	s_setprio 0
	s_setprio 1
	v_mfma_scale_f32_16x16x128_f8f6f4 v[24:27], v[0:7], v[172:179], v[228:231], v146, v146 op_sel_hi:[0,0,0]
	v_mfma_scale_f32_16x16x128_f8f6f4 v[4:7], v[148:155], v[172:179], v[232:235], v146, v146 op_sel_hi:[0,0,0]
	v_mfma_scale_f32_16x16x128_f8f6f4 v[16:19], v[130:137], v[172:179], v[236:239], v146, v146 op_sel_hi:[0,0,0]
	v_mfma_scale_f32_16x16x128_f8f6f4 v[0:3], v[156:163], v[172:179], v[240:243], v146, v146 op_sel_hi:[0,0,0]
	s_barrier
	s_setprio 0
	s_add_u32 s52, s52, 0x100
	s_addc_u32 s53, s53, 0
	s_add_u32 s21, s21, 0x100
	s_addc_u32 s24, s24, 0
	s_cmp_ge_i32 s30, s22
	s_mov_b32 s31, s30
	s_cbranch_scc0 .LBB0_239

; #define PG8_LDA(dst, b, h) do { if constexpr (FP8) { _Pragma("unroll") for (int m = 0; m < 4; ++m) dst##8[m] = PG8_LD8(PG8_SA(b, h), aoff, aoff1, m); } \
;         else { _Pragma("unroll") for (int m = 0; m < 4; ++m) _Pragma("unroll") for (int k = 0; k < 2; ++k) dst[m][k] = *(const LAS bf16x8*)(lds + PG8_SA(b, h) + (k ? aoff1 : aoff) + m * 2048); } } while (0)
; #define PG8_LDB(dst, b, h) do { if constexpr (FP8) { dst##8[0] = PG8_LD8(PG8_SB(b, h), boff, boff1, 0); dst##8[1] = PG8_LD8(PG8_SB(b, h), boff, boff1, 1); } \
;         else { _Pragma("unroll") for (int n = 0; n < 2; ++n) _Pragma("unroll") for (int k = 0; k < 2; ++k) dst[n][k] = *(const LAS bf16x8*)(lds + PG8_SB(b, h) + (k ? boff1 : boff) + n * 2048); } } while (0)
; #define PG8_WAIT_V(n) asm volatile("s_waitcnt vmcnt(" #n ")" ::: "memory")
; #define PG8_WAIT_L(n) asm volatile("s_waitcnt lgkmcnt(" #n ")" ::: "memory")
; #define PG8_BAR __builtin_amdgcn_s_barrier()
; #define PG8_SCHED __builtin_amdgcn_sched_barrier(0)
; #define PG8_S1 PG8_STAGE(PG8_SA(1, 1), a1 + hstepA, voffA)
; template <class Epi, class SchedT, bool ALIGN_EPI, bool SP2, bool FP8 = false>
; __device__ __forceinline__ void gemm_phase(LAS unsigned char* lds, const Gemm g, const SchedT& S, const Epi& E, const int wid) {
;     ...
;     for (;;) {
;         const bool has_next = S.next(ui + 1, nxt);
;         const char* nA = has_next ? (const char*)g.A + (size_t)nxt.pm * tstepA + (size_t)nxt.aoff * 2 : cA; const char* nB = has_next ? (const char*)g.Bt + (size_t)nxt.pn * tstepB + (size_t)nxt.boff * 2 : cB;
;         const int nt = cur.nt;
;         for (int t = 0; t < nt; t += 2) {
;             const bool last = (t == nt - 2);
;             const char* a1 = cA + (size_t)(t + 1) * kstep;
;             const char* a2 = last ? nA : cA + (size_t)(t + 2) * kstep; const char* b2 = last ? nB : cB + (size_t)(t + 2) * kstep;
;             const char* a3 = a2 + kstep; const char* b3 = b2 + kstep;
;             if constexpr (SP2) {
;     ...
;             PG8_LDB(B0, 0, 0); PG8_LDB(B1, 0, 1); PG8_SCHED; PG8_LDA(At, 0, 0); PG8_S1;
;             PG8_WAIT_V(8); PG8_WAIT_L(0); PG8_BAR; PG8_MMAP(0, 0, 0); PG8_BAR; PG8_SCHED;
;             PG8_LDA(At, 0, 1); PG8_S2;
;             PG8_WAIT_V(8); PG8_WAIT_L(0); PG8_BAR; PG8_MMAP(1, 0, 1); PG8_BAR; PG8_SCHED;
.LBB0_254:
	s_ashr_i32 s45, s44, 31
	s_lshl_b64 s[20:21], s[44:45], 19
	s_add_u32 s46, s23, s20
	s_addc_u32 s47, s34, s21
	s_ashr_i32 s43, s42, 31
	s_lshl_b64 s[20:21], s[42:43], 19
	s_add_u32 s48, s64, s20
	s_addc_u32 s49, s65, s21
	s_cmp_lt_i32 s8, 1
	s_cbranch_scc1 .LBB0_262
	s_and_b64 s[20:21], s[4:5], exec
	s_cselect_b32 s9, s47, s51
	s_cselect_b32 s20, s46, s50
	s_cselect_b32 s21, s49, s53
	s_cselect_b32 s24, s48, s52
	s_add_i32 s30, s8, -2
	s_add_u32 s50, s50, 0x40080
	s_addc_u32 s51, s51, 0
	s_add_u32 s31, s52, 0x100
	s_addc_u32 s38, s53, 0
	s_mov_b32 s39, 0
	ds_read_b128 v[146:149], v139
	ds_read_b128 v[150:153], v139 offset:1024
	ds_read_b128 v[154:157], v140
	ds_read_b128 v[158:161], v140 offset:1024
	ds_read_b128 v[162:165], v141
	ds_read_b128 v[166:169], v141 offset:1024
	ds_read_b128 v[170:173], v142
	ds_read_b128 v[174:177], v142 offset:1024
	s_add_i32 s43, s39, 2
	s_add_u32 s6, s50, 0xfffc0080
	s_addc_u32 s7, s51, -1
	s_cmp_eq_u32 s30, s39
	s_cselect_b32 s53, s9, s7
	s_cselect_b32 s52, s20, s6
	s_cselect_b32 s67, s21, s38
	s_cselect_b32 s66, s24, s31
	v_mov_b32_e32 v128, v134
	ds_read_b128 v[178:181], v143
	ds_read_b128 v[182:185], v143 offset:1024
	ds_read_b128 v[186:189], v143 offset:2048
	ds_read_b128 v[190:193], v143 offset:3072
	ds_read_b128 v[194:197], v143 offset:4096
	ds_read_b128 v[198:201], v143 offset:5120
	ds_read_b128 v[202:205], v143 offset:6144
	ds_read_b128 v[206:209], v143 offset:7168
	s_add_i32 m0, s87, 0xc000
	s_nop 0
	global_load_lds_dwordx4 v128, s[50:51]
	v_mov_b32_e32 v128, v136
	s_add_i32 m0, s87, 0xe000
	s_nop 0
	global_load_lds_dwordx4 v128, s[50:51]
	s_waitcnt vmcnt(8)
	s_waitcnt lgkmcnt(0)
	s_setprio 1
	s_barrier
	v_mfma_f32_16x16x32_bf16 v[124:127], v[146:149], v[178:181], 0
	v_mfma_f32_16x16x32_bf16 v[120:123], v[154:157], v[178:181], 0
	v_mfma_f32_16x16x32_bf16 v[104:107], v[154:157], v[186:189], 0
	v_mfma_f32_16x16x32_bf16 v[108:111], v[146:149], v[186:189], 0
	s_setprio 0
	s_setprio 1
	v_mfma_f32_16x16x32_bf16 v[92:95], v[146:149], v[194:197], 0
	v_mfma_f32_16x16x32_bf16 v[88:91], v[154:157], v[194:197], 0
	v_mfma_f32_16x16x32_bf16 v[72:75], v[154:157], v[202:205], 0
	v_mfma_f32_16x16x32_bf16 v[76:79], v[146:149], v[202:205], 0
	s_setprio 0
	s_setprio 1
	v_mfma_f32_16x16x32_bf16 v[124:127], v[150:153], v[182:185], v[124:127]
	v_mfma_f32_16x16x32_bf16 v[120:123], v[158:161], v[182:185], v[120:123]
	v_mfma_f32_16x16x32_bf16 v[104:107], v[158:161], v[190:193], v[104:107]
	v_mfma_f32_16x16x32_bf16 v[108:111], v[150:153], v[190:193], v[108:111]
	s_setprio 0
	s_setprio 1
	v_mfma_f32_16x16x32_bf16 v[92:95], v[150:153], v[198:201], v[92:95]
	v_mfma_f32_16x16x32_bf16 v[88:91], v[158:161], v[198:201], v[88:91]
	v_mfma_f32_16x16x32_bf16 v[72:75], v[158:161], v[206:209], v[72:75]
	v_mfma_f32_16x16x32_bf16 v[76:79], v[150:153], v[206:209], v[76:79]
	s_setprio 0
	s_setprio 1
	v_mfma_f32_16x16x32_bf16 v[116:119], v[162:165], v[178:181], 0
	v_mfma_f32_16x16x32_bf16 v[112:115], v[170:173], v[178:181], 0
	v_mfma_f32_16x16x32_bf16 v[96:99], v[170:173], v[186:189], 0
	v_mfma_f32_16x16x32_bf16 v[100:103], v[162:165], v[186:189], 0
	s_setprio 0
	s_setprio 1
	v_mfma_f32_16x16x32_bf16 v[84:87], v[162:165], v[194:197], 0
	v_mfma_f32_16x16x32_bf16 v[80:83], v[170:173], v[194:197], 0
	v_mfma_f32_16x16x32_bf16 v[56:59], v[170:173], v[202:205], 0
	v_mfma_f32_16x16x32_bf16 v[60:63], v[162:165], v[202:205], 0
	s_setprio 0
	s_setprio 1
	v_mfma_f32_16x16x32_bf16 v[116:119], v[166:169], v[182:185], v[116:119]
	v_mfma_f32_16x16x32_bf16 v[112:115], v[174:177], v[182:185], v[112:115]
	v_mfma_f32_16x16x32_bf16 v[96:99], v[174:177], v[190:193], v[96:99]
	v_mfma_f32_16x16x32_bf16 v[100:103], v[166:169], v[190:193], v[100:103]
	s_setprio 0
	s_setprio 1
	v_mfma_f32_16x16x32_bf16 v[84:87], v[166:169], v[198:201], v[84:87]
	v_mfma_f32_16x16x32_bf16 v[80:83], v[174:177], v[198:201], v[80:83]
	v_mfma_f32_16x16x32_bf16 v[56:59], v[174:177], v[206:209], v[56:59]
	v_mfma_f32_16x16x32_bf16 v[60:63], v[166:169], v[206:209], v[60:63]
	s_barrier
	s_setprio 0
	v_mov_b32_e32 v128, v135
	s_add_i32 s6, s94, s86
	ds_read_b128 v[178:181], v143 offset:16384
	ds_read_b128 v[182:185], v143 offset:17408
	ds_read_b128 v[186:189], v143 offset:18432
	ds_read_b128 v[190:193], v143 offset:19456
	ds_read_b128 v[194:197], v143 offset:20480
	ds_read_b128 v[198:201], v143 offset:21504
	ds_read_b128 v[202:205], v143 offset:22528
	ds_read_b128 v[206:209], v143 offset:23552
	s_mov_b32 m0, s6
	s_nop 0
	global_load_lds_dwordx4 v128, s[66:67]
	v_mov_b32_e32 v128, v137
	s_add_i32 m0, s6, 0x2000
	s_add_u32 s60, s66, 0x40000
	global_load_lds_dwordx4 v128, s[66:67]
	s_addc_u32 s61, s67, 0
	v_mov_b32_e32 v128, v135
	s_add_i32 s6, s95, s86
	s_mov_b32 m0, s6
	s_nop 0
	global_load_lds_dwordx4 v128, s[60:61]
	v_mov_b32_e32 v128, v137
	s_add_i32 m0, s6, 0x2000
	s_nop 0
	global_load_lds_dwordx4 v128, s[60:61]
	v_mov_b32_e32 v128, v134
	s_mov_b32 m0, s87
	s_nop 0
	global_load_lds_dwordx4 v128, s[52:53]
	v_mov_b32_e32 v128, v136
	s_mov_b32 m0, s88
	s_nop 0
	global_load_lds_dwordx4 v128, s[52:53]
	s_waitcnt vmcnt(8)
	s_waitcnt lgkmcnt(0)
	s_setprio 1
	s_barrier
; #define PG8_LDA(dst, b, h) do { if constexpr (FP8) { _Pragma("unroll") for (int m = 0; m < 4; ++m) dst##8[m] = PG8_LD8(PG8_SA(b, h), aoff, aoff1, m); } \
;         else { _Pragma("unroll") for (int m = 0; m < 4; ++m) _Pragma("unroll") for (int k = 0; k < 2; ++k) dst[m][k] = *(const LAS bf16x8*)(lds + PG8_SA(b, h) + (k ? aoff1 : aoff) + m * 2048); } } while (0)
; #define PG8_LDB(dst, b, h) do { if constexpr (FP8) { dst##8[0] = PG8_LD8(PG8_SB(b, h), boff, boff1, 0); dst##8[1] = PG8_LD8(PG8_SB(b, h), boff, boff1, 1); } \
;         else { _Pragma("unroll") for (int n = 0; n < 2; ++n) _Pragma("unroll") for (int k = 0; k < 2; ++k) dst[n][k] = *(const LAS bf16x8*)(lds + PG8_SB(b, h) + (k ? boff1 : boff) + n * 2048); } } while (0)
; #define PG8_WAIT_V(n) asm volatile("s_waitcnt vmcnt(" #n ")" ::: "memory")
; #define PG8_WAIT_L(n) asm volatile("s_waitcnt lgkmcnt(" #n ")" ::: "memory")
; #define PG8_BAR __builtin_amdgcn_s_barrier()
; #define PG8_SCHED __builtin_amdgcn_sched_barrier(0)
; #define PG8_S3 PG8_STAGE(PG8_SA(0, 1), a2 + hstepA, voffA)
; template <class Epi, class SchedT, bool ALIGN_EPI, bool SP2, bool FP8 = false>
; __device__ __forceinline__ void gemm_phase(LAS unsigned char* lds, const Gemm g, const SchedT& S, const Epi& E, const int wid) {
;     ...
;             PG8_WAIT_V(8); PG8_WAIT_L(0); PG8_BAR; PG8_MMAP(1, 0, 1); PG8_BAR; PG8_SCHED;
;             PG8_LDB(B0, 1, 0); PG8_LDB(B1, 1, 1); PG8_SCHED; PG8_LDA(At, 1, 0); PG8_S3;
;             PG8_WAIT_V(8); PG8_WAIT_L(0); PG8_BAR; PG8_MMAP(0, 1, 0); PG8_BAR; PG8_SCHED;
	v_mfma_f32_16x16x32_bf16 v[68:71], v[146:149], v[178:181], 0
	v_mfma_f32_16x16x32_bf16 v[64:67], v[154:157], v[178:181], 0
	v_mfma_f32_16x16x32_bf16 v[40:43], v[154:157], v[186:189], 0
	v_mfma_f32_16x16x32_bf16 v[44:47], v[146:149], v[186:189], 0
	s_setprio 0
	s_setprio 1
	v_mfma_f32_16x16x32_bf16 v[28:31], v[146:149], v[194:197], 0
	v_mfma_f32_16x16x32_bf16 v[24:27], v[154:157], v[194:197], 0
	v_mfma_f32_16x16x32_bf16 v[8:11], v[154:157], v[202:205], 0
	v_mfma_f32_16x16x32_bf16 v[12:15], v[146:149], v[202:205], 0
	s_setprio 0
	s_setprio 1
	v_mfma_f32_16x16x32_bf16 v[68:71], v[150:153], v[182:185], v[68:71]
	v_mfma_f32_16x16x32_bf16 v[64:67], v[158:161], v[182:185], v[64:67]
	v_mfma_f32_16x16x32_bf16 v[40:43], v[158:161], v[190:193], v[40:43]
	v_mfma_f32_16x16x32_bf16 v[44:47], v[150:153], v[190:193], v[44:47]
	s_setprio 0
	s_setprio 1
	v_mfma_f32_16x16x32_bf16 v[28:31], v[150:153], v[198:201], v[28:31]
	v_mfma_f32_16x16x32_bf16 v[24:27], v[158:161], v[198:201], v[24:27]
	v_mfma_f32_16x16x32_bf16 v[8:11], v[158:161], v[206:209], v[8:11]
	v_mfma_f32_16x16x32_bf16 v[12:15], v[150:153], v[206:209], v[12:15]
	s_setprio 0
	s_setprio 1
	v_mfma_f32_16x16x32_bf16 v[52:55], v[162:165], v[178:181], 0
	v_mfma_f32_16x16x32_bf16 v[48:51], v[170:173], v[178:181], 0
	v_mfma_f32_16x16x32_bf16 v[32:35], v[170:173], v[186:189], 0
	v_mfma_f32_16x16x32_bf16 v[36:39], v[162:165], v[186:189], 0
	s_setprio 0
	s_setprio 1
	v_mfma_f32_16x16x32_bf16 v[20:23], v[162:165], v[194:197], 0
	v_mfma_f32_16x16x32_bf16 v[16:19], v[170:173], v[194:197], 0
	v_mfma_f32_16x16x32_bf16 v[0:3], v[170:173], v[202:205], 0
	v_mfma_f32_16x16x32_bf16 v[4:7], v[162:165], v[202:205], 0
	s_setprio 0
	s_setprio 1
	v_mfma_f32_16x16x32_bf16 v[52:55], v[166:169], v[182:185], v[52:55]
	v_mfma_f32_16x16x32_bf16 v[48:51], v[174:177], v[182:185], v[48:51]
	v_mfma_f32_16x16x32_bf16 v[32:35], v[174:177], v[190:193], v[32:35]
	v_mfma_f32_16x16x32_bf16 v[36:39], v[166:169], v[190:193], v[36:39]
	s_setprio 0
	s_setprio 1
	v_mfma_f32_16x16x32_bf16 v[20:23], v[166:169], v[198:201], v[20:23]
	v_mfma_f32_16x16x32_bf16 v[16:19], v[174:177], v[198:201], v[16:19]
	v_mfma_f32_16x16x32_bf16 v[0:3], v[174:177], v[206:209], v[0:3]
	v_mfma_f32_16x16x32_bf16 v[4:7], v[166:169], v[206:209], v[4:7]
	s_barrier
	s_setprio 0
	s_add_i32 s6, 0, 0x18000
	v_add_u32_e32 v128, s6, v138
	s_add_i32 s7, 0, 0x1c000
	ds_read_b128 v[146:149], v128
	ds_read_b128 v[150:153], v128 offset:1024
	ds_read_b128 v[154:157], v144
	ds_read_b128 v[158:161], v144 offset:1024
	v_add_u32_e32 v128, s7, v138
	ds_read_b128 v[162:165], v128
	ds_read_b128 v[166:169], v128 offset:1024
	ds_read_b128 v[170:173], v145
	ds_read_b128 v[174:177], v145 offset:1024
	s_add_u32 s60, s52, 0x40000
	v_mov_b32_e32 v128, v134
	s_mov_b32 m0, s89
	ds_read_b128 v[178:181], v143 offset:32768
	ds_read_b128 v[182:185], v143 offset:33792
	ds_read_b128 v[186:189], v143 offset:34816
	ds_read_b128 v[190:193], v143 offset:35840
	ds_read_b128 v[194:197], v143 offset:36864
	ds_read_b128 v[198:201], v143 offset:37888
	ds_read_b128 v[202:205], v143 offset:38912
	ds_read_b128 v[206:209], v143 offset:39936
	s_addc_u32 s61, s53, 0
	s_nop 0
	global_load_lds_dwordx4 v128, s[60:61]
	v_mov_b32_e32 v128, v136
	s_mov_b32 m0, s90
	s_nop 0
	global_load_lds_dwordx4 v128, s[60:61]
	s_waitcnt vmcnt(8)
	s_waitcnt lgkmcnt(0)
	s_setprio 1
	s_barrier
	v_mfma_f32_16x16x32_bf16 v[124:127], v[146:149], v[178:181], v[124:127]
	v_mfma_f32_16x16x32_bf16 v[120:123], v[154:157], v[178:181], v[120:123]
	v_mfma_f32_16x16x32_bf16 v[104:107], v[154:157], v[186:189], v[104:107]
	v_mfma_f32_16x16x32_bf16 v[108:111], v[146:149], v[186:189], v[108:111]
	s_setprio 0
	s_setprio 1
	v_mfma_f32_16x16x32_bf16 v[92:95], v[146:149], v[194:197], v[92:95]
	v_mfma_f32_16x16x32_bf16 v[88:91], v[154:157], v[194:197], v[88:91]
	v_mfma_f32_16x16x32_bf16 v[72:75], v[154:157], v[202:205], v[72:75]
	v_mfma_f32_16x16x32_bf16 v[76:79], v[146:149], v[202:205], v[76:79]
	s_setprio 0
	s_setprio 1
	v_mfma_f32_16x16x32_bf16 v[124:127], v[150:153], v[182:185], v[124:127]
	v_mfma_f32_16x16x32_bf16 v[120:123], v[158:161], v[182:185], v[120:123]
	v_mfma_f32_16x16x32_bf16 v[104:107], v[158:161], v[190:193], v[104:107]
	v_mfma_f32_16x16x32_bf16 v[108:111], v[150:153], v[190:193], v[108:111]
	s_setprio 0
	s_setprio 1
	v_mfma_f32_16x16x32_bf16 v[92:95], v[150:153], v[198:201], v[92:95]
	v_mfma_f32_16x16x32_bf16 v[88:91], v[158:161], v[198:201], v[88:91]
	v_mfma_f32_16x16x32_bf16 v[72:75], v[158:161], v[206:209], v[72:75]
	v_mfma_f32_16x16x32_bf16 v[76:79], v[150:153], v[206:209], v[76:79]
	s_setprio 0
	s_setprio 1
	v_mfma_f32_16x16x32_bf16 v[116:119], v[162:165], v[178:181], v[116:119]
	v_mfma_f32_16x16x32_bf16 v[112:115], v[170:173], v[178:181], v[112:115]
	v_mfma_f32_16x16x32_bf16 v[96:99], v[170:173], v[186:189], v[96:99]
	v_mfma_f32_16x16x32_bf16 v[100:103], v[162:165], v[186:189], v[100:103]
	s_setprio 0
	s_setprio 1
	v_mfma_f32_16x16x32_bf16 v[84:87], v[162:165], v[194:197], v[84:87]
	v_mfma_f32_16x16x32_bf16 v[80:83], v[170:173], v[194:197], v[80:83]
	v_mfma_f32_16x16x32_bf16 v[56:59], v[170:173], v[202:205], v[56:59]
	v_mfma_f32_16x16x32_bf16 v[60:63], v[162:165], v[202:205], v[60:63]
	s_setprio 0
	s_setprio 1
	v_mfma_f32_16x16x32_bf16 v[116:119], v[166:169], v[182:185], v[116:119]
	v_mfma_f32_16x16x32_bf16 v[112:115], v[174:177], v[182:185], v[112:115]
	v_mfma_f32_16x16x32_bf16 v[96:99], v[174:177], v[190:193], v[96:99]
	v_mfma_f32_16x16x32_bf16 v[100:103], v[166:169], v[190:193], v[100:103]
	s_setprio 0
	s_setprio 1
	v_mfma_f32_16x16x32_bf16 v[84:87], v[166:169], v[198:201], v[84:87]
	v_mfma_f32_16x16x32_bf16 v[80:83], v[174:177], v[198:201], v[80:83]
	v_mfma_f32_16x16x32_bf16 v[56:59], v[174:177], v[206:209], v[56:59]
	v_mfma_f32_16x16x32_bf16 v[60:63], v[166:169], v[206:209], v[60:63]
	s_barrier
; #define PG8_LDA(dst, b, h) do { if constexpr (FP8) { _Pragma("unroll") for (int m = 0; m < 4; ++m) dst##8[m] = PG8_LD8(PG8_SA(b, h), aoff, aoff1, m); } \
;         else { _Pragma("unroll") for (int m = 0; m < 4; ++m) _Pragma("unroll") for (int k = 0; k < 2; ++k) dst[m][k] = *(const LAS bf16x8*)(lds + PG8_SA(b, h) + (k ? aoff1 : aoff) + m * 2048); } } while (0)
; #define PG8_LDB(dst, b, h) do { if constexpr (FP8) { dst##8[0] = PG8_LD8(PG8_SB(b, h), boff, boff1, 0); dst##8[1] = PG8_LD8(PG8_SB(b, h), boff, boff1, 1); } \
;         else { _Pragma("unroll") for (int n = 0; n < 2; ++n) _Pragma("unroll") for (int k = 0; k < 2; ++k) dst[n][k] = *(const LAS bf16x8*)(lds + PG8_SB(b, h) + (k ? boff1 : boff) + n * 2048); } } while (0)
; #define PG8_WAIT_V(n) asm volatile("s_waitcnt vmcnt(" #n ")" ::: "memory")
; #define PG8_WAIT_L(n) asm volatile("s_waitcnt lgkmcnt(" #n ")" ::: "memory")
; #define PG8_BAR __builtin_amdgcn_s_barrier()
; #define PG8_SCHED __builtin_amdgcn_sched_barrier(0)
; #define PG8_S1 PG8_STAGE(PG8_SA(1, 1), a1 + hstepA, voffA)
; #define PG8_S4 do { PG8_STAGE(PG8_SB(1, 0), b3, voffB); PG8_STAGE(PG8_SB(1, 1), b3 + hstepB, voffB); PG8_STAGE(PG8_SA(1, 0), a3, voffA); } while (0)
; template <class Epi, class SchedT, bool ALIGN_EPI, bool SP2, bool FP8 = false>
; __device__ __forceinline__ void gemm_phase(LAS unsigned char* lds, const Gemm g, const SchedT& S, const Epi& E, const int wid) {
;     ...
;             PG8_LDB(B0, 0, 0); PG8_LDB(B1, 0, 1); PG8_SCHED; PG8_LDA(At, 0, 0); PG8_S1;
;             PG8_WAIT_V(8); PG8_WAIT_L(0); PG8_BAR; PG8_MMAP(0, 0, 0); PG8_BAR; PG8_SCHED;
;     ...
;             PG8_LDA(At, 1, 1); PG8_S4;
;             PG8_WAIT_V(8); PG8_WAIT_L(0); PG8_BAR; PG8_MMAP(1, 1, 1); PG8_BAR; PG8_SCHED;
	s_setprio 0
	v_mov_b32_e32 v128, v135
	ds_read_b128 v[178:181], v143 offset:49152
	ds_read_b128 v[182:185], v143 offset:50176
	ds_read_b128 v[186:189], v143 offset:51200
	ds_read_b128 v[190:193], v143 offset:52224
	ds_read_b128 v[194:197], v143 offset:53248
	ds_read_b128 v[198:201], v143 offset:54272
	ds_read_b128 v[202:205], v143 offset:55296
	ds_read_b128 v[206:209], v143 offset:56320
	s_add_i32 s6, s6, s86
	v_lshl_add_u64 v[210:211], s[66:67], 0, v[128:129]
	v_lshl_add_u64 v[210:211], v[210:211], 0, s[36:37]
	s_mov_b32 m0, s6
	v_mov_b32_e32 v128, v137
	global_load_lds_dwordx4 v[210:211], off
	s_add_i32 m0, s6, 0x2000
	s_add_u32 s60, s66, 0x40080
	v_lshl_add_u64 v[210:211], s[66:67], 0, v[128:129]
	v_lshl_add_u64 v[210:211], v[210:211], 0, s[36:37]
	s_addc_u32 s61, s67, 0
	v_mov_b32_e32 v128, v135
	s_add_i32 s6, s7, s86
	global_load_lds_dwordx4 v[210:211], off
	s_mov_b32 m0, s6
	s_nop 0
	global_load_lds_dwordx4 v128, s[60:61]
	v_mov_b32_e32 v128, v137
	s_add_i32 m0, s6, 0x2000
	s_nop 0
	global_load_lds_dwordx4 v128, s[60:61]
	v_mov_b32_e32 v128, v134
	s_mov_b32 m0, s92
	v_lshl_add_u64 v[210:211], s[52:53], 0, v[128:129]
	v_lshl_add_u64 v[210:211], v[210:211], 0, s[36:37]
	v_mov_b32_e32 v128, v136
	global_load_lds_dwordx4 v[210:211], off
	s_mov_b32 m0, s93
	v_lshl_add_u64 v[210:211], s[52:53], 0, v[128:129]
	v_lshl_add_u64 v[210:211], v[210:211], 0, s[36:37]
	global_load_lds_dwordx4 v[210:211], off
	s_waitcnt vmcnt(8)
	s_waitcnt lgkmcnt(0)
	s_setprio 1
	s_barrier
	v_mfma_f32_16x16x32_bf16 v[68:71], v[146:149], v[178:181], v[68:71]
	v_mfma_f32_16x16x32_bf16 v[64:67], v[154:157], v[178:181], v[64:67]
	v_mfma_f32_16x16x32_bf16 v[40:43], v[154:157], v[186:189], v[40:43]
	v_mfma_f32_16x16x32_bf16 v[44:47], v[146:149], v[186:189], v[44:47]
	s_setprio 0
	s_setprio 1
	v_mfma_f32_16x16x32_bf16 v[28:31], v[146:149], v[194:197], v[28:31]
	v_mfma_f32_16x16x32_bf16 v[24:27], v[154:157], v[194:197], v[24:27]
	v_mfma_f32_16x16x32_bf16 v[8:11], v[154:157], v[202:205], v[8:11]
	v_mfma_f32_16x16x32_bf16 v[12:15], v[146:149], v[202:205], v[12:15]
	s_setprio 0
	s_setprio 1
	v_mfma_f32_16x16x32_bf16 v[68:71], v[150:153], v[182:185], v[68:71]
	v_mfma_f32_16x16x32_bf16 v[64:67], v[158:161], v[182:185], v[64:67]
	v_mfma_f32_16x16x32_bf16 v[40:43], v[158:161], v[190:193], v[40:43]
	v_mfma_f32_16x16x32_bf16 v[44:47], v[150:153], v[190:193], v[44:47]
	s_setprio 0
	s_setprio 1
	v_mfma_f32_16x16x32_bf16 v[28:31], v[150:153], v[198:201], v[28:31]
	v_mfma_f32_16x16x32_bf16 v[24:27], v[158:161], v[198:201], v[24:27]
	v_mfma_f32_16x16x32_bf16 v[8:11], v[158:161], v[206:209], v[8:11]
	v_mfma_f32_16x16x32_bf16 v[12:15], v[150:153], v[206:209], v[12:15]
	s_setprio 0
	s_setprio 1
	v_mfma_f32_16x16x32_bf16 v[52:55], v[162:165], v[178:181], v[52:55]
	v_mfma_f32_16x16x32_bf16 v[48:51], v[170:173], v[178:181], v[48:51]
	v_mfma_f32_16x16x32_bf16 v[32:35], v[170:173], v[186:189], v[32:35]
	v_mfma_f32_16x16x32_bf16 v[36:39], v[162:165], v[186:189], v[36:39]
	s_setprio 0
	s_setprio 1
	v_mfma_f32_16x16x32_bf16 v[20:23], v[162:165], v[194:197], v[20:23]
	v_mfma_f32_16x16x32_bf16 v[16:19], v[170:173], v[194:197], v[16:19]
	v_mfma_f32_16x16x32_bf16 v[0:3], v[170:173], v[202:205], v[0:3]
	v_mfma_f32_16x16x32_bf16 v[4:7], v[162:165], v[202:205], v[4:7]
	s_setprio 0
	s_setprio 1
	v_mfma_f32_16x16x32_bf16 v[52:55], v[166:169], v[182:185], v[52:55]
	v_mfma_f32_16x16x32_bf16 v[48:51], v[174:177], v[182:185], v[48:51]
	v_mfma_f32_16x16x32_bf16 v[32:35], v[174:177], v[190:193], v[32:35]
	v_mfma_f32_16x16x32_bf16 v[36:39], v[166:169], v[190:193], v[36:39]
	s_setprio 0
	s_setprio 1
	v_mfma_f32_16x16x32_bf16 v[20:23], v[166:169], v[198:201], v[20:23]
	v_mfma_f32_16x16x32_bf16 v[16:19], v[174:177], v[198:201], v[16:19]
	v_mfma_f32_16x16x32_bf16 v[0:3], v[174:177], v[206:209], v[0:3]
	v_mfma_f32_16x16x32_bf16 v[4:7], v[166:169], v[206:209], v[4:7]
	s_barrier
	s_setprio 0
	s_add_u32 s50, s50, 0x100
	s_addc_u32 s51, s51, 0
	s_add_u32 s31, s31, 0x100
	s_addc_u32 s38, s38, 0
	s_cmp_ge_i32 s43, s8
	s_mov_b32 s39, s43
	s_cbranch_scc1 .Lpeel_exit_lbb0_256
.LBB0_256:
	ds_read_b128 v[146:149], v139
	ds_read_b128 v[150:153], v139 offset:1024
	ds_read_b128 v[154:157], v140
	ds_read_b128 v[158:161], v140 offset:1024
	ds_read_b128 v[162:165], v141
	ds_read_b128 v[166:169], v141 offset:1024
	ds_read_b128 v[170:173], v142
	ds_read_b128 v[174:177], v142 offset:1024
	s_add_i32 s43, s39, 2
	s_add_u32 s6, s50, 0xfffc0080
	s_addc_u32 s7, s51, -1
	s_cmp_eq_u32 s30, s39
	s_cselect_b32 s53, s9, s7
	s_cselect_b32 s52, s20, s6
	s_cselect_b32 s67, s21, s38
	s_cselect_b32 s66, s24, s31
	v_mov_b32_e32 v128, v134
	ds_read_b128 v[178:181], v143
	ds_read_b128 v[182:185], v143 offset:1024
	ds_read_b128 v[186:189], v143 offset:2048
	ds_read_b128 v[190:193], v143 offset:3072
	ds_read_b128 v[194:197], v143 offset:4096
	ds_read_b128 v[198:201], v143 offset:5120
	ds_read_b128 v[202:205], v143 offset:6144
	ds_read_b128 v[206:209], v143 offset:7168
	s_add_i32 m0, s87, 0xc000
	s_nop 0
	global_load_lds_dwordx4 v128, s[50:51]
	v_mov_b32_e32 v128, v136
	s_add_i32 m0, s87, 0xe000
	s_nop 0
	global_load_lds_dwordx4 v128, s[50:51]
	s_waitcnt vmcnt(8)
	s_waitcnt lgkmcnt(0)
	s_setprio 1
	s_barrier
; #define PG8_LDA(dst, b, h) do { if constexpr (FP8) { _Pragma("unroll") for (int m = 0; m < 4; ++m) dst##8[m] = PG8_LD8(PG8_SA(b, h), aoff, aoff1, m); } \
;         else { _Pragma("unroll") for (int m = 0; m < 4; ++m) _Pragma("unroll") for (int k = 0; k < 2; ++k) dst[m][k] = *(const LAS bf16x8*)(lds + PG8_SA(b, h) + (k ? aoff1 : aoff) + m * 2048); } } while (0)
; #define PG8_WAIT_V(n) asm volatile("s_waitcnt vmcnt(" #n ")" ::: "memory")
; #define PG8_WAIT_L(n) asm volatile("s_waitcnt lgkmcnt(" #n ")" ::: "memory")
; #define PG8_BAR __builtin_amdgcn_s_barrier()
; #define PG8_SCHED __builtin_amdgcn_sched_barrier(0)
; #define PG8_S2 do { PG8_STAGE(PG8_SB(0, 0), b2, voffB); PG8_STAGE(PG8_SB(0, 1), b2 + hstepB, voffB); PG8_STAGE(PG8_SA(0, 0), a2, voffA); } while (0)
; template <class Epi, class SchedT, bool ALIGN_EPI, bool SP2, bool FP8 = false>
; __device__ __forceinline__ void gemm_phase(LAS unsigned char* lds, const Gemm g, const SchedT& S, const Epi& E, const int wid) {
;     ...
;             PG8_WAIT_V(8); PG8_WAIT_L(0); PG8_BAR; PG8_MMAP(0, 0, 0); PG8_BAR; PG8_SCHED;
;             PG8_LDA(At, 0, 1); PG8_S2;
;             PG8_WAIT_V(8); PG8_WAIT_L(0); PG8_BAR; PG8_MMAP(1, 0, 1); PG8_BAR; PG8_SCHED;
	v_mfma_f32_16x16x32_bf16 v[124:127], v[146:149], v[178:181], v[124:127]
	v_mfma_f32_16x16x32_bf16 v[120:123], v[154:157], v[178:181], v[120:123]
	v_mfma_f32_16x16x32_bf16 v[104:107], v[154:157], v[186:189], v[104:107]
	v_mfma_f32_16x16x32_bf16 v[108:111], v[146:149], v[186:189], v[108:111]
	s_setprio 0
	s_setprio 1
	v_mfma_f32_16x16x32_bf16 v[92:95], v[146:149], v[194:197], v[92:95]
	v_mfma_f32_16x16x32_bf16 v[88:91], v[154:157], v[194:197], v[88:91]
	v_mfma_f32_16x16x32_bf16 v[72:75], v[154:157], v[202:205], v[72:75]
	v_mfma_f32_16x16x32_bf16 v[76:79], v[146:149], v[202:205], v[76:79]
	s_setprio 0
	s_setprio 1
	v_mfma_f32_16x16x32_bf16 v[124:127], v[150:153], v[182:185], v[124:127]
	v_mfma_f32_16x16x32_bf16 v[120:123], v[158:161], v[182:185], v[120:123]
	v_mfma_f32_16x16x32_bf16 v[104:107], v[158:161], v[190:193], v[104:107]
	v_mfma_f32_16x16x32_bf16 v[108:111], v[150:153], v[190:193], v[108:111]
	s_setprio 0
	s_setprio 1
	v_mfma_f32_16x16x32_bf16 v[92:95], v[150:153], v[198:201], v[92:95]
	v_mfma_f32_16x16x32_bf16 v[88:91], v[158:161], v[198:201], v[88:91]
	v_mfma_f32_16x16x32_bf16 v[72:75], v[158:161], v[206:209], v[72:75]
	v_mfma_f32_16x16x32_bf16 v[76:79], v[150:153], v[206:209], v[76:79]
	s_setprio 0
	s_setprio 1
	v_mfma_f32_16x16x32_bf16 v[116:119], v[162:165], v[178:181], v[116:119]
	v_mfma_f32_16x16x32_bf16 v[112:115], v[170:173], v[178:181], v[112:115]
	v_mfma_f32_16x16x32_bf16 v[96:99], v[170:173], v[186:189], v[96:99]
	v_mfma_f32_16x16x32_bf16 v[100:103], v[162:165], v[186:189], v[100:103]
	s_setprio 0
	s_setprio 1
	v_mfma_f32_16x16x32_bf16 v[84:87], v[162:165], v[194:197], v[84:87]
	v_mfma_f32_16x16x32_bf16 v[80:83], v[170:173], v[194:197], v[80:83]
	v_mfma_f32_16x16x32_bf16 v[56:59], v[170:173], v[202:205], v[56:59]
	v_mfma_f32_16x16x32_bf16 v[60:63], v[162:165], v[202:205], v[60:63]
	s_setprio 0
	s_setprio 1
	v_mfma_f32_16x16x32_bf16 v[116:119], v[166:169], v[182:185], v[116:119]
	v_mfma_f32_16x16x32_bf16 v[112:115], v[174:177], v[182:185], v[112:115]
	v_mfma_f32_16x16x32_bf16 v[96:99], v[174:177], v[190:193], v[96:99]
	v_mfma_f32_16x16x32_bf16 v[100:103], v[166:169], v[190:193], v[100:103]
	s_setprio 0
	s_setprio 1
	v_mfma_f32_16x16x32_bf16 v[84:87], v[166:169], v[198:201], v[84:87]
	v_mfma_f32_16x16x32_bf16 v[80:83], v[174:177], v[198:201], v[80:83]
	v_mfma_f32_16x16x32_bf16 v[56:59], v[174:177], v[206:209], v[56:59]
	v_mfma_f32_16x16x32_bf16 v[60:63], v[166:169], v[206:209], v[60:63]
	s_barrier
	s_setprio 0
	v_mov_b32_e32 v128, v135
	s_add_i32 s6, s94, s86
	ds_read_b128 v[178:181], v143 offset:16384
	ds_read_b128 v[182:185], v143 offset:17408
	ds_read_b128 v[186:189], v143 offset:18432
	ds_read_b128 v[190:193], v143 offset:19456
	ds_read_b128 v[194:197], v143 offset:20480
	ds_read_b128 v[198:201], v143 offset:21504
	ds_read_b128 v[202:205], v143 offset:22528
	ds_read_b128 v[206:209], v143 offset:23552
	s_mov_b32 m0, s6
	s_nop 0
	global_load_lds_dwordx4 v128, s[66:67]
	v_mov_b32_e32 v128, v137
	s_add_i32 m0, s6, 0x2000
	s_add_u32 s60, s66, 0x40000
	global_load_lds_dwordx4 v128, s[66:67]
	s_addc_u32 s61, s67, 0
	v_mov_b32_e32 v128, v135
	s_add_i32 s6, s95, s86
	s_mov_b32 m0, s6
	s_nop 0
	global_load_lds_dwordx4 v128, s[60:61]
	v_mov_b32_e32 v128, v137
	s_add_i32 m0, s6, 0x2000
	s_nop 0
	global_load_lds_dwordx4 v128, s[60:61]
	v_mov_b32_e32 v128, v134
	s_mov_b32 m0, s87
	s_nop 0
	global_load_lds_dwordx4 v128, s[52:53]
	v_mov_b32_e32 v128, v136
	s_mov_b32 m0, s88
	s_nop 0
	global_load_lds_dwordx4 v128, s[52:53]
	s_waitcnt vmcnt(8)
	s_waitcnt lgkmcnt(0)
	s_setprio 1
	s_barrier
	v_mfma_f32_16x16x32_bf16 v[68:71], v[146:149], v[178:181], v[68:71]
	v_mfma_f32_16x16x32_bf16 v[64:67], v[154:157], v[178:181], v[64:67]
	v_mfma_f32_16x16x32_bf16 v[40:43], v[154:157], v[186:189], v[40:43]
	v_mfma_f32_16x16x32_bf16 v[44:47], v[146:149], v[186:189], v[44:47]
	s_setprio 0
	s_setprio 1
	v_mfma_f32_16x16x32_bf16 v[28:31], v[146:149], v[194:197], v[28:31]
	v_mfma_f32_16x16x32_bf16 v[24:27], v[154:157], v[194:197], v[24:27]
	v_mfma_f32_16x16x32_bf16 v[8:11], v[154:157], v[202:205], v[8:11]
	v_mfma_f32_16x16x32_bf16 v[12:15], v[146:149], v[202:205], v[12:15]
	s_setprio 0
	s_setprio 1
	v_mfma_f32_16x16x32_bf16 v[68:71], v[150:153], v[182:185], v[68:71]
	v_mfma_f32_16x16x32_bf16 v[64:67], v[158:161], v[182:185], v[64:67]
	v_mfma_f32_16x16x32_bf16 v[40:43], v[158:161], v[190:193], v[40:43]
	v_mfma_f32_16x16x32_bf16 v[44:47], v[150:153], v[190:193], v[44:47]
	s_setprio 0
	s_setprio 1
	v_mfma_f32_16x16x32_bf16 v[28:31], v[150:153], v[198:201], v[28:31]
	v_mfma_f32_16x16x32_bf16 v[24:27], v[158:161], v[198:201], v[24:27]
	v_mfma_f32_16x16x32_bf16 v[8:11], v[158:161], v[206:209], v[8:11]
	v_mfma_f32_16x16x32_bf16 v[12:15], v[150:153], v[206:209], v[12:15]
	s_setprio 0
	s_setprio 1
	v_mfma_f32_16x16x32_bf16 v[52:55], v[162:165], v[178:181], v[52:55]
	v_mfma_f32_16x16x32_bf16 v[48:51], v[170:173], v[178:181], v[48:51]
	v_mfma_f32_16x16x32_bf16 v[32:35], v[170:173], v[186:189], v[32:35]
	v_mfma_f32_16x16x32_bf16 v[36:39], v[162:165], v[186:189], v[36:39]
	s_setprio 0
	s_setprio 1
	v_mfma_f32_16x16x32_bf16 v[20:23], v[162:165], v[194:197], v[20:23]
	v_mfma_f32_16x16x32_bf16 v[16:19], v[170:173], v[194:197], v[16:19]
	v_mfma_f32_16x16x32_bf16 v[0:3], v[170:173], v[202:205], v[0:3]
	v_mfma_f32_16x16x32_bf16 v[4:7], v[162:165], v[202:205], v[4:7]
	s_setprio 0
	s_setprio 1
	v_mfma_f32_16x16x32_bf16 v[52:55], v[166:169], v[182:185], v[52:55]
	v_mfma_f32_16x16x32_bf16 v[48:51], v[174:177], v[182:185], v[48:51]
	v_mfma_f32_16x16x32_bf16 v[32:35], v[174:177], v[190:193], v[32:35]
	v_mfma_f32_16x16x32_bf16 v[36:39], v[166:169], v[190:193], v[36:39]
	s_setprio 0
	s_setprio 1
	v_mfma_f32_16x16x32_bf16 v[20:23], v[166:169], v[198:201], v[20:23]
	v_mfma_f32_16x16x32_bf16 v[16:19], v[174:177], v[198:201], v[16:19]
	v_mfma_f32_16x16x32_bf16 v[0:3], v[174:177], v[206:209], v[0:3]
	v_mfma_f32_16x16x32_bf16 v[4:7], v[166:169], v[206:209], v[4:7]
	s_barrier
; #define PG8_LDA(dst, b, h) do { if constexpr (FP8) { _Pragma("unroll") for (int m = 0; m < 4; ++m) dst##8[m] = PG8_LD8(PG8_SA(b, h), aoff, aoff1, m); } \
;         else { _Pragma("unroll") for (int m = 0; m < 4; ++m) _Pragma("unroll") for (int k = 0; k < 2; ++k) dst[m][k] = *(const LAS bf16x8*)(lds + PG8_SA(b, h) + (k ? aoff1 : aoff) + m * 2048); } } while (0)
; #define PG8_LDB(dst, b, h) do { if constexpr (FP8) { dst##8[0] = PG8_LD8(PG8_SB(b, h), boff, boff1, 0); dst##8[1] = PG8_LD8(PG8_SB(b, h), boff, boff1, 1); } \
;         else { _Pragma("unroll") for (int n = 0; n < 2; ++n) _Pragma("unroll") for (int k = 0; k < 2; ++k) dst[n][k] = *(const LAS bf16x8*)(lds + PG8_SB(b, h) + (k ? boff1 : boff) + n * 2048); } } while (0)
; #define PG8_WAIT_V(n) asm volatile("s_waitcnt vmcnt(" #n ")" ::: "memory")
; #define PG8_WAIT_L(n) asm volatile("s_waitcnt lgkmcnt(" #n ")" ::: "memory")
; #define PG8_BAR __builtin_amdgcn_s_barrier()
; #define PG8_SCHED __builtin_amdgcn_sched_barrier(0)
; #define PG8_S3 PG8_STAGE(PG8_SA(0, 1), a2 + hstepA, voffA)
; template <class Epi, class SchedT, bool ALIGN_EPI, bool SP2, bool FP8 = false>
; __device__ __forceinline__ void gemm_phase(LAS unsigned char* lds, const Gemm g, const SchedT& S, const Epi& E, const int wid) {
;     ...
;             PG8_LDB(B0, 1, 0); PG8_LDB(B1, 1, 1); PG8_SCHED; PG8_LDA(At, 1, 0); PG8_S3;
;             PG8_WAIT_V(8); PG8_WAIT_L(0); PG8_BAR; PG8_MMAP(0, 1, 0); PG8_BAR; PG8_SCHED;
	s_setprio 0
	s_add_i32 s6, 0, 0x18000
	v_add_u32_e32 v128, s6, v138
	s_add_i32 s7, 0, 0x1c000
	ds_read_b128 v[146:149], v128
	ds_read_b128 v[150:153], v128 offset:1024
	ds_read_b128 v[154:157], v144
	ds_read_b128 v[158:161], v144 offset:1024
	v_add_u32_e32 v128, s7, v138
	ds_read_b128 v[162:165], v128
	ds_read_b128 v[166:169], v128 offset:1024
	ds_read_b128 v[170:173], v145
	ds_read_b128 v[174:177], v145 offset:1024
	s_add_u32 s60, s52, 0x40000
	v_mov_b32_e32 v128, v134
	s_mov_b32 m0, s89
	ds_read_b128 v[178:181], v143 offset:32768
	ds_read_b128 v[182:185], v143 offset:33792
	ds_read_b128 v[186:189], v143 offset:34816
	ds_read_b128 v[190:193], v143 offset:35840
	ds_read_b128 v[194:197], v143 offset:36864
	ds_read_b128 v[198:201], v143 offset:37888
	ds_read_b128 v[202:205], v143 offset:38912
	ds_read_b128 v[206:209], v143 offset:39936
	s_addc_u32 s61, s53, 0
	s_nop 0
	global_load_lds_dwordx4 v128, s[60:61]
	v_mov_b32_e32 v128, v136
	s_mov_b32 m0, s90
	s_nop 0
	global_load_lds_dwordx4 v128, s[60:61]
	s_waitcnt vmcnt(8)
	s_waitcnt lgkmcnt(0)
	s_setprio 1
	s_barrier
	v_mfma_f32_16x16x32_bf16 v[124:127], v[146:149], v[178:181], v[124:127]
	v_mfma_f32_16x16x32_bf16 v[120:123], v[154:157], v[178:181], v[120:123]
	v_mfma_f32_16x16x32_bf16 v[104:107], v[154:157], v[186:189], v[104:107]
	v_mfma_f32_16x16x32_bf16 v[108:111], v[146:149], v[186:189], v[108:111]
	s_setprio 0
	s_setprio 1
	v_mfma_f32_16x16x32_bf16 v[92:95], v[146:149], v[194:197], v[92:95]
	v_mfma_f32_16x16x32_bf16 v[88:91], v[154:157], v[194:197], v[88:91]
	v_mfma_f32_16x16x32_bf16 v[72:75], v[154:157], v[202:205], v[72:75]
	v_mfma_f32_16x16x32_bf16 v[76:79], v[146:149], v[202:205], v[76:79]
	s_setprio 0
	s_setprio 1
	v_mfma_f32_16x16x32_bf16 v[124:127], v[150:153], v[182:185], v[124:127]
	v_mfma_f32_16x16x32_bf16 v[120:123], v[158:161], v[182:185], v[120:123]
	v_mfma_f32_16x16x32_bf16 v[104:107], v[158:161], v[190:193], v[104:107]
	v_mfma_f32_16x16x32_bf16 v[108:111], v[150:153], v[190:193], v[108:111]
	s_setprio 0
	s_setprio 1
	v_mfma_f32_16x16x32_bf16 v[92:95], v[150:153], v[198:201], v[92:95]
	v_mfma_f32_16x16x32_bf16 v[88:91], v[158:161], v[198:201], v[88:91]
	v_mfma_f32_16x16x32_bf16 v[72:75], v[158:161], v[206:209], v[72:75]
	v_mfma_f32_16x16x32_bf16 v[76:79], v[150:153], v[206:209], v[76:79]
	s_setprio 0
	s_setprio 1
	v_mfma_f32_16x16x32_bf16 v[116:119], v[162:165], v[178:181], v[116:119]
	v_mfma_f32_16x16x32_bf16 v[112:115], v[170:173], v[178:181], v[112:115]
	v_mfma_f32_16x16x32_bf16 v[96:99], v[170:173], v[186:189], v[96:99]
	v_mfma_f32_16x16x32_bf16 v[100:103], v[162:165], v[186:189], v[100:103]
	s_setprio 0
	s_setprio 1
	v_mfma_f32_16x16x32_bf16 v[84:87], v[162:165], v[194:197], v[84:87]
	v_mfma_f32_16x16x32_bf16 v[80:83], v[170:173], v[194:197], v[80:83]
	v_mfma_f32_16x16x32_bf16 v[56:59], v[170:173], v[202:205], v[56:59]
	v_mfma_f32_16x16x32_bf16 v[60:63], v[162:165], v[202:205], v[60:63]
	s_setprio 0
	s_setprio 1
	v_mfma_f32_16x16x32_bf16 v[116:119], v[166:169], v[182:185], v[116:119]
	v_mfma_f32_16x16x32_bf16 v[112:115], v[174:177], v[182:185], v[112:115]
	v_mfma_f32_16x16x32_bf16 v[96:99], v[174:177], v[190:193], v[96:99]
	v_mfma_f32_16x16x32_bf16 v[100:103], v[166:169], v[190:193], v[100:103]
	s_setprio 0
	s_setprio 1
	v_mfma_f32_16x16x32_bf16 v[84:87], v[166:169], v[198:201], v[84:87]
	v_mfma_f32_16x16x32_bf16 v[80:83], v[174:177], v[198:201], v[80:83]
	v_mfma_f32_16x16x32_bf16 v[56:59], v[174:177], v[206:209], v[56:59]
	v_mfma_f32_16x16x32_bf16 v[60:63], v[166:169], v[206:209], v[60:63]
	s_barrier
; #define PG8_LDA(dst, b, h) do { if constexpr (FP8) { _Pragma("unroll") for (int m = 0; m < 4; ++m) dst##8[m] = PG8_LD8(PG8_SA(b, h), aoff, aoff1, m); } \
;         else { _Pragma("unroll") for (int m = 0; m < 4; ++m) _Pragma("unroll") for (int k = 0; k < 2; ++k) dst[m][k] = *(const LAS bf16x8*)(lds + PG8_SA(b, h) + (k ? aoff1 : aoff) + m * 2048); } } while (0)
; #define PG8_WAIT_V(n) asm volatile("s_waitcnt vmcnt(" #n ")" ::: "memory")
; #define PG8_WAIT_L(n) asm volatile("s_waitcnt lgkmcnt(" #n ")" ::: "memory")
; #define PG8_BAR __builtin_amdgcn_s_barrier()
; #define PG8_SCHED __builtin_amdgcn_sched_barrier(0)
; #define PG8_S4 do { PG8_STAGE(PG8_SB(1, 0), b3, voffB); PG8_STAGE(PG8_SB(1, 1), b3 + hstepB, voffB); PG8_STAGE(PG8_SA(1, 0), a3, voffA); } while (0)
; template <class Epi, class SchedT, bool ALIGN_EPI, bool SP2, bool FP8 = false>
; __device__ __forceinline__ void gemm_phase(LAS unsigned char* lds, const Gemm g, const SchedT& S, const Epi& E, const int wid) {
;     ...
;             PG8_LDA(At, 1, 1); PG8_S4;
;             PG8_WAIT_V(8); PG8_WAIT_L(0); PG8_BAR; PG8_MMAP(1, 1, 1); PG8_BAR; PG8_SCHED;
	s_setprio 0
	v_mov_b32_e32 v128, v135
	ds_read_b128 v[178:181], v143 offset:49152
	ds_read_b128 v[182:185], v143 offset:50176
	ds_read_b128 v[186:189], v143 offset:51200
	ds_read_b128 v[190:193], v143 offset:52224
	ds_read_b128 v[194:197], v143 offset:53248
	ds_read_b128 v[198:201], v143 offset:54272
	ds_read_b128 v[202:205], v143 offset:55296
	ds_read_b128 v[206:209], v143 offset:56320
	s_add_i32 s6, s6, s86
	v_lshl_add_u64 v[210:211], s[66:67], 0, v[128:129]
	v_lshl_add_u64 v[210:211], v[210:211], 0, s[36:37]
	s_mov_b32 m0, s6
	v_mov_b32_e32 v128, v137
	global_load_lds_dwordx4 v[210:211], off
	s_add_i32 m0, s6, 0x2000
	s_add_u32 s60, s66, 0x40080
	v_lshl_add_u64 v[210:211], s[66:67], 0, v[128:129]
	v_lshl_add_u64 v[210:211], v[210:211], 0, s[36:37]
	s_addc_u32 s61, s67, 0
	v_mov_b32_e32 v128, v135
	s_add_i32 s6, s7, s86
	global_load_lds_dwordx4 v[210:211], off
	s_mov_b32 m0, s6
	s_nop 0
	global_load_lds_dwordx4 v128, s[60:61]
	v_mov_b32_e32 v128, v137
	s_add_i32 m0, s6, 0x2000
	s_nop 0
	global_load_lds_dwordx4 v128, s[60:61]
	v_mov_b32_e32 v128, v134
	s_mov_b32 m0, s92
	v_lshl_add_u64 v[210:211], s[52:53], 0, v[128:129]
	v_lshl_add_u64 v[210:211], v[210:211], 0, s[36:37]
	v_mov_b32_e32 v128, v136
	global_load_lds_dwordx4 v[210:211], off
	s_mov_b32 m0, s93
	v_lshl_add_u64 v[210:211], s[52:53], 0, v[128:129]
	v_lshl_add_u64 v[210:211], v[210:211], 0, s[36:37]
	global_load_lds_dwordx4 v[210:211], off
	s_waitcnt vmcnt(8)
	s_waitcnt lgkmcnt(0)
	s_setprio 1
	s_barrier
	v_mfma_f32_16x16x32_bf16 v[68:71], v[146:149], v[178:181], v[68:71]
	v_mfma_f32_16x16x32_bf16 v[64:67], v[154:157], v[178:181], v[64:67]
	v_mfma_f32_16x16x32_bf16 v[40:43], v[154:157], v[186:189], v[40:43]
	v_mfma_f32_16x16x32_bf16 v[44:47], v[146:149], v[186:189], v[44:47]
	s_setprio 0
	s_setprio 1
	v_mfma_f32_16x16x32_bf16 v[28:31], v[146:149], v[194:197], v[28:31]
	v_mfma_f32_16x16x32_bf16 v[24:27], v[154:157], v[194:197], v[24:27]
	v_mfma_f32_16x16x32_bf16 v[8:11], v[154:157], v[202:205], v[8:11]
	v_mfma_f32_16x16x32_bf16 v[12:15], v[146:149], v[202:205], v[12:15]
	s_setprio 0
	s_setprio 1
	v_mfma_f32_16x16x32_bf16 v[68:71], v[150:153], v[182:185], v[68:71]
	v_mfma_f32_16x16x32_bf16 v[64:67], v[158:161], v[182:185], v[64:67]
	v_mfma_f32_16x16x32_bf16 v[40:43], v[158:161], v[190:193], v[40:43]
	v_mfma_f32_16x16x32_bf16 v[44:47], v[150:153], v[190:193], v[44:47]
	s_setprio 0
	s_setprio 1
	v_mfma_f32_16x16x32_bf16 v[28:31], v[150:153], v[198:201], v[28:31]
	v_mfma_f32_16x16x32_bf16 v[24:27], v[158:161], v[198:201], v[24:27]
	v_mfma_f32_16x16x32_bf16 v[8:11], v[158:161], v[206:209], v[8:11]
	v_mfma_f32_16x16x32_bf16 v[12:15], v[150:153], v[206:209], v[12:15]
	s_setprio 0
	s_setprio 1
	v_mfma_f32_16x16x32_bf16 v[52:55], v[162:165], v[178:181], v[52:55]
	v_mfma_f32_16x16x32_bf16 v[48:51], v[170:173], v[178:181], v[48:51]
	v_mfma_f32_16x16x32_bf16 v[32:35], v[170:173], v[186:189], v[32:35]
	v_mfma_f32_16x16x32_bf16 v[36:39], v[162:165], v[186:189], v[36:39]
	s_setprio 0
	s_setprio 1
	v_mfma_f32_16x16x32_bf16 v[20:23], v[162:165], v[194:197], v[20:23]
	v_mfma_f32_16x16x32_bf16 v[16:19], v[170:173], v[194:197], v[16:19]
	v_mfma_f32_16x16x32_bf16 v[0:3], v[170:173], v[202:205], v[0:3]
	v_mfma_f32_16x16x32_bf16 v[4:7], v[162:165], v[202:205], v[4:7]
	s_setprio 0
	s_setprio 1
	v_mfma_f32_16x16x32_bf16 v[52:55], v[166:169], v[182:185], v[52:55]
	v_mfma_f32_16x16x32_bf16 v[48:51], v[174:177], v[182:185], v[48:51]
	v_mfma_f32_16x16x32_bf16 v[32:35], v[174:177], v[190:193], v[32:35]
	v_mfma_f32_16x16x32_bf16 v[36:39], v[166:169], v[190:193], v[36:39]
	s_setprio 0
	s_setprio 1
	v_mfma_f32_16x16x32_bf16 v[20:23], v[166:169], v[198:201], v[20:23]
	v_mfma_f32_16x16x32_bf16 v[16:19], v[174:177], v[198:201], v[16:19]
	v_mfma_f32_16x16x32_bf16 v[0:3], v[174:177], v[206:209], v[0:3]
	v_mfma_f32_16x16x32_bf16 v[4:7], v[166:169], v[206:209], v[4:7]
	s_barrier
	s_setprio 0
	s_add_u32 s50, s50, 0x100
	s_addc_u32 s51, s51, 0
	s_add_u32 s31, s31, 0x100
	s_addc_u32 s38, s38, 0
	s_cmp_ge_i32 s43, s8
	s_mov_b32 s39, s43
	s_cbranch_scc0 .LBB0_256

; #define PG8_LDA(dst, b, h) do { if constexpr (FP8) { _Pragma("unroll") for (int m = 0; m < 4; ++m) dst##8[m] = PG8_LD8(PG8_SA(b, h), aoff, aoff1, m); } \
;         else { _Pragma("unroll") for (int m = 0; m < 4; ++m) _Pragma("unroll") for (int k = 0; k < 2; ++k) dst[m][k] = *(const LAS bf16x8*)(lds + PG8_SA(b, h) + (k ? aoff1 : aoff) + m * 2048); } } while (0)
; #define PG8_LDB(dst, b, h) do { if constexpr (FP8) { dst##8[0] = PG8_LD8(PG8_SB(b, h), boff, boff1, 0); dst##8[1] = PG8_LD8(PG8_SB(b, h), boff, boff1, 1); } \
;         else { _Pragma("unroll") for (int n = 0; n < 2; ++n) _Pragma("unroll") for (int k = 0; k < 2; ++k) dst[n][k] = *(const LAS bf16x8*)(lds + PG8_SB(b, h) + (k ? boff1 : boff) + n * 2048); } } while (0)
; #define PG8_WAIT_V(n) asm volatile("s_waitcnt vmcnt(" #n ")" ::: "memory")
; #define PG8_WAIT_L(n) asm volatile("s_waitcnt lgkmcnt(" #n ")" ::: "memory")
; #define PG8_BAR __builtin_amdgcn_s_barrier()
; #define PG8_SCHED __builtin_amdgcn_sched_barrier(0)
; #define PG8_S1 PG8_STAGE(PG8_SA(1, 1), a1 + hstepA, voffA)
; #define PG8_S2 do { PG8_STAGE(PG8_SB(0, 0), b2, voffB); PG8_STAGE(PG8_SB(0, 1), b2 + hstepB, voffB); PG8_STAGE(PG8_SA(0, 0), a2, voffA); } while (0)
; template <class Epi, class SchedT, bool ALIGN_EPI, bool SP2, bool FP8 = false>
; __device__ __forceinline__ void gemm_phase(LAS unsigned char* lds, const Gemm g, const SchedT& S, const Epi& E, const int wid) {
;     ...
;             if constexpr (SP2) {
;     ...
;             PG8_LDB(B0, 0, 0); PG8_LDB(B1, 0, 1); PG8_SCHED; PG8_LDA(At, 0, 0); PG8_S1;
;             PG8_WAIT_V(8); PG8_WAIT_L(0); PG8_BAR; PG8_MMAP(0, 0, 0); PG8_BAR; PG8_SCHED;
;             PG8_LDA(At, 0, 1); PG8_S2;
;             PG8_WAIT_V(8); PG8_WAIT_L(0); PG8_BAR; PG8_MMAP(1, 0, 1); PG8_BAR; PG8_SCHED;
.LBB0_538:
	s_add_i32 s20, s71, -2
	s_add_u32 s8, s66, 0x90080
	s_addc_u32 s9, s67, 0
	s_add_u32 s21, s10, 0x100
	s_addc_u32 s24, s11, 0
	s_mov_b32 s10, 0
	ds_read_b128 v[134:137], v215
	ds_read_b128 v[138:141], v215 offset:16
	ds_read_b128 v[142:145], v215 offset:2048
	ds_read_b128 v[146:149], v215 offset:2064
	ds_read_b128 v[150:153], v216
	ds_read_b128 v[154:157], v216 offset:16
	ds_read_b128 v[158:161], v216 offset:2048
	ds_read_b128 v[162:165], v216 offset:2064
	s_add_i32 s30, s10, 2
	s_add_u32 s16, s8, 0xfff70080
	s_addc_u32 s11, s9, -1
	s_cmp_eq_u32 s20, s10
	s_cselect_b32 s10, s52, s16
	s_cselect_b32 s11, s53, s11
	v_mov_b32_e32 v128, v210
	ds_read_b128 v[166:169], v217
	ds_read_b128 v[170:173], v217 offset:16
	ds_read_b128 v[174:177], v217 offset:2048
	ds_read_b128 v[178:181], v217 offset:2064
	ds_read_b128 v[182:185], v217 offset:4096
	ds_read_b128 v[186:189], v217 offset:4112
	ds_read_b128 v[190:193], v217 offset:6144
	ds_read_b128 v[194:197], v217 offset:6160
	s_cselect_b32 s67, s65, s24
	s_cselect_b32 s66, s64, s21
	s_add_i32 m0, s87, 0xc000
	s_nop 0
	global_load_lds_dwordx4 v128, s[8:9]
	v_mov_b32_e32 v128, v212
	s_add_i32 m0, s87, 0xe000
	s_nop 0
	global_load_lds_dwordx4 v128, s[8:9]
	s_waitcnt vmcnt(8)
	s_waitcnt lgkmcnt(0)
	s_setprio 1
	s_barrier
	v_mfma_scale_f32_16x16x128_f8f6f4 v[124:127], v[134:141], v[166:173], 0, v218, v218 op_sel_hi:[0,0,0]
	v_mfma_scale_f32_16x16x128_f8f6f4 v[120:123], v[142:149], v[166:173], 0, v218, v218 op_sel_hi:[0,0,0]
	v_mfma_scale_f32_16x16x128_f8f6f4 v[116:119], v[134:141], v[174:181], 0, v218, v218 op_sel_hi:[0,0,0]
	v_mfma_scale_f32_16x16x128_f8f6f4 v[112:115], v[142:149], v[174:181], 0, v218, v218 op_sel_hi:[0,0,0]
	s_setprio 0
	s_setprio 1
	v_mfma_scale_f32_16x16x128_f8f6f4 v[108:111], v[134:141], v[182:189], 0, v218, v218 op_sel_hi:[0,0,0]
	v_mfma_scale_f32_16x16x128_f8f6f4 v[104:107], v[142:149], v[182:189], 0, v218, v218 op_sel_hi:[0,0,0]
	v_mfma_scale_f32_16x16x128_f8f6f4 v[100:103], v[134:141], v[190:197], 0, v218, v218 op_sel_hi:[0,0,0]
	v_mfma_scale_f32_16x16x128_f8f6f4 v[96:99], v[142:149], v[190:197], 0, v218, v218 op_sel_hi:[0,0,0]
	s_setprio 0
	s_setprio 1
	v_mfma_scale_f32_16x16x128_f8f6f4 v[198:201], v[150:157], v[166:173], 0, v218, v218 op_sel_hi:[0,0,0]
	v_mfma_scale_f32_16x16x128_f8f6f4 v[166:169], v[158:165], v[166:173], 0, v218, v218 op_sel_hi:[0,0,0]
	v_mfma_scale_f32_16x16x128_f8f6f4 v[170:173], v[150:157], v[174:181], 0, v218, v218 op_sel_hi:[0,0,0]
	v_mfma_scale_f32_16x16x128_f8f6f4 v[174:177], v[158:165], v[174:181], 0, v218, v218 op_sel_hi:[0,0,0]
	s_setprio 0
	s_setprio 1
	v_mfma_scale_f32_16x16x128_f8f6f4 v[178:181], v[150:157], v[182:189], 0, v218, v218 op_sel_hi:[0,0,0]
	v_mfma_scale_f32_16x16x128_f8f6f4 v[182:185], v[158:165], v[182:189], 0, v218, v218 op_sel_hi:[0,0,0]
	v_mfma_scale_f32_16x16x128_f8f6f4 v[186:189], v[150:157], v[190:197], 0, v218, v218 op_sel_hi:[0,0,0]
	v_mfma_scale_f32_16x16x128_f8f6f4 v[190:193], v[158:165], v[190:197], 0, v218, v218 op_sel_hi:[0,0,0]
	s_barrier
	s_setprio 0
	v_mov_b32_e32 v128, v211
	s_add_i32 s16, s94, s86
	s_nop 2
	ds_read_b128 v[64:67], v217 offset:16384
	ds_read_b128 v[68:71], v217 offset:16400
	ds_read_b128 v[72:75], v217 offset:18432
	ds_read_b128 v[76:79], v217 offset:18448
	ds_read_b128 v[80:83], v217 offset:20480
	ds_read_b128 v[84:87], v217 offset:20496
	ds_read_b128 v[88:91], v217 offset:22528
	ds_read_b128 v[92:95], v217 offset:22544
	s_mov_b32 m0, s16
	s_nop 0
	global_load_lds_dwordx4 v128, s[66:67]
	v_mov_b32_e32 v128, v213
	s_add_i32 m0, s16, 0x2000
	s_add_u32 s60, s66, 0x88000
	global_load_lds_dwordx4 v128, s[66:67]
	s_addc_u32 s61, s67, 0
	v_mov_b32_e32 v128, v211
	s_add_i32 s16, s95, s86
	s_mov_b32 m0, s16
	s_nop 0
	global_load_lds_dwordx4 v128, s[60:61]
	v_mov_b32_e32 v128, v213
	s_add_i32 m0, s16, 0x2000
	s_nop 0
	global_load_lds_dwordx4 v128, s[60:61]
	v_mov_b32_e32 v128, v210
	s_mov_b32 m0, s87
	s_nop 0
	global_load_lds_dwordx4 v128, s[10:11]
	v_mov_b32_e32 v128, v212
	s_mov_b32 m0, s88
	s_nop 0
	global_load_lds_dwordx4 v128, s[10:11]
	s_waitcnt vmcnt(8)
	s_waitcnt lgkmcnt(0)
	s_setprio 1
	s_barrier
	v_mfma_scale_f32_16x16x128_f8f6f4 v[60:63], v[134:141], v[64:71], 0, v218, v218 op_sel_hi:[0,0,0]
	v_mfma_scale_f32_16x16x128_f8f6f4 v[56:59], v[142:149], v[64:71], 0, v218, v218 op_sel_hi:[0,0,0]
	v_mfma_scale_f32_16x16x128_f8f6f4 v[52:55], v[134:141], v[72:79], 0, v218, v218 op_sel_hi:[0,0,0]
	v_mfma_scale_f32_16x16x128_f8f6f4 v[48:51], v[142:149], v[72:79], 0, v218, v218 op_sel_hi:[0,0,0]
	s_setprio 0
	s_setprio 1
	v_mfma_scale_f32_16x16x128_f8f6f4 v[44:47], v[134:141], v[80:87], 0, v218, v218 op_sel_hi:[0,0,0]
	v_mfma_scale_f32_16x16x128_f8f6f4 v[40:43], v[142:149], v[80:87], 0, v218, v218 op_sel_hi:[0,0,0]
	v_mfma_scale_f32_16x16x128_f8f6f4 v[194:197], v[150:157], v[64:71], 0, v218, v218 op_sel_hi:[0,0,0]
	v_mfma_scale_f32_16x16x128_f8f6f4 v[202:205], v[158:165], v[64:71], 0, v218, v218 op_sel_hi:[0,0,0]
	s_setprio 0
	s_setprio 1
	v_mfma_scale_f32_16x16x128_f8f6f4 v[206:209], v[150:157], v[72:79], 0, v218, v218 op_sel_hi:[0,0,0]
	v_mfma_scale_f32_16x16x128_f8f6f4 v[220:223], v[158:165], v[72:79], 0, v218, v218 op_sel_hi:[0,0,0]
	v_mfma_scale_f32_16x16x128_f8f6f4 v[224:227], v[150:157], v[80:87], 0, v218, v218 op_sel_hi:[0,0,0]
	v_mfma_scale_f32_16x16x128_f8f6f4 v[228:231], v[158:165], v[80:87], 0, v218, v218 op_sel_hi:[0,0,0]
	s_setprio 0
	s_setprio 1
	v_mfma_scale_f32_16x16x128_f8f6f4 v[232:235], v[134:141], v[88:95], 0, v218, v218 op_sel_hi:[0,0,0]
	v_mfma_scale_f32_16x16x128_f8f6f4 v[236:239], v[150:157], v[88:95], 0, v218, v218 op_sel_hi:[0,0,0]
	v_mfma_scale_f32_16x16x128_f8f6f4 v[240:243], v[142:149], v[88:95], 0, v218, v218 op_sel_hi:[0,0,0]
	v_mfma_scale_f32_16x16x128_f8f6f4 v[244:247], v[158:165], v[88:95], 0, v218, v218 op_sel_hi:[0,0,0]
	s_barrier
; #define PG8_LDA(dst, b, h) do { if constexpr (FP8) { _Pragma("unroll") for (int m = 0; m < 4; ++m) dst##8[m] = PG8_LD8(PG8_SA(b, h), aoff, aoff1, m); } \
;         else { _Pragma("unroll") for (int m = 0; m < 4; ++m) _Pragma("unroll") for (int k = 0; k < 2; ++k) dst[m][k] = *(const LAS bf16x8*)(lds + PG8_SA(b, h) + (k ? aoff1 : aoff) + m * 2048); } } while (0)
; #define PG8_LDB(dst, b, h) do { if constexpr (FP8) { dst##8[0] = PG8_LD8(PG8_SB(b, h), boff, boff1, 0); dst##8[1] = PG8_LD8(PG8_SB(b, h), boff, boff1, 1); } \
;         else { _Pragma("unroll") for (int n = 0; n < 2; ++n) _Pragma("unroll") for (int k = 0; k < 2; ++k) dst[n][k] = *(const LAS bf16x8*)(lds + PG8_SB(b, h) + (k ? boff1 : boff) + n * 2048); } } while (0)
; #define PG8_WAIT_V(n) asm volatile("s_waitcnt vmcnt(" #n ")" ::: "memory")
; #define PG8_WAIT_L(n) asm volatile("s_waitcnt lgkmcnt(" #n ")" ::: "memory")
; #define PG8_BAR __builtin_amdgcn_s_barrier()
; #define PG8_SCHED __builtin_amdgcn_sched_barrier(0)
; #define PG8_S3 PG8_STAGE(PG8_SA(0, 1), a2 + hstepA, voffA)
; #define PG8_S4 do { PG8_STAGE(PG8_SB(1, 0), b3, voffB); PG8_STAGE(PG8_SB(1, 1), b3 + hstepB, voffB); PG8_STAGE(PG8_SA(1, 0), a3, voffA); } while (0)
; template <class Epi, class SchedT, bool ALIGN_EPI, bool SP2, bool FP8 = false>
; __device__ __forceinline__ void gemm_phase(LAS unsigned char* lds, const Gemm g, const SchedT& S, const Epi& E, const int wid) {
;     ...
;             PG8_LDB(B0, 1, 0); PG8_LDB(B1, 1, 1); PG8_SCHED; PG8_LDA(At, 1, 0); PG8_S3;
;             PG8_WAIT_V(8); PG8_WAIT_L(0); PG8_BAR; PG8_MMAP(0, 1, 0); PG8_BAR; PG8_SCHED;
;             PG8_LDA(At, 1, 1); PG8_S4;
;             PG8_WAIT_V(8); PG8_WAIT_L(0); PG8_BAR; PG8_MMAP(1, 1, 1); PG8_BAR; PG8_SCHED;
	s_setprio 0
	s_add_i32 s16, 0, 0x18000
	v_add_u32_e32 v8, s16, v214
	s_add_i32 s17, 0, 0x1c000
	s_nop 1
	ds_read_b128 v[0:3], v8
	ds_read_b128 v[4:7], v8 offset:16
	ds_read_b128 v[134:137], v8 offset:2048
	ds_read_b128 v[138:141], v8 offset:2064
	v_add_u32_e32 v8, s17, v214
	ds_read_b128 v[142:145], v8
	ds_read_b128 v[146:149], v8 offset:16
	ds_read_b128 v[150:153], v8 offset:2048
	ds_read_b128 v[154:157], v8 offset:2064
	s_add_u32 s60, s10, 0x90000
	v_mov_b32_e32 v64, v210
	s_mov_b32 m0, s89
	ds_read_b128 v[8:11], v217 offset:32768
	ds_read_b128 v[12:15], v217 offset:32784
	ds_read_b128 v[16:19], v217 offset:34816
	ds_read_b128 v[20:23], v217 offset:34832
	ds_read_b128 v[24:27], v217 offset:36864
	ds_read_b128 v[28:31], v217 offset:36880
	ds_read_b128 v[32:35], v217 offset:38912
	ds_read_b128 v[36:39], v217 offset:38928
	s_addc_u32 s61, s11, 0
	s_nop 0
	global_load_lds_dwordx4 v64, s[60:61]
	v_mov_b32_e32 v64, v212
	s_mov_b32 m0, s90
	s_nop 0
	global_load_lds_dwordx4 v64, s[60:61]
	s_waitcnt vmcnt(8)
	s_waitcnt lgkmcnt(0)
	s_setprio 1
	s_barrier
	v_mfma_scale_f32_16x16x128_f8f6f4 v[124:127], v[0:7], v[8:15], v[124:127], v218, v218 op_sel_hi:[0,0,0]
	v_mfma_scale_f32_16x16x128_f8f6f4 v[92:95], v[142:149], v[8:15], v[198:201], v218, v218 op_sel_hi:[0,0,0]
	v_mfma_scale_f32_16x16x128_f8f6f4 v[120:123], v[134:141], v[8:15], v[120:123], v218, v218 op_sel_hi:[0,0,0]
	v_mfma_scale_f32_16x16x128_f8f6f4 v[88:91], v[150:157], v[8:15], v[166:169], v218, v218 op_sel_hi:[0,0,0]
	s_setprio 0
	s_setprio 1
	v_mfma_scale_f32_16x16x128_f8f6f4 v[116:119], v[0:7], v[16:23], v[116:119], v218, v218 op_sel_hi:[0,0,0]
	v_mfma_scale_f32_16x16x128_f8f6f4 v[84:87], v[142:149], v[16:23], v[170:173], v218, v218 op_sel_hi:[0,0,0]
	v_mfma_scale_f32_16x16x128_f8f6f4 v[112:115], v[134:141], v[16:23], v[112:115], v218, v218 op_sel_hi:[0,0,0]
	v_mfma_scale_f32_16x16x128_f8f6f4 v[80:83], v[150:157], v[16:23], v[174:177], v218, v218 op_sel_hi:[0,0,0]
	s_setprio 0
	s_setprio 1
	v_mfma_scale_f32_16x16x128_f8f6f4 v[108:111], v[0:7], v[24:31], v[108:111], v218, v218 op_sel_hi:[0,0,0]
	v_mfma_scale_f32_16x16x128_f8f6f4 v[76:79], v[142:149], v[24:31], v[178:181], v218, v218 op_sel_hi:[0,0,0]
	v_mfma_scale_f32_16x16x128_f8f6f4 v[104:107], v[134:141], v[24:31], v[104:107], v218, v218 op_sel_hi:[0,0,0]
	v_mfma_scale_f32_16x16x128_f8f6f4 v[72:75], v[150:157], v[24:31], v[182:185], v218, v218 op_sel_hi:[0,0,0]
	s_setprio 0
	s_setprio 1
	v_mfma_scale_f32_16x16x128_f8f6f4 v[100:103], v[0:7], v[32:39], v[100:103], v218, v218 op_sel_hi:[0,0,0]
	v_mfma_scale_f32_16x16x128_f8f6f4 v[68:71], v[142:149], v[32:39], v[186:189], v218, v218 op_sel_hi:[0,0,0]
	v_mfma_scale_f32_16x16x128_f8f6f4 v[96:99], v[134:141], v[32:39], v[96:99], v218, v218 op_sel_hi:[0,0,0]
	v_mfma_scale_f32_16x16x128_f8f6f4 v[64:67], v[150:157], v[32:39], v[190:193], v218, v218 op_sel_hi:[0,0,0]
	s_barrier
	s_setprio 0
	v_mov_b32_e32 v128, v211
	ds_read_b128 v[8:11], v217 offset:49152
	ds_read_b128 v[12:15], v217 offset:49168
	ds_read_b128 v[32:35], v217 offset:51200
	ds_read_b128 v[36:39], v217 offset:51216
	ds_read_b128 v[158:161], v217 offset:53248
	ds_read_b128 v[162:165], v217 offset:53264
	ds_read_b128 v[166:169], v217 offset:55296
	ds_read_b128 v[170:173], v217 offset:55312
	s_add_i32 s16, s16, s86
	v_lshl_add_u64 v[16:17], s[66:67], 0, v[128:129]
	v_lshl_add_u64 v[16:17], v[16:17], 0, s[44:45]
	s_mov_b32 m0, s16
	v_mov_b32_e32 v128, v213
	global_load_lds_dwordx4 v[16:17], off
	s_add_i32 m0, s16, 0x2000
	v_lshl_add_u64 v[16:17], s[66:67], 0, v[128:129]
	v_lshl_add_u64 v[16:17], v[16:17], 0, s[44:45]
	s_add_u32 s60, s66, 0x88080
	global_load_lds_dwordx4 v[16:17], off
	s_addc_u32 s61, s67, 0
	v_mov_b32_e32 v16, v211
	s_add_i32 s16, s17, s86
	s_mov_b32 m0, s16
	v_mov_b32_e32 v128, v210
	global_load_lds_dwordx4 v16, s[60:61]
	v_mov_b32_e32 v16, v213
	s_add_i32 m0, s16, 0x2000
	s_nop 0
	global_load_lds_dwordx4 v16, s[60:61]
	s_mov_b32 m0, s92
	v_lshl_add_u64 v[16:17], s[10:11], 0, v[128:129]
	v_lshl_add_u64 v[16:17], v[16:17], 0, s[44:45]
	v_mov_b32_e32 v128, v212
	global_load_lds_dwordx4 v[16:17], off
	s_mov_b32 m0, s93
	v_lshl_add_u64 v[16:17], s[10:11], 0, v[128:129]
	v_lshl_add_u64 v[16:17], v[16:17], 0, s[44:45]
	global_load_lds_dwordx4 v[16:17], off
	s_waitcnt vmcnt(8)
	s_waitcnt lgkmcnt(0)
	s_setprio 1
	s_barrier
	v_mfma_scale_f32_16x16x128_f8f6f4 v[60:63], v[0:7], v[8:15], v[60:63], v218, v218 op_sel_hi:[0,0,0]
	v_mfma_scale_f32_16x16x128_f8f6f4 v[28:31], v[142:149], v[8:15], v[194:197], v218, v218 op_sel_hi:[0,0,0]
	v_mfma_scale_f32_16x16x128_f8f6f4 v[56:59], v[134:141], v[8:15], v[56:59], v218, v218 op_sel_hi:[0,0,0]
	v_mfma_scale_f32_16x16x128_f8f6f4 v[24:27], v[150:157], v[8:15], v[202:205], v218, v218 op_sel_hi:[0,0,0]
	s_setprio 0
	s_setprio 1
	v_mfma_scale_f32_16x16x128_f8f6f4 v[52:55], v[0:7], v[32:39], v[52:55], v218, v218 op_sel_hi:[0,0,0]
	v_mfma_scale_f32_16x16x128_f8f6f4 v[20:23], v[142:149], v[32:39], v[206:209], v218, v218 op_sel_hi:[0,0,0]
	v_mfma_scale_f32_16x16x128_f8f6f4 v[48:51], v[134:141], v[32:39], v[48:51], v218, v218 op_sel_hi:[0,0,0]
	v_mfma_scale_f32_16x16x128_f8f6f4 v[16:19], v[150:157], v[32:39], v[220:223], v218, v218 op_sel_hi:[0,0,0]
	s_setprio 0
	s_setprio 1
	v_mfma_scale_f32_16x16x128_f8f6f4 v[44:47], v[0:7], v[158:165], v[44:47], v218, v218 op_sel_hi:[0,0,0]
	v_mfma_scale_f32_16x16x128_f8f6f4 v[12:15], v[142:149], v[158:165], v[224:227], v218, v218 op_sel_hi:[0,0,0]
	v_mfma_scale_f32_16x16x128_f8f6f4 v[40:43], v[134:141], v[158:165], v[40:43], v218, v218 op_sel_hi:[0,0,0]
	v_mfma_scale_f32_16x16x128_f8f6f4 v[8:11], v[150:157], v[158:165], v[228:231], v218, v218 op_sel_hi:[0,0,0]
	s_setprio 0
	s_setprio 1
	v_mfma_scale_f32_16x16x128_f8f6f4 v[36:39], v[0:7], v[166:173], v[232:235], v218, v218 op_sel_hi:[0,0,0]
	v_mfma_scale_f32_16x16x128_f8f6f4 v[4:7], v[142:149], v[166:173], v[236:239], v218, v218 op_sel_hi:[0,0,0]
	v_mfma_scale_f32_16x16x128_f8f6f4 v[32:35], v[134:141], v[166:173], v[240:243], v218, v218 op_sel_hi:[0,0,0]
	v_mfma_scale_f32_16x16x128_f8f6f4 v[0:3], v[150:157], v[166:173], v[244:247], v218, v218 op_sel_hi:[0,0,0]
	s_barrier
	s_setprio 0
	s_add_u32 s8, s8, 0x100
	s_addc_u32 s9, s9, 0
	s_add_u32 s21, s21, 0x100
	s_addc_u32 s24, s24, 0
	s_cmp_ge_i32 s30, s71
	s_mov_b32 s10, s30
	s_cbranch_scc1 .Lpeel_exit_lbb0_539
; #define PG8_LDA(dst, b, h) do { if constexpr (FP8) { _Pragma("unroll") for (int m = 0; m < 4; ++m) dst##8[m] = PG8_LD8(PG8_SA(b, h), aoff, aoff1, m); } \
;         else { _Pragma("unroll") for (int m = 0; m < 4; ++m) _Pragma("unroll") for (int k = 0; k < 2; ++k) dst[m][k] = *(const LAS bf16x8*)(lds + PG8_SA(b, h) + (k ? aoff1 : aoff) + m * 2048); } } while (0)
; #define PG8_LDB(dst, b, h) do { if constexpr (FP8) { dst##8[0] = PG8_LD8(PG8_SB(b, h), boff, boff1, 0); dst##8[1] = PG8_LD8(PG8_SB(b, h), boff, boff1, 1); } \
;         else { _Pragma("unroll") for (int n = 0; n < 2; ++n) _Pragma("unroll") for (int k = 0; k < 2; ++k) dst[n][k] = *(const LAS bf16x8*)(lds + PG8_SB(b, h) + (k ? boff1 : boff) + n * 2048); } } while (0)
; #define PG8_WAIT_V(n) asm volatile("s_waitcnt vmcnt(" #n ")" ::: "memory")
; #define PG8_WAIT_L(n) asm volatile("s_waitcnt lgkmcnt(" #n ")" ::: "memory")
; #define PG8_BAR __builtin_amdgcn_s_barrier()
; #define PG8_SCHED __builtin_amdgcn_sched_barrier(0)
; #define PG8_S1 PG8_STAGE(PG8_SA(1, 1), a1 + hstepA, voffA)
; #define PG8_S2 do { PG8_STAGE(PG8_SB(0, 0), b2, voffB); PG8_STAGE(PG8_SB(0, 1), b2 + hstepB, voffB); PG8_STAGE(PG8_SA(0, 0), a2, voffA); } while (0)
; template <class Epi, class SchedT, bool ALIGN_EPI, bool SP2, bool FP8 = false>
; __device__ __forceinline__ void gemm_phase(LAS unsigned char* lds, const Gemm g, const SchedT& S, const Epi& E, const int wid) {
;     ...
;         for (int t = 0; t < nt; t += 2) {
;             const bool last = (t == nt - 2);
;             const char* a1 = cA + (size_t)(t + 1) * kstep;
;             const char* a2 = last ? nA : cA + (size_t)(t + 2) * kstep; const char* b2 = last ? nB : cB + (size_t)(t + 2) * kstep;
;             const char* a3 = a2 + kstep; const char* b3 = b2 + kstep;
;             if constexpr (SP2) {
;     ...
;             PG8_LDB(B0, 0, 0); PG8_LDB(B1, 0, 1); PG8_SCHED; PG8_LDA(At, 0, 0); PG8_S1;
;             PG8_WAIT_V(8); PG8_WAIT_L(0); PG8_BAR; PG8_MMAP(0, 0, 0); PG8_BAR; PG8_SCHED;
;             PG8_LDA(At, 0, 1); PG8_S2;
;             PG8_WAIT_V(8); PG8_WAIT_L(0); PG8_BAR; PG8_MMAP(1, 0, 1); PG8_BAR; PG8_SCHED;
.LBB0_539:
	ds_read_b128 v[134:137], v215
	ds_read_b128 v[138:141], v215 offset:16
	ds_read_b128 v[142:145], v215 offset:2048
	ds_read_b128 v[146:149], v215 offset:2064
	ds_read_b128 v[150:153], v216
	ds_read_b128 v[154:157], v216 offset:16
	ds_read_b128 v[158:161], v216 offset:2048
	ds_read_b128 v[162:165], v216 offset:2064
	s_add_i32 s30, s10, 2
	s_add_u32 s16, s8, 0xfff70080
	s_addc_u32 s11, s9, -1
	s_cmp_eq_u32 s20, s10
	s_cselect_b32 s10, s52, s16
	s_cselect_b32 s11, s53, s11
	v_mov_b32_e32 v128, v210
	ds_read_b128 v[166:169], v217
	ds_read_b128 v[170:173], v217 offset:16
	ds_read_b128 v[174:177], v217 offset:2048
	ds_read_b128 v[178:181], v217 offset:2064
	ds_read_b128 v[182:185], v217 offset:4096
	ds_read_b128 v[186:189], v217 offset:4112
	ds_read_b128 v[190:193], v217 offset:6144
	ds_read_b128 v[194:197], v217 offset:6160
	s_cselect_b32 s67, s65, s24
	s_cselect_b32 s66, s64, s21
	s_add_i32 m0, s87, 0xc000
	s_nop 0
	global_load_lds_dwordx4 v128, s[8:9]
	v_mov_b32_e32 v128, v212
	s_add_i32 m0, s87, 0xe000
	s_nop 0
	global_load_lds_dwordx4 v128, s[8:9]
	s_waitcnt vmcnt(8)
	s_waitcnt lgkmcnt(0)
	s_setprio 1
	s_barrier
	v_mfma_scale_f32_16x16x128_f8f6f4 v[124:127], v[134:141], v[166:173], v[124:127], v218, v218 op_sel_hi:[0,0,0]
	v_mfma_scale_f32_16x16x128_f8f6f4 v[120:123], v[142:149], v[166:173], v[120:123], v218, v218 op_sel_hi:[0,0,0]
	v_mfma_scale_f32_16x16x128_f8f6f4 v[116:119], v[134:141], v[174:181], v[116:119], v218, v218 op_sel_hi:[0,0,0]
	v_mfma_scale_f32_16x16x128_f8f6f4 v[112:115], v[142:149], v[174:181], v[112:115], v218, v218 op_sel_hi:[0,0,0]
	s_setprio 0
	s_setprio 1
	v_mfma_scale_f32_16x16x128_f8f6f4 v[108:111], v[134:141], v[182:189], v[108:111], v218, v218 op_sel_hi:[0,0,0]
	v_mfma_scale_f32_16x16x128_f8f6f4 v[104:107], v[142:149], v[182:189], v[104:107], v218, v218 op_sel_hi:[0,0,0]
	v_mfma_scale_f32_16x16x128_f8f6f4 v[100:103], v[134:141], v[190:197], v[100:103], v218, v218 op_sel_hi:[0,0,0]
	v_mfma_scale_f32_16x16x128_f8f6f4 v[96:99], v[142:149], v[190:197], v[96:99], v218, v218 op_sel_hi:[0,0,0]
	s_setprio 0
	s_setprio 1
	v_mfma_scale_f32_16x16x128_f8f6f4 v[198:201], v[150:157], v[166:173], v[92:95], v218, v218 op_sel_hi:[0,0,0]
	v_mfma_scale_f32_16x16x128_f8f6f4 v[166:169], v[158:165], v[166:173], v[88:91], v218, v218 op_sel_hi:[0,0,0]
	v_mfma_scale_f32_16x16x128_f8f6f4 v[170:173], v[150:157], v[174:181], v[84:87], v218, v218 op_sel_hi:[0,0,0]
	v_mfma_scale_f32_16x16x128_f8f6f4 v[174:177], v[158:165], v[174:181], v[80:83], v218, v218 op_sel_hi:[0,0,0]
	s_setprio 0
	s_setprio 1
	v_mfma_scale_f32_16x16x128_f8f6f4 v[178:181], v[150:157], v[182:189], v[76:79], v218, v218 op_sel_hi:[0,0,0]
	v_mfma_scale_f32_16x16x128_f8f6f4 v[182:185], v[158:165], v[182:189], v[72:75], v218, v218 op_sel_hi:[0,0,0]
	v_mfma_scale_f32_16x16x128_f8f6f4 v[186:189], v[150:157], v[190:197], v[68:71], v218, v218 op_sel_hi:[0,0,0]
	v_mfma_scale_f32_16x16x128_f8f6f4 v[190:193], v[158:165], v[190:197], v[64:67], v218, v218 op_sel_hi:[0,0,0]
	s_barrier
	s_setprio 0
	v_mov_b32_e32 v128, v211
	s_add_i32 s16, s94, s86
	s_nop 2
	ds_read_b128 v[64:67], v217 offset:16384
	ds_read_b128 v[68:71], v217 offset:16400
	ds_read_b128 v[72:75], v217 offset:18432
	ds_read_b128 v[76:79], v217 offset:18448
	ds_read_b128 v[80:83], v217 offset:20480
	ds_read_b128 v[84:87], v217 offset:20496
	ds_read_b128 v[88:91], v217 offset:22528
	ds_read_b128 v[92:95], v217 offset:22544
	s_mov_b32 m0, s16
	s_nop 0
	global_load_lds_dwordx4 v128, s[66:67]
	v_mov_b32_e32 v128, v213
	s_add_i32 m0, s16, 0x2000
	s_add_u32 s60, s66, 0x88000
	global_load_lds_dwordx4 v128, s[66:67]
	s_addc_u32 s61, s67, 0
	v_mov_b32_e32 v128, v211
	s_add_i32 s16, s95, s86
	s_mov_b32 m0, s16
	s_nop 0
	global_load_lds_dwordx4 v128, s[60:61]
	v_mov_b32_e32 v128, v213
	s_add_i32 m0, s16, 0x2000
	s_nop 0
	global_load_lds_dwordx4 v128, s[60:61]
	v_mov_b32_e32 v128, v210
	s_mov_b32 m0, s87
	s_nop 0
	global_load_lds_dwordx4 v128, s[10:11]
	v_mov_b32_e32 v128, v212
	s_mov_b32 m0, s88
	s_nop 0
	global_load_lds_dwordx4 v128, s[10:11]
	s_waitcnt vmcnt(8)
	s_waitcnt lgkmcnt(0)
	s_setprio 1
	s_barrier
	v_mfma_scale_f32_16x16x128_f8f6f4 v[60:63], v[134:141], v[64:71], v[60:63], v218, v218 op_sel_hi:[0,0,0]
	v_mfma_scale_f32_16x16x128_f8f6f4 v[56:59], v[142:149], v[64:71], v[56:59], v218, v218 op_sel_hi:[0,0,0]
	v_mfma_scale_f32_16x16x128_f8f6f4 v[52:55], v[134:141], v[72:79], v[52:55], v218, v218 op_sel_hi:[0,0,0]
	v_mfma_scale_f32_16x16x128_f8f6f4 v[48:51], v[142:149], v[72:79], v[48:51], v218, v218 op_sel_hi:[0,0,0]
	s_setprio 0
	s_setprio 1
	v_mfma_scale_f32_16x16x128_f8f6f4 v[44:47], v[134:141], v[80:87], v[44:47], v218, v218 op_sel_hi:[0,0,0]
	v_mfma_scale_f32_16x16x128_f8f6f4 v[40:43], v[142:149], v[80:87], v[40:43], v218, v218 op_sel_hi:[0,0,0]
	v_mfma_scale_f32_16x16x128_f8f6f4 v[194:197], v[150:157], v[64:71], v[28:31], v218, v218 op_sel_hi:[0,0,0]
	v_mfma_scale_f32_16x16x128_f8f6f4 v[202:205], v[158:165], v[64:71], v[24:27], v218, v218 op_sel_hi:[0,0,0]
	s_setprio 0
	s_setprio 1
	v_mfma_scale_f32_16x16x128_f8f6f4 v[206:209], v[150:157], v[72:79], v[20:23], v218, v218 op_sel_hi:[0,0,0]
	v_mfma_scale_f32_16x16x128_f8f6f4 v[220:223], v[158:165], v[72:79], v[16:19], v218, v218 op_sel_hi:[0,0,0]
	v_mfma_scale_f32_16x16x128_f8f6f4 v[224:227], v[150:157], v[80:87], v[12:15], v218, v218 op_sel_hi:[0,0,0]
	v_mfma_scale_f32_16x16x128_f8f6f4 v[228:231], v[158:165], v[80:87], v[8:11], v218, v218 op_sel_hi:[0,0,0]
	s_setprio 0
	s_setprio 1
	v_mfma_scale_f32_16x16x128_f8f6f4 v[232:235], v[134:141], v[88:95], v[36:39], v218, v218 op_sel_hi:[0,0,0]
	v_mfma_scale_f32_16x16x128_f8f6f4 v[236:239], v[150:157], v[88:95], v[4:7], v218, v218 op_sel_hi:[0,0,0]
	v_mfma_scale_f32_16x16x128_f8f6f4 v[240:243], v[142:149], v[88:95], v[32:35], v218, v218 op_sel_hi:[0,0,0]
	v_mfma_scale_f32_16x16x128_f8f6f4 v[244:247], v[158:165], v[88:95], v[0:3], v218, v218 op_sel_hi:[0,0,0]
	s_barrier
; #define PG8_LDA(dst, b, h) do { if constexpr (FP8) { _Pragma("unroll") for (int m = 0; m < 4; ++m) dst##8[m] = PG8_LD8(PG8_SA(b, h), aoff, aoff1, m); } \
;         else { _Pragma("unroll") for (int m = 0; m < 4; ++m) _Pragma("unroll") for (int k = 0; k < 2; ++k) dst[m][k] = *(const LAS bf16x8*)(lds + PG8_SA(b, h) + (k ? aoff1 : aoff) + m * 2048); } } while (0)
; #define PG8_LDB(dst, b, h) do { if constexpr (FP8) { dst##8[0] = PG8_LD8(PG8_SB(b, h), boff, boff1, 0); dst##8[1] = PG8_LD8(PG8_SB(b, h), boff, boff1, 1); } \
;         else { _Pragma("unroll") for (int n = 0; n < 2; ++n) _Pragma("unroll") for (int k = 0; k < 2; ++k) dst[n][k] = *(const LAS bf16x8*)(lds + PG8_SB(b, h) + (k ? boff1 : boff) + n * 2048); } } while (0)
; #define PG8_WAIT_V(n) asm volatile("s_waitcnt vmcnt(" #n ")" ::: "memory")
; #define PG8_WAIT_L(n) asm volatile("s_waitcnt lgkmcnt(" #n ")" ::: "memory")
; #define PG8_BAR __builtin_amdgcn_s_barrier()
; #define PG8_SCHED __builtin_amdgcn_sched_barrier(0)
; #define PG8_S3 PG8_STAGE(PG8_SA(0, 1), a2 + hstepA, voffA)
; #define PG8_S4 do { PG8_STAGE(PG8_SB(1, 0), b3, voffB); PG8_STAGE(PG8_SB(1, 1), b3 + hstepB, voffB); PG8_STAGE(PG8_SA(1, 0), a3, voffA); } while (0)
; template <class Epi, class SchedT, bool ALIGN_EPI, bool SP2, bool FP8 = false>
; __device__ __forceinline__ void gemm_phase(LAS unsigned char* lds, const Gemm g, const SchedT& S, const Epi& E, const int wid) {
;     ...
;             PG8_LDB(B0, 1, 0); PG8_LDB(B1, 1, 1); PG8_SCHED; PG8_LDA(At, 1, 0); PG8_S3;
;             PG8_WAIT_V(8); PG8_WAIT_L(0); PG8_BAR; PG8_MMAP(0, 1, 0); PG8_BAR; PG8_SCHED;
;             PG8_LDA(At, 1, 1); PG8_S4;
;             PG8_WAIT_V(8); PG8_WAIT_L(0); PG8_BAR; PG8_MMAP(1, 1, 1); PG8_BAR; PG8_SCHED;
	s_setprio 0
	s_add_i32 s16, 0, 0x18000
	v_add_u32_e32 v8, s16, v214
	s_add_i32 s17, 0, 0x1c000
	s_nop 1
	ds_read_b128 v[0:3], v8
	ds_read_b128 v[4:7], v8 offset:16
	ds_read_b128 v[134:137], v8 offset:2048
	ds_read_b128 v[138:141], v8 offset:2064
	v_add_u32_e32 v8, s17, v214
	ds_read_b128 v[142:145], v8
	ds_read_b128 v[146:149], v8 offset:16
	ds_read_b128 v[150:153], v8 offset:2048
	ds_read_b128 v[154:157], v8 offset:2064
	s_add_u32 s60, s10, 0x90000
	v_mov_b32_e32 v64, v210
	s_mov_b32 m0, s89
	ds_read_b128 v[8:11], v217 offset:32768
	ds_read_b128 v[12:15], v217 offset:32784
	ds_read_b128 v[16:19], v217 offset:34816
	ds_read_b128 v[20:23], v217 offset:34832
	ds_read_b128 v[24:27], v217 offset:36864
	ds_read_b128 v[28:31], v217 offset:36880
	ds_read_b128 v[32:35], v217 offset:38912
	ds_read_b128 v[36:39], v217 offset:38928
	s_addc_u32 s61, s11, 0
	s_nop 0
	global_load_lds_dwordx4 v64, s[60:61]
	v_mov_b32_e32 v64, v212
	s_mov_b32 m0, s90
	s_nop 0
	global_load_lds_dwordx4 v64, s[60:61]
	s_waitcnt vmcnt(8)
	s_waitcnt lgkmcnt(0)
	s_setprio 1
	s_barrier
	v_mfma_scale_f32_16x16x128_f8f6f4 v[124:127], v[0:7], v[8:15], v[124:127], v218, v218 op_sel_hi:[0,0,0]
	v_mfma_scale_f32_16x16x128_f8f6f4 v[92:95], v[142:149], v[8:15], v[198:201], v218, v218 op_sel_hi:[0,0,0]
	v_mfma_scale_f32_16x16x128_f8f6f4 v[120:123], v[134:141], v[8:15], v[120:123], v218, v218 op_sel_hi:[0,0,0]
	v_mfma_scale_f32_16x16x128_f8f6f4 v[88:91], v[150:157], v[8:15], v[166:169], v218, v218 op_sel_hi:[0,0,0]
	s_setprio 0
	s_setprio 1
	v_mfma_scale_f32_16x16x128_f8f6f4 v[116:119], v[0:7], v[16:23], v[116:119], v218, v218 op_sel_hi:[0,0,0]
	v_mfma_scale_f32_16x16x128_f8f6f4 v[84:87], v[142:149], v[16:23], v[170:173], v218, v218 op_sel_hi:[0,0,0]
	v_mfma_scale_f32_16x16x128_f8f6f4 v[112:115], v[134:141], v[16:23], v[112:115], v218, v218 op_sel_hi:[0,0,0]
	v_mfma_scale_f32_16x16x128_f8f6f4 v[80:83], v[150:157], v[16:23], v[174:177], v218, v218 op_sel_hi:[0,0,0]
	s_setprio 0
	s_setprio 1
	v_mfma_scale_f32_16x16x128_f8f6f4 v[108:111], v[0:7], v[24:31], v[108:111], v218, v218 op_sel_hi:[0,0,0]
	v_mfma_scale_f32_16x16x128_f8f6f4 v[76:79], v[142:149], v[24:31], v[178:181], v218, v218 op_sel_hi:[0,0,0]
	v_mfma_scale_f32_16x16x128_f8f6f4 v[104:107], v[134:141], v[24:31], v[104:107], v218, v218 op_sel_hi:[0,0,0]
	v_mfma_scale_f32_16x16x128_f8f6f4 v[72:75], v[150:157], v[24:31], v[182:185], v218, v218 op_sel_hi:[0,0,0]
	s_setprio 0
	s_setprio 1
	v_mfma_scale_f32_16x16x128_f8f6f4 v[100:103], v[0:7], v[32:39], v[100:103], v218, v218 op_sel_hi:[0,0,0]
	v_mfma_scale_f32_16x16x128_f8f6f4 v[68:71], v[142:149], v[32:39], v[186:189], v218, v218 op_sel_hi:[0,0,0]
	v_mfma_scale_f32_16x16x128_f8f6f4 v[96:99], v[134:141], v[32:39], v[96:99], v218, v218 op_sel_hi:[0,0,0]
	v_mfma_scale_f32_16x16x128_f8f6f4 v[64:67], v[150:157], v[32:39], v[190:193], v218, v218 op_sel_hi:[0,0,0]
	s_barrier
	s_setprio 0
	v_mov_b32_e32 v128, v211
	ds_read_b128 v[8:11], v217 offset:49152
	ds_read_b128 v[12:15], v217 offset:49168
	ds_read_b128 v[32:35], v217 offset:51200
	ds_read_b128 v[36:39], v217 offset:51216
	ds_read_b128 v[158:161], v217 offset:53248
	ds_read_b128 v[162:165], v217 offset:53264
	ds_read_b128 v[166:169], v217 offset:55296
	ds_read_b128 v[170:173], v217 offset:55312
	s_add_i32 s16, s16, s86
	v_lshl_add_u64 v[16:17], s[66:67], 0, v[128:129]
	v_lshl_add_u64 v[16:17], v[16:17], 0, s[44:45]
	s_mov_b32 m0, s16
	v_mov_b32_e32 v128, v213
	global_load_lds_dwordx4 v[16:17], off
	s_add_i32 m0, s16, 0x2000
	v_lshl_add_u64 v[16:17], s[66:67], 0, v[128:129]
	v_lshl_add_u64 v[16:17], v[16:17], 0, s[44:45]
	s_add_u32 s60, s66, 0x88080
	global_load_lds_dwordx4 v[16:17], off
	s_addc_u32 s61, s67, 0
	v_mov_b32_e32 v16, v211
	s_add_i32 s16, s17, s86
	s_mov_b32 m0, s16
	v_mov_b32_e32 v128, v210
	global_load_lds_dwordx4 v16, s[60:61]
	v_mov_b32_e32 v16, v213
	s_add_i32 m0, s16, 0x2000
	s_nop 0
	global_load_lds_dwordx4 v16, s[60:61]
	s_mov_b32 m0, s92
	v_lshl_add_u64 v[16:17], s[10:11], 0, v[128:129]
	v_lshl_add_u64 v[16:17], v[16:17], 0, s[44:45]
	v_mov_b32_e32 v128, v212
	global_load_lds_dwordx4 v[16:17], off
	s_mov_b32 m0, s93
	v_lshl_add_u64 v[16:17], s[10:11], 0, v[128:129]
	v_lshl_add_u64 v[16:17], v[16:17], 0, s[44:45]
	global_load_lds_dwordx4 v[16:17], off
	s_waitcnt vmcnt(8)
	s_waitcnt lgkmcnt(0)
	s_setprio 1
	s_barrier
	v_mfma_scale_f32_16x16x128_f8f6f4 v[60:63], v[0:7], v[8:15], v[60:63], v218, v218 op_sel_hi:[0,0,0]
	v_mfma_scale_f32_16x16x128_f8f6f4 v[28:31], v[142:149], v[8:15], v[194:197], v218, v218 op_sel_hi:[0,0,0]
	v_mfma_scale_f32_16x16x128_f8f6f4 v[56:59], v[134:141], v[8:15], v[56:59], v218, v218 op_sel_hi:[0,0,0]
	v_mfma_scale_f32_16x16x128_f8f6f4 v[24:27], v[150:157], v[8:15], v[202:205], v218, v218 op_sel_hi:[0,0,0]
	s_setprio 0
	s_setprio 1
	v_mfma_scale_f32_16x16x128_f8f6f4 v[52:55], v[0:7], v[32:39], v[52:55], v218, v218 op_sel_hi:[0,0,0]
	v_mfma_scale_f32_16x16x128_f8f6f4 v[20:23], v[142:149], v[32:39], v[206:209], v218, v218 op_sel_hi:[0,0,0]
	v_mfma_scale_f32_16x16x128_f8f6f4 v[48:51], v[134:141], v[32:39], v[48:51], v218, v218 op_sel_hi:[0,0,0]
	v_mfma_scale_f32_16x16x128_f8f6f4 v[16:19], v[150:157], v[32:39], v[220:223], v218, v218 op_sel_hi:[0,0,0]
	s_setprio 0
	s_setprio 1
	v_mfma_scale_f32_16x16x128_f8f6f4 v[44:47], v[0:7], v[158:165], v[44:47], v218, v218 op_sel_hi:[0,0,0]
	v_mfma_scale_f32_16x16x128_f8f6f4 v[12:15], v[142:149], v[158:165], v[224:227], v218, v218 op_sel_hi:[0,0,0]
	v_mfma_scale_f32_16x16x128_f8f6f4 v[40:43], v[134:141], v[158:165], v[40:43], v218, v218 op_sel_hi:[0,0,0]
	v_mfma_scale_f32_16x16x128_f8f6f4 v[8:11], v[150:157], v[158:165], v[228:231], v218, v218 op_sel_hi:[0,0,0]
	s_setprio 0
	s_setprio 1
	v_mfma_scale_f32_16x16x128_f8f6f4 v[36:39], v[0:7], v[166:173], v[232:235], v218, v218 op_sel_hi:[0,0,0]
	v_mfma_scale_f32_16x16x128_f8f6f4 v[4:7], v[142:149], v[166:173], v[236:239], v218, v218 op_sel_hi:[0,0,0]
	v_mfma_scale_f32_16x16x128_f8f6f4 v[32:35], v[134:141], v[166:173], v[240:243], v218, v218 op_sel_hi:[0,0,0]
	v_mfma_scale_f32_16x16x128_f8f6f4 v[0:3], v[150:157], v[166:173], v[244:247], v218, v218 op_sel_hi:[0,0,0]
	s_barrier
	s_setprio 0
	s_add_u32 s8, s8, 0x100
	s_addc_u32 s9, s9, 0
	s_add_u32 s21, s21, 0x100
	s_addc_u32 s24, s24, 0
	s_cmp_ge_i32 s30, s71
	s_mov_b32 s10, s30
	s_cbranch_scc0 .LBB0_539

; #define PG8_LDA(dst, b, h) do { if constexpr (FP8) { _Pragma("unroll") for (int m = 0; m < 4; ++m) dst##8[m] = PG8_LD8(PG8_SA(b, h), aoff, aoff1, m); } \
;         else { _Pragma("unroll") for (int m = 0; m < 4; ++m) _Pragma("unroll") for (int k = 0; k < 2; ++k) dst[m][k] = *(const LAS bf16x8*)(lds + PG8_SA(b, h) + (k ? aoff1 : aoff) + m * 2048); } } while (0)
; #define PG8_LDB(dst, b, h) do { if constexpr (FP8) { dst##8[0] = PG8_LD8(PG8_SB(b, h), boff, boff1, 0); dst##8[1] = PG8_LD8(PG8_SB(b, h), boff, boff1, 1); } \
;         else { _Pragma("unroll") for (int n = 0; n < 2; ++n) _Pragma("unroll") for (int k = 0; k < 2; ++k) dst[n][k] = *(const LAS bf16x8*)(lds + PG8_SB(b, h) + (k ? boff1 : boff) + n * 2048); } } while (0)
; #define PG8_WAIT_V(n) asm volatile("s_waitcnt vmcnt(" #n ")" ::: "memory")
; #define PG8_WAIT_L(n) asm volatile("s_waitcnt lgkmcnt(" #n ")" ::: "memory")
; #define PG8_BAR __builtin_amdgcn_s_barrier()
; #define PG8_SCHED __builtin_amdgcn_sched_barrier(0)
; #define PG8_S1 PG8_STAGE(PG8_SA(1, 1), a1 + hstepA, voffA)
; template <class Epi, class SchedT, bool ALIGN_EPI, bool SP2, bool FP8 = false>
; __device__ __forceinline__ void gemm_phase(LAS unsigned char* lds, const Gemm g, const SchedT& S, const Epi& E, const int wid) {
;     ...
;     for (;;) {
;         const bool has_next = S.next(ui + 1, nxt);
;         const char* nA = has_next ? (const char*)g.A + (size_t)nxt.pm * tstepA + (size_t)nxt.aoff * 2 : cA; const char* nB = has_next ? (const char*)g.Bt + (size_t)nxt.pn * tstepB + (size_t)nxt.boff * 2 : cB;
;         const int nt = cur.nt;
;         for (int t = 0; t < nt; t += 2) {
;             const bool last = (t == nt - 2);
;             const char* a1 = cA + (size_t)(t + 1) * kstep;
;             const char* a2 = last ? nA : cA + (size_t)(t + 2) * kstep; const char* b2 = last ? nB : cB + (size_t)(t + 2) * kstep;
;             const char* a3 = a2 + kstep; const char* b3 = b2 + kstep;
;             if constexpr (SP2) {
;     ...
;             PG8_LDB(B0, 0, 0); PG8_LDB(B1, 0, 1); PG8_SCHED; PG8_LDA(At, 0, 0); PG8_S1;
;             PG8_WAIT_V(8); PG8_WAIT_L(0); PG8_BAR; PG8_MMAP(0, 0, 0); PG8_BAR; PG8_SCHED;
;             PG8_LDA(At, 0, 1); PG8_S2;
;             PG8_WAIT_V(8); PG8_WAIT_L(0); PG8_BAR; PG8_MMAP(1, 0, 1); PG8_BAR; PG8_SCHED;
.LBB0_777:
	s_ashr_i32 s47, s46, 31
	s_lshl_b64 s[22:23], s[46:47], 18
	s_add_u32 s48, s36, s22
	s_addc_u32 s49, s37, s23
	s_ashr_i32 s45, s44, 31
	s_lshl_b64 s[22:23], s[44:45], 18
	s_add_u32 s50, s12, s22
	s_addc_u32 s51, s13, s23
	s_cmp_lt_i32 s20, 1
	s_cbranch_scc1 .LBB0_833
	s_and_b64 s[22:23], s[6:7], exec
	s_cselect_b32 s9, s49, s53
	s_cselect_b32 s21, s48, s52
	s_cselect_b32 s22, s51, s65
	s_cselect_b32 s23, s50, s64
	s_add_i32 s24, s20, -2
	s_add_u32 s52, s52, 0x20080
	s_addc_u32 s53, s53, 0
	s_add_u32 s30, s64, 0x100
	s_addc_u32 s31, s65, 0
	s_mov_b32 s47, 0
	s_waitcnt lgkmcnt(0)
	ds_read_b128 v[134:137], v149
	ds_read_b128 v[138:141], v149 offset:16
	ds_read_b128 v[154:157], v149 offset:2048
	ds_read_b128 v[158:161], v149 offset:2064
	ds_read_b128 v[162:165], v150
	ds_read_b128 v[166:169], v150 offset:16
	ds_read_b128 v[170:173], v150 offset:2048
	ds_read_b128 v[174:177], v150 offset:2064
	s_add_i32 s45, s47, 2
	s_add_u32 s16, s52, 0xfffe0080
	s_addc_u32 s17, s53, -1
	s_cmp_eq_u32 s24, s47
	s_cselect_b32 s65, s9, s17
	s_cselect_b32 s64, s21, s16
	v_mov_b32_e32 v128, v146
	ds_read_b128 v[178:181], v151
	ds_read_b128 v[182:185], v151 offset:16
	ds_read_b128 v[186:189], v151 offset:2048
	ds_read_b128 v[190:193], v151 offset:2064
	ds_read_b128 v[194:197], v151 offset:4096
	ds_read_b128 v[198:201], v151 offset:4112
	ds_read_b128 v[202:205], v151 offset:6144
	ds_read_b128 v[206:209], v151 offset:6160
	s_cselect_b32 s67, s22, s31
	s_cselect_b32 s66, s23, s30
	s_add_i32 m0, s87, 0xc000
	s_nop 0
	global_load_lds_dwordx4 v128, s[52:53]
	v_mov_b32_e32 v128, v147
	s_add_i32 m0, s87, 0xe000
	s_nop 0
	global_load_lds_dwordx4 v128, s[52:53]
	s_waitcnt vmcnt(8)
	s_waitcnt lgkmcnt(0)
	s_setprio 1
	s_barrier
	v_mfma_scale_f32_16x16x128_f8f6f4 v[124:127], v[134:141], v[178:185], 0, v152, v152 op_sel_hi:[0,0,0]
	v_mfma_scale_f32_16x16x128_f8f6f4 v[108:111], v[162:169], v[178:185], 0, v152, v152 op_sel_hi:[0,0,0]
	v_mfma_scale_f32_16x16x128_f8f6f4 v[120:123], v[154:161], v[178:185], 0, v152, v152 op_sel_hi:[0,0,0]
	v_mfma_scale_f32_16x16x128_f8f6f4 v[100:103], v[170:177], v[178:185], 0, v152, v152 op_sel_hi:[0,0,0]
	s_setprio 0
	s_setprio 1
	v_mfma_scale_f32_16x16x128_f8f6f4 v[116:119], v[134:141], v[186:193], 0, v152, v152 op_sel_hi:[0,0,0]
	v_mfma_scale_f32_16x16x128_f8f6f4 v[112:115], v[154:161], v[186:193], 0, v152, v152 op_sel_hi:[0,0,0]
	v_mfma_scale_f32_16x16x128_f8f6f4 v[104:107], v[134:141], v[194:201], 0, v152, v152 op_sel_hi:[0,0,0]
	v_mfma_scale_f32_16x16x128_f8f6f4 v[60:63], v[170:177], v[202:209], 0, v152, v152 op_sel_hi:[0,0,0]
	s_setprio 0
	s_setprio 1
	v_mfma_scale_f32_16x16x128_f8f6f4 v[142:145], v[162:169], v[186:193], 0, v152, v152 op_sel_hi:[0,0,0]
	v_mfma_scale_f32_16x16x128_f8f6f4 v[178:181], v[170:177], v[186:193], 0, v152, v152 op_sel_hi:[0,0,0]
	v_mfma_scale_f32_16x16x128_f8f6f4 v[182:185], v[162:169], v[194:201], 0, v152, v152 op_sel_hi:[0,0,0]
	v_mfma_scale_f32_16x16x128_f8f6f4 v[186:189], v[154:161], v[194:201], 0, v152, v152 op_sel_hi:[0,0,0]
	s_setprio 0
	s_setprio 1
	v_mfma_scale_f32_16x16x128_f8f6f4 v[190:193], v[170:177], v[194:201], 0, v152, v152 op_sel_hi:[0,0,0]
	v_mfma_scale_f32_16x16x128_f8f6f4 v[194:197], v[134:141], v[202:209], 0, v152, v152 op_sel_hi:[0,0,0]
	v_mfma_scale_f32_16x16x128_f8f6f4 v[198:201], v[162:169], v[202:209], 0, v152, v152 op_sel_hi:[0,0,0]
	v_mfma_scale_f32_16x16x128_f8f6f4 v[210:213], v[154:161], v[202:209], 0, v152, v152 op_sel_hi:[0,0,0]
	s_barrier
	s_setprio 0
	v_mov_b32_e32 v128, v146
	s_add_i32 s16, s94, s86
	s_nop 1
	ds_read_b128 v[68:71], v151 offset:16384
	ds_read_b128 v[72:75], v151 offset:16400
	ds_read_b128 v[76:79], v151 offset:18432
	ds_read_b128 v[80:83], v151 offset:18448
	ds_read_b128 v[84:87], v151 offset:20480
	ds_read_b128 v[88:91], v151 offset:20496
	ds_read_b128 v[92:95], v151 offset:22528
	ds_read_b128 v[96:99], v151 offset:22544
	s_mov_b32 m0, s16
	s_nop 0
	global_load_lds_dwordx4 v128, s[66:67]
	v_mov_b32_e32 v128, v147
	s_add_i32 m0, s16, 0x2000
	s_add_u32 s60, s66, 0x20000
	global_load_lds_dwordx4 v128, s[66:67]
	s_addc_u32 s61, s67, 0
	v_mov_b32_e32 v128, v146
	s_add_i32 s16, s95, s86
	s_mov_b32 m0, s16
	s_nop 0
	global_load_lds_dwordx4 v128, s[60:61]
	v_mov_b32_e32 v128, v147
	s_add_i32 m0, s16, 0x2000
	s_nop 0
	global_load_lds_dwordx4 v128, s[60:61]
	v_mov_b32_e32 v128, v146
	s_mov_b32 m0, s87
	s_nop 0
	global_load_lds_dwordx4 v128, s[64:65]
	v_mov_b32_e32 v128, v147
	s_mov_b32 m0, s88
	s_nop 0
	global_load_lds_dwordx4 v128, s[64:65]
	s_waitcnt vmcnt(8)
	s_waitcnt lgkmcnt(0)
	s_setprio 1
	s_barrier
	v_mfma_scale_f32_16x16x128_f8f6f4 v[64:67], v[134:141], v[68:75], 0, v152, v152 op_sel_hi:[0,0,0]
	v_mfma_scale_f32_16x16x128_f8f6f4 v[44:47], v[162:169], v[68:75], 0, v152, v152 op_sel_hi:[0,0,0]
	v_mfma_scale_f32_16x16x128_f8f6f4 v[56:59], v[154:161], v[68:75], 0, v152, v152 op_sel_hi:[0,0,0]
	v_mfma_scale_f32_16x16x128_f8f6f4 v[52:55], v[134:141], v[76:83], 0, v152, v152 op_sel_hi:[0,0,0]
	s_setprio 0
	s_setprio 1
	v_mfma_scale_f32_16x16x128_f8f6f4 v[48:51], v[154:161], v[76:83], 0, v152, v152 op_sel_hi:[0,0,0]
	v_mfma_scale_f32_16x16x128_f8f6f4 v[40:43], v[134:141], v[84:91], 0, v152, v152 op_sel_hi:[0,0,0]
	v_mfma_scale_f32_16x16x128_f8f6f4 v[202:205], v[170:177], v[68:75], 0, v152, v152 op_sel_hi:[0,0,0]
	v_mfma_scale_f32_16x16x128_f8f6f4 v[206:209], v[162:169], v[76:83], 0, v152, v152 op_sel_hi:[0,0,0]
	s_setprio 0
	s_setprio 1
	v_mfma_scale_f32_16x16x128_f8f6f4 v[214:217], v[170:177], v[76:83], 0, v152, v152 op_sel_hi:[0,0,0]
	v_mfma_scale_f32_16x16x128_f8f6f4 v[218:221], v[162:169], v[84:91], 0, v152, v152 op_sel_hi:[0,0,0]
	v_mfma_scale_f32_16x16x128_f8f6f4 v[222:225], v[154:161], v[84:91], 0, v152, v152 op_sel_hi:[0,0,0]
	v_mfma_scale_f32_16x16x128_f8f6f4 v[226:229], v[170:177], v[84:91], 0, v152, v152 op_sel_hi:[0,0,0]
	s_setprio 0
	s_setprio 1
	v_mfma_scale_f32_16x16x128_f8f6f4 v[230:233], v[134:141], v[92:99], 0, v152, v152 op_sel_hi:[0,0,0]
	v_mfma_scale_f32_16x16x128_f8f6f4 v[234:237], v[162:169], v[92:99], 0, v152, v152 op_sel_hi:[0,0,0]
	v_mfma_scale_f32_16x16x128_f8f6f4 v[238:241], v[154:161], v[92:99], 0, v152, v152 op_sel_hi:[0,0,0]
	v_mfma_scale_f32_16x16x128_f8f6f4 v[242:245], v[170:177], v[92:99], 0, v152, v152 op_sel_hi:[0,0,0]
	s_barrier
; #define PG8_LDA(dst, b, h) do { if constexpr (FP8) { _Pragma("unroll") for (int m = 0; m < 4; ++m) dst##8[m] = PG8_LD8(PG8_SA(b, h), aoff, aoff1, m); } \
;         else { _Pragma("unroll") for (int m = 0; m < 4; ++m) _Pragma("unroll") for (int k = 0; k < 2; ++k) dst[m][k] = *(const LAS bf16x8*)(lds + PG8_SA(b, h) + (k ? aoff1 : aoff) + m * 2048); } } while (0)
; #define PG8_LDB(dst, b, h) do { if constexpr (FP8) { dst##8[0] = PG8_LD8(PG8_SB(b, h), boff, boff1, 0); dst##8[1] = PG8_LD8(PG8_SB(b, h), boff, boff1, 1); } \
;         else { _Pragma("unroll") for (int n = 0; n < 2; ++n) _Pragma("unroll") for (int k = 0; k < 2; ++k) dst[n][k] = *(const LAS bf16x8*)(lds + PG8_SB(b, h) + (k ? boff1 : boff) + n * 2048); } } while (0)
; #define PG8_WAIT_V(n) asm volatile("s_waitcnt vmcnt(" #n ")" ::: "memory")
; #define PG8_WAIT_L(n) asm volatile("s_waitcnt lgkmcnt(" #n ")" ::: "memory")
; #define PG8_BAR __builtin_amdgcn_s_barrier()
; #define PG8_SCHED __builtin_amdgcn_sched_barrier(0)
; #define PG8_S3 PG8_STAGE(PG8_SA(0, 1), a2 + hstepA, voffA)
; #define PG8_S4 do { PG8_STAGE(PG8_SB(1, 0), b3, voffB); PG8_STAGE(PG8_SB(1, 1), b3 + hstepB, voffB); PG8_STAGE(PG8_SA(1, 0), a3, voffA); } while (0)
; template <class Epi, class SchedT, bool ALIGN_EPI, bool SP2, bool FP8 = false>
; __device__ __forceinline__ void gemm_phase(LAS unsigned char* lds, const Gemm g, const SchedT& S, const Epi& E, const int wid) {
;     ...
;             PG8_LDB(B0, 1, 0); PG8_LDB(B1, 1, 1); PG8_SCHED; PG8_LDA(At, 1, 0); PG8_S3;
;             PG8_WAIT_V(8); PG8_WAIT_L(0); PG8_BAR; PG8_MMAP(0, 1, 0); PG8_BAR; PG8_SCHED;
;             PG8_LDA(At, 1, 1); PG8_S4;
;             PG8_WAIT_V(8); PG8_WAIT_L(0); PG8_BAR; PG8_MMAP(1, 1, 1); PG8_BAR; PG8_SCHED;
	s_setprio 0
	s_add_i32 s16, 0, 0x18000
	v_add_u32_e32 v8, s16, v148
	s_add_i32 s17, 0, 0x1c000
	s_nop 1
	ds_read_b128 v[0:3], v8
	ds_read_b128 v[4:7], v8 offset:16
	ds_read_b128 v[134:137], v8 offset:2048
	ds_read_b128 v[138:141], v8 offset:2064
	v_add_u32_e32 v8, s17, v148
	ds_read_b128 v[154:157], v8
	ds_read_b128 v[158:161], v8 offset:16
	ds_read_b128 v[162:165], v8 offset:2048
	ds_read_b128 v[166:169], v8 offset:2064
	s_add_u32 s60, s64, 0x20000
	v_mov_b32_e32 v68, v146
	s_mov_b32 m0, s89
	ds_read_b128 v[8:11], v151 offset:32768
	ds_read_b128 v[12:15], v151 offset:32784
	ds_read_b128 v[16:19], v151 offset:34816
	ds_read_b128 v[20:23], v151 offset:34832
	ds_read_b128 v[24:27], v151 offset:36864
	ds_read_b128 v[28:31], v151 offset:36880
	ds_read_b128 v[32:35], v151 offset:38912
	ds_read_b128 v[36:39], v151 offset:38928
	s_addc_u32 s61, s65, 0
	s_nop 0
	global_load_lds_dwordx4 v68, s[60:61]
	v_mov_b32_e32 v68, v147
	s_mov_b32 m0, s90
	s_nop 0
	global_load_lds_dwordx4 v68, s[60:61]
	s_waitcnt vmcnt(8)
	s_waitcnt lgkmcnt(0)
	s_setprio 1
	s_barrier
	v_mfma_scale_f32_16x16x128_f8f6f4 v[124:127], v[0:7], v[8:15], v[124:127], v152, v152 op_sel_hi:[0,0,0]
	v_mfma_scale_f32_16x16x128_f8f6f4 v[108:111], v[154:161], v[8:15], v[108:111], v152, v152 op_sel_hi:[0,0,0]
	v_mfma_scale_f32_16x16x128_f8f6f4 v[120:123], v[134:141], v[8:15], v[120:123], v152, v152 op_sel_hi:[0,0,0]
	v_mfma_scale_f32_16x16x128_f8f6f4 v[100:103], v[162:169], v[8:15], v[100:103], v152, v152 op_sel_hi:[0,0,0]
	s_setprio 0
	s_setprio 1
	v_mfma_scale_f32_16x16x128_f8f6f4 v[116:119], v[0:7], v[16:23], v[116:119], v152, v152 op_sel_hi:[0,0,0]
	v_mfma_scale_f32_16x16x128_f8f6f4 v[92:95], v[154:161], v[16:23], v[142:145], v152, v152 op_sel_hi:[0,0,0]
	v_mfma_scale_f32_16x16x128_f8f6f4 v[112:115], v[134:141], v[16:23], v[112:115], v152, v152 op_sel_hi:[0,0,0]
	v_mfma_scale_f32_16x16x128_f8f6f4 v[84:87], v[162:169], v[16:23], v[178:181], v152, v152 op_sel_hi:[0,0,0]
	s_setprio 0
	s_setprio 1
	v_mfma_scale_f32_16x16x128_f8f6f4 v[104:107], v[0:7], v[24:31], v[104:107], v152, v152 op_sel_hi:[0,0,0]
	v_mfma_scale_f32_16x16x128_f8f6f4 v[76:79], v[154:161], v[24:31], v[182:185], v152, v152 op_sel_hi:[0,0,0]
	v_mfma_scale_f32_16x16x128_f8f6f4 v[96:99], v[134:141], v[24:31], v[186:189], v152, v152 op_sel_hi:[0,0,0]
	v_mfma_scale_f32_16x16x128_f8f6f4 v[72:75], v[162:169], v[24:31], v[190:193], v152, v152 op_sel_hi:[0,0,0]
	s_setprio 0
	s_setprio 1
	v_mfma_scale_f32_16x16x128_f8f6f4 v[88:91], v[0:7], v[32:39], v[194:197], v152, v152 op_sel_hi:[0,0,0]
	v_mfma_scale_f32_16x16x128_f8f6f4 v[68:71], v[154:161], v[32:39], v[198:201], v152, v152 op_sel_hi:[0,0,0]
	v_mfma_scale_f32_16x16x128_f8f6f4 v[80:83], v[134:141], v[32:39], v[210:213], v152, v152 op_sel_hi:[0,0,0]
	v_mfma_scale_f32_16x16x128_f8f6f4 v[60:63], v[162:169], v[32:39], v[60:63], v152, v152 op_sel_hi:[0,0,0]
	s_barrier
	s_setprio 0
	v_mov_b32_e32 v128, v146
	ds_read_b128 v[8:11], v151 offset:49152
	ds_read_b128 v[12:15], v151 offset:49168
	ds_read_b128 v[16:19], v151 offset:51200
	ds_read_b128 v[20:23], v151 offset:51216
	ds_read_b128 v[170:173], v151 offset:53248
	ds_read_b128 v[174:177], v151 offset:53264
	ds_read_b128 v[178:181], v151 offset:55296
	ds_read_b128 v[182:185], v151 offset:55312
	s_add_i32 s16, s16, s86
	v_lshl_add_u64 v[24:25], s[66:67], 0, v[128:129]
	v_lshl_add_u64 v[24:25], v[24:25], 0, s[26:27]
	s_mov_b32 m0, s16
	v_mov_b32_e32 v128, v147
	global_load_lds_dwordx4 v[24:25], off
	s_add_i32 m0, s16, 0x2000
	v_lshl_add_u64 v[24:25], s[66:67], 0, v[128:129]
	v_lshl_add_u64 v[24:25], v[24:25], 0, s[26:27]
	s_add_u32 s60, s66, 0x20080
	global_load_lds_dwordx4 v[24:25], off
	s_addc_u32 s61, s67, 0
	v_mov_b32_e32 v24, v146
	s_add_i32 s16, s17, s86
	s_mov_b32 m0, s16
	v_mov_b32_e32 v128, v146
	global_load_lds_dwordx4 v24, s[60:61]
	v_mov_b32_e32 v24, v147
	s_add_i32 m0, s16, 0x2000
	s_nop 0
	global_load_lds_dwordx4 v24, s[60:61]
	s_mov_b32 m0, s92
	v_lshl_add_u64 v[24:25], s[64:65], 0, v[128:129]
	v_lshl_add_u64 v[24:25], v[24:25], 0, s[26:27]
	v_mov_b32_e32 v128, v147
	global_load_lds_dwordx4 v[24:25], off
	s_mov_b32 m0, s93
	v_lshl_add_u64 v[24:25], s[64:65], 0, v[128:129]
	v_lshl_add_u64 v[24:25], v[24:25], 0, s[26:27]
	global_load_lds_dwordx4 v[24:25], off
	s_waitcnt vmcnt(8)
	s_waitcnt lgkmcnt(0)
	s_setprio 1
	s_barrier
	v_mfma_scale_f32_16x16x128_f8f6f4 v[64:67], v[0:7], v[8:15], v[64:67], v152, v152 op_sel_hi:[0,0,0]
	v_mfma_scale_f32_16x16x128_f8f6f4 v[44:47], v[154:161], v[8:15], v[44:47], v152, v152 op_sel_hi:[0,0,0]
	v_mfma_scale_f32_16x16x128_f8f6f4 v[56:59], v[134:141], v[8:15], v[56:59], v152, v152 op_sel_hi:[0,0,0]
	v_mfma_scale_f32_16x16x128_f8f6f4 v[36:39], v[162:169], v[8:15], v[202:205], v152, v152 op_sel_hi:[0,0,0]
	s_setprio 0
	s_setprio 1
	v_mfma_scale_f32_16x16x128_f8f6f4 v[52:55], v[0:7], v[16:23], v[52:55], v152, v152 op_sel_hi:[0,0,0]
	v_mfma_scale_f32_16x16x128_f8f6f4 v[28:31], v[154:161], v[16:23], v[206:209], v152, v152 op_sel_hi:[0,0,0]
	v_mfma_scale_f32_16x16x128_f8f6f4 v[48:51], v[134:141], v[16:23], v[48:51], v152, v152 op_sel_hi:[0,0,0]
	v_mfma_scale_f32_16x16x128_f8f6f4 v[20:23], v[162:169], v[16:23], v[214:217], v152, v152 op_sel_hi:[0,0,0]
	s_setprio 0
	s_setprio 1
	v_mfma_scale_f32_16x16x128_f8f6f4 v[40:43], v[0:7], v[170:177], v[40:43], v152, v152 op_sel_hi:[0,0,0]
	v_mfma_scale_f32_16x16x128_f8f6f4 v[12:15], v[154:161], v[170:177], v[218:221], v152, v152 op_sel_hi:[0,0,0]
	v_mfma_scale_f32_16x16x128_f8f6f4 v[32:35], v[134:141], v[170:177], v[222:225], v152, v152 op_sel_hi:[0,0,0]
	v_mfma_scale_f32_16x16x128_f8f6f4 v[8:11], v[162:169], v[170:177], v[226:229], v152, v152 op_sel_hi:[0,0,0]
	s_setprio 0
	s_setprio 1
	v_mfma_scale_f32_16x16x128_f8f6f4 v[24:27], v[0:7], v[178:185], v[230:233], v152, v152 op_sel_hi:[0,0,0]
	v_mfma_scale_f32_16x16x128_f8f6f4 v[4:7], v[154:161], v[178:185], v[234:237], v152, v152 op_sel_hi:[0,0,0]
	v_mfma_scale_f32_16x16x128_f8f6f4 v[16:19], v[134:141], v[178:185], v[238:241], v152, v152 op_sel_hi:[0,0,0]
	v_mfma_scale_f32_16x16x128_f8f6f4 v[0:3], v[162:169], v[178:185], v[242:245], v152, v152 op_sel_hi:[0,0,0]
	s_barrier
	s_setprio 0
	s_add_u32 s52, s52, 0x100
	s_addc_u32 s53, s53, 0
	s_add_u32 s30, s30, 0x100
	s_addc_u32 s31, s31, 0
	s_cmp_ge_i32 s45, s20
	s_mov_b32 s47, s45
	s_cbranch_scc1 .Lpeel_exit_lbb0_779
; #define PG8_LDA(dst, b, h) do { if constexpr (FP8) { _Pragma("unroll") for (int m = 0; m < 4; ++m) dst##8[m] = PG8_LD8(PG8_SA(b, h), aoff, aoff1, m); } \
;         else { _Pragma("unroll") for (int m = 0; m < 4; ++m) _Pragma("unroll") for (int k = 0; k < 2; ++k) dst[m][k] = *(const LAS bf16x8*)(lds + PG8_SA(b, h) + (k ? aoff1 : aoff) + m * 2048); } } while (0)
; #define PG8_LDB(dst, b, h) do { if constexpr (FP8) { dst##8[0] = PG8_LD8(PG8_SB(b, h), boff, boff1, 0); dst##8[1] = PG8_LD8(PG8_SB(b, h), boff, boff1, 1); } \
;         else { _Pragma("unroll") for (int n = 0; n < 2; ++n) _Pragma("unroll") for (int k = 0; k < 2; ++k) dst[n][k] = *(const LAS bf16x8*)(lds + PG8_SB(b, h) + (k ? boff1 : boff) + n * 2048); } } while (0)
; #define PG8_WAIT_V(n) asm volatile("s_waitcnt vmcnt(" #n ")" ::: "memory")
; #define PG8_WAIT_L(n) asm volatile("s_waitcnt lgkmcnt(" #n ")" ::: "memory")
; #define PG8_BAR __builtin_amdgcn_s_barrier()
; #define PG8_SCHED __builtin_amdgcn_sched_barrier(0)
; #define PG8_S1 PG8_STAGE(PG8_SA(1, 1), a1 + hstepA, voffA)
; #define PG8_S2 do { PG8_STAGE(PG8_SB(0, 0), b2, voffB); PG8_STAGE(PG8_SB(0, 1), b2 + hstepB, voffB); PG8_STAGE(PG8_SA(0, 0), a2, voffA); } while (0)
; template <class Epi, class SchedT, bool ALIGN_EPI, bool SP2, bool FP8 = false>
; __device__ __forceinline__ void gemm_phase(LAS unsigned char* lds, const Gemm g, const SchedT& S, const Epi& E, const int wid) {
;     ...
;         for (int t = 0; t < nt; t += 2) {
;             const bool last = (t == nt - 2);
;             const char* a1 = cA + (size_t)(t + 1) * kstep;
;             const char* a2 = last ? nA : cA + (size_t)(t + 2) * kstep; const char* b2 = last ? nB : cB + (size_t)(t + 2) * kstep;
;             const char* a3 = a2 + kstep; const char* b3 = b2 + kstep;
;             if constexpr (SP2) {
;     ...
;             PG8_LDB(B0, 0, 0); PG8_LDB(B1, 0, 1); PG8_SCHED; PG8_LDA(At, 0, 0); PG8_S1;
;             PG8_WAIT_V(8); PG8_WAIT_L(0); PG8_BAR; PG8_MMAP(0, 0, 0); PG8_BAR; PG8_SCHED;
;             PG8_LDA(At, 0, 1); PG8_S2;
;             PG8_WAIT_V(8); PG8_WAIT_L(0); PG8_BAR; PG8_MMAP(1, 0, 1); PG8_BAR; PG8_SCHED;
.LBB0_779:
	ds_read_b128 v[134:137], v149
	ds_read_b128 v[138:141], v149 offset:16
	ds_read_b128 v[154:157], v149 offset:2048
	ds_read_b128 v[158:161], v149 offset:2064
	ds_read_b128 v[162:165], v150
	ds_read_b128 v[166:169], v150 offset:16
	ds_read_b128 v[170:173], v150 offset:2048
	ds_read_b128 v[174:177], v150 offset:2064
	s_add_i32 s45, s47, 2
	s_add_u32 s16, s52, 0xfffe0080
	s_addc_u32 s17, s53, -1
	s_cmp_eq_u32 s24, s47
	s_cselect_b32 s65, s9, s17
	s_cselect_b32 s64, s21, s16
	v_mov_b32_e32 v128, v146
	ds_read_b128 v[178:181], v151
	ds_read_b128 v[182:185], v151 offset:16
	ds_read_b128 v[186:189], v151 offset:2048
	ds_read_b128 v[190:193], v151 offset:2064
	ds_read_b128 v[194:197], v151 offset:4096
	ds_read_b128 v[198:201], v151 offset:4112
	ds_read_b128 v[202:205], v151 offset:6144
	ds_read_b128 v[206:209], v151 offset:6160
	s_cselect_b32 s67, s22, s31
	s_cselect_b32 s66, s23, s30
	s_add_i32 m0, s87, 0xc000
	s_nop 0
	global_load_lds_dwordx4 v128, s[52:53]
	v_mov_b32_e32 v128, v147
	s_add_i32 m0, s87, 0xe000
	s_nop 0
	global_load_lds_dwordx4 v128, s[52:53]
	s_waitcnt vmcnt(8)
	s_waitcnt lgkmcnt(0)
	s_setprio 1
	s_barrier
	v_mfma_scale_f32_16x16x128_f8f6f4 v[124:127], v[134:141], v[178:185], v[124:127], v152, v152 op_sel_hi:[0,0,0]
	v_mfma_scale_f32_16x16x128_f8f6f4 v[108:111], v[162:169], v[178:185], v[108:111], v152, v152 op_sel_hi:[0,0,0]
	v_mfma_scale_f32_16x16x128_f8f6f4 v[120:123], v[154:161], v[178:185], v[120:123], v152, v152 op_sel_hi:[0,0,0]
	v_mfma_scale_f32_16x16x128_f8f6f4 v[100:103], v[170:177], v[178:185], v[100:103], v152, v152 op_sel_hi:[0,0,0]
	s_setprio 0
	s_setprio 1
	v_mfma_scale_f32_16x16x128_f8f6f4 v[116:119], v[134:141], v[186:193], v[116:119], v152, v152 op_sel_hi:[0,0,0]
	v_mfma_scale_f32_16x16x128_f8f6f4 v[112:115], v[154:161], v[186:193], v[112:115], v152, v152 op_sel_hi:[0,0,0]
	v_mfma_scale_f32_16x16x128_f8f6f4 v[104:107], v[134:141], v[194:201], v[104:107], v152, v152 op_sel_hi:[0,0,0]
	v_mfma_scale_f32_16x16x128_f8f6f4 v[60:63], v[170:177], v[202:209], v[60:63], v152, v152 op_sel_hi:[0,0,0]
	s_setprio 0
	s_setprio 1
	v_mfma_scale_f32_16x16x128_f8f6f4 v[142:145], v[162:169], v[186:193], v[92:95], v152, v152 op_sel_hi:[0,0,0]
	v_mfma_scale_f32_16x16x128_f8f6f4 v[178:181], v[170:177], v[186:193], v[84:87], v152, v152 op_sel_hi:[0,0,0]
	v_mfma_scale_f32_16x16x128_f8f6f4 v[182:185], v[162:169], v[194:201], v[76:79], v152, v152 op_sel_hi:[0,0,0]
	v_mfma_scale_f32_16x16x128_f8f6f4 v[186:189], v[154:161], v[194:201], v[96:99], v152, v152 op_sel_hi:[0,0,0]
	s_setprio 0
	s_setprio 1
	v_mfma_scale_f32_16x16x128_f8f6f4 v[190:193], v[170:177], v[194:201], v[72:75], v152, v152 op_sel_hi:[0,0,0]
	v_mfma_scale_f32_16x16x128_f8f6f4 v[194:197], v[134:141], v[202:209], v[88:91], v152, v152 op_sel_hi:[0,0,0]
	v_mfma_scale_f32_16x16x128_f8f6f4 v[198:201], v[162:169], v[202:209], v[68:71], v152, v152 op_sel_hi:[0,0,0]
	v_mfma_scale_f32_16x16x128_f8f6f4 v[210:213], v[154:161], v[202:209], v[80:83], v152, v152 op_sel_hi:[0,0,0]
	s_barrier
	s_setprio 0
	v_mov_b32_e32 v128, v146
	s_add_i32 s16, s94, s86
	s_nop 1
	ds_read_b128 v[68:71], v151 offset:16384
	ds_read_b128 v[72:75], v151 offset:16400
	ds_read_b128 v[76:79], v151 offset:18432
	ds_read_b128 v[80:83], v151 offset:18448
	ds_read_b128 v[84:87], v151 offset:20480
	ds_read_b128 v[88:91], v151 offset:20496
	ds_read_b128 v[92:95], v151 offset:22528
	ds_read_b128 v[96:99], v151 offset:22544
	s_mov_b32 m0, s16
	s_nop 0
	global_load_lds_dwordx4 v128, s[66:67]
	v_mov_b32_e32 v128, v147
	s_add_i32 m0, s16, 0x2000
	s_add_u32 s60, s66, 0x20000
	global_load_lds_dwordx4 v128, s[66:67]
	s_addc_u32 s61, s67, 0
	v_mov_b32_e32 v128, v146
	s_add_i32 s16, s95, s86
	s_mov_b32 m0, s16
	s_nop 0
	global_load_lds_dwordx4 v128, s[60:61]
	v_mov_b32_e32 v128, v147
	s_add_i32 m0, s16, 0x2000
	s_nop 0
	global_load_lds_dwordx4 v128, s[60:61]
	v_mov_b32_e32 v128, v146
	s_mov_b32 m0, s87
	s_nop 0
	global_load_lds_dwordx4 v128, s[64:65]
	v_mov_b32_e32 v128, v147
	s_mov_b32 m0, s88
	s_nop 0
	global_load_lds_dwordx4 v128, s[64:65]
	s_waitcnt vmcnt(8)
	s_waitcnt lgkmcnt(0)
	s_setprio 1
	s_barrier
	v_mfma_scale_f32_16x16x128_f8f6f4 v[64:67], v[134:141], v[68:75], v[64:67], v152, v152 op_sel_hi:[0,0,0]
	v_mfma_scale_f32_16x16x128_f8f6f4 v[44:47], v[162:169], v[68:75], v[44:47], v152, v152 op_sel_hi:[0,0,0]
	v_mfma_scale_f32_16x16x128_f8f6f4 v[56:59], v[154:161], v[68:75], v[56:59], v152, v152 op_sel_hi:[0,0,0]
	v_mfma_scale_f32_16x16x128_f8f6f4 v[52:55], v[134:141], v[76:83], v[52:55], v152, v152 op_sel_hi:[0,0,0]
	s_setprio 0
	s_setprio 1
	v_mfma_scale_f32_16x16x128_f8f6f4 v[48:51], v[154:161], v[76:83], v[48:51], v152, v152 op_sel_hi:[0,0,0]
	v_mfma_scale_f32_16x16x128_f8f6f4 v[40:43], v[134:141], v[84:91], v[40:43], v152, v152 op_sel_hi:[0,0,0]
	v_mfma_scale_f32_16x16x128_f8f6f4 v[202:205], v[170:177], v[68:75], v[36:39], v152, v152 op_sel_hi:[0,0,0]
	v_mfma_scale_f32_16x16x128_f8f6f4 v[206:209], v[162:169], v[76:83], v[28:31], v152, v152 op_sel_hi:[0,0,0]
	s_setprio 0
	s_setprio 1
	v_mfma_scale_f32_16x16x128_f8f6f4 v[214:217], v[170:177], v[76:83], v[20:23], v152, v152 op_sel_hi:[0,0,0]
	v_mfma_scale_f32_16x16x128_f8f6f4 v[218:221], v[162:169], v[84:91], v[12:15], v152, v152 op_sel_hi:[0,0,0]
	v_mfma_scale_f32_16x16x128_f8f6f4 v[222:225], v[154:161], v[84:91], v[32:35], v152, v152 op_sel_hi:[0,0,0]
	v_mfma_scale_f32_16x16x128_f8f6f4 v[226:229], v[170:177], v[84:91], v[8:11], v152, v152 op_sel_hi:[0,0,0]
	s_setprio 0
	s_setprio 1
	v_mfma_scale_f32_16x16x128_f8f6f4 v[230:233], v[134:141], v[92:99], v[24:27], v152, v152 op_sel_hi:[0,0,0]
	v_mfma_scale_f32_16x16x128_f8f6f4 v[234:237], v[162:169], v[92:99], v[4:7], v152, v152 op_sel_hi:[0,0,0]
	v_mfma_scale_f32_16x16x128_f8f6f4 v[238:241], v[154:161], v[92:99], v[16:19], v152, v152 op_sel_hi:[0,0,0]
	v_mfma_scale_f32_16x16x128_f8f6f4 v[242:245], v[170:177], v[92:99], v[0:3], v152, v152 op_sel_hi:[0,0,0]
	s_barrier
; #define PG8_LDA(dst, b, h) do { if constexpr (FP8) { _Pragma("unroll") for (int m = 0; m < 4; ++m) dst##8[m] = PG8_LD8(PG8_SA(b, h), aoff, aoff1, m); } \
;         else { _Pragma("unroll") for (int m = 0; m < 4; ++m) _Pragma("unroll") for (int k = 0; k < 2; ++k) dst[m][k] = *(const LAS bf16x8*)(lds + PG8_SA(b, h) + (k ? aoff1 : aoff) + m * 2048); } } while (0)
; #define PG8_LDB(dst, b, h) do { if constexpr (FP8) { dst##8[0] = PG8_LD8(PG8_SB(b, h), boff, boff1, 0); dst##8[1] = PG8_LD8(PG8_SB(b, h), boff, boff1, 1); } \
;         else { _Pragma("unroll") for (int n = 0; n < 2; ++n) _Pragma("unroll") for (int k = 0; k < 2; ++k) dst[n][k] = *(const LAS bf16x8*)(lds + PG8_SB(b, h) + (k ? boff1 : boff) + n * 2048); } } while (0)
; #define PG8_WAIT_V(n) asm volatile("s_waitcnt vmcnt(" #n ")" ::: "memory")
; #define PG8_WAIT_L(n) asm volatile("s_waitcnt lgkmcnt(" #n ")" ::: "memory")
; #define PG8_BAR __builtin_amdgcn_s_barrier()
; #define PG8_SCHED __builtin_amdgcn_sched_barrier(0)
; #define PG8_S3 PG8_STAGE(PG8_SA(0, 1), a2 + hstepA, voffA)
; #define PG8_S4 do { PG8_STAGE(PG8_SB(1, 0), b3, voffB); PG8_STAGE(PG8_SB(1, 1), b3 + hstepB, voffB); PG8_STAGE(PG8_SA(1, 0), a3, voffA); } while (0)
; template <class Epi, class SchedT, bool ALIGN_EPI, bool SP2, bool FP8 = false>
; __device__ __forceinline__ void gemm_phase(LAS unsigned char* lds, const Gemm g, const SchedT& S, const Epi& E, const int wid) {
;     ...
;             PG8_LDB(B0, 1, 0); PG8_LDB(B1, 1, 1); PG8_SCHED; PG8_LDA(At, 1, 0); PG8_S3;
;             PG8_WAIT_V(8); PG8_WAIT_L(0); PG8_BAR; PG8_MMAP(0, 1, 0); PG8_BAR; PG8_SCHED;
;             PG8_LDA(At, 1, 1); PG8_S4;
;             PG8_WAIT_V(8); PG8_WAIT_L(0); PG8_BAR; PG8_MMAP(1, 1, 1); PG8_BAR; PG8_SCHED;
	s_setprio 0
	s_add_i32 s16, 0, 0x18000
	v_add_u32_e32 v8, s16, v148
	s_add_i32 s17, 0, 0x1c000
	s_nop 1
	ds_read_b128 v[0:3], v8
	ds_read_b128 v[4:7], v8 offset:16
	ds_read_b128 v[134:137], v8 offset:2048
	ds_read_b128 v[138:141], v8 offset:2064
	v_add_u32_e32 v8, s17, v148
	ds_read_b128 v[154:157], v8
	ds_read_b128 v[158:161], v8 offset:16
	ds_read_b128 v[162:165], v8 offset:2048
	ds_read_b128 v[166:169], v8 offset:2064
	s_add_u32 s60, s64, 0x20000
	v_mov_b32_e32 v68, v146
	s_mov_b32 m0, s89
	ds_read_b128 v[8:11], v151 offset:32768
	ds_read_b128 v[12:15], v151 offset:32784
	ds_read_b128 v[16:19], v151 offset:34816
	ds_read_b128 v[20:23], v151 offset:34832
	ds_read_b128 v[24:27], v151 offset:36864
	ds_read_b128 v[28:31], v151 offset:36880
	ds_read_b128 v[32:35], v151 offset:38912
	ds_read_b128 v[36:39], v151 offset:38928
	s_addc_u32 s61, s65, 0
	s_nop 0
	global_load_lds_dwordx4 v68, s[60:61]
	v_mov_b32_e32 v68, v147
	s_mov_b32 m0, s90
	s_nop 0
	global_load_lds_dwordx4 v68, s[60:61]
	s_waitcnt vmcnt(8)
	s_waitcnt lgkmcnt(0)
	s_setprio 1
	s_barrier
	v_mfma_scale_f32_16x16x128_f8f6f4 v[124:127], v[0:7], v[8:15], v[124:127], v152, v152 op_sel_hi:[0,0,0]
	v_mfma_scale_f32_16x16x128_f8f6f4 v[108:111], v[154:161], v[8:15], v[108:111], v152, v152 op_sel_hi:[0,0,0]
	v_mfma_scale_f32_16x16x128_f8f6f4 v[120:123], v[134:141], v[8:15], v[120:123], v152, v152 op_sel_hi:[0,0,0]
	v_mfma_scale_f32_16x16x128_f8f6f4 v[100:103], v[162:169], v[8:15], v[100:103], v152, v152 op_sel_hi:[0,0,0]
	s_setprio 0
	s_setprio 1
	v_mfma_scale_f32_16x16x128_f8f6f4 v[116:119], v[0:7], v[16:23], v[116:119], v152, v152 op_sel_hi:[0,0,0]
	v_mfma_scale_f32_16x16x128_f8f6f4 v[92:95], v[154:161], v[16:23], v[142:145], v152, v152 op_sel_hi:[0,0,0]
	v_mfma_scale_f32_16x16x128_f8f6f4 v[112:115], v[134:141], v[16:23], v[112:115], v152, v152 op_sel_hi:[0,0,0]
	v_mfma_scale_f32_16x16x128_f8f6f4 v[84:87], v[162:169], v[16:23], v[178:181], v152, v152 op_sel_hi:[0,0,0]
	s_setprio 0
	s_setprio 1
	v_mfma_scale_f32_16x16x128_f8f6f4 v[104:107], v[0:7], v[24:31], v[104:107], v152, v152 op_sel_hi:[0,0,0]
	v_mfma_scale_f32_16x16x128_f8f6f4 v[76:79], v[154:161], v[24:31], v[182:185], v152, v152 op_sel_hi:[0,0,0]
	v_mfma_scale_f32_16x16x128_f8f6f4 v[96:99], v[134:141], v[24:31], v[186:189], v152, v152 op_sel_hi:[0,0,0]
	v_mfma_scale_f32_16x16x128_f8f6f4 v[72:75], v[162:169], v[24:31], v[190:193], v152, v152 op_sel_hi:[0,0,0]
	s_setprio 0
	s_setprio 1
	v_mfma_scale_f32_16x16x128_f8f6f4 v[88:91], v[0:7], v[32:39], v[194:197], v152, v152 op_sel_hi:[0,0,0]
	v_mfma_scale_f32_16x16x128_f8f6f4 v[68:71], v[154:161], v[32:39], v[198:201], v152, v152 op_sel_hi:[0,0,0]
	v_mfma_scale_f32_16x16x128_f8f6f4 v[80:83], v[134:141], v[32:39], v[210:213], v152, v152 op_sel_hi:[0,0,0]
	v_mfma_scale_f32_16x16x128_f8f6f4 v[60:63], v[162:169], v[32:39], v[60:63], v152, v152 op_sel_hi:[0,0,0]
	s_barrier
	s_setprio 0
	v_mov_b32_e32 v128, v146
	ds_read_b128 v[8:11], v151 offset:49152
	ds_read_b128 v[12:15], v151 offset:49168
	ds_read_b128 v[16:19], v151 offset:51200
	ds_read_b128 v[20:23], v151 offset:51216
	ds_read_b128 v[170:173], v151 offset:53248
	ds_read_b128 v[174:177], v151 offset:53264
	ds_read_b128 v[178:181], v151 offset:55296
	ds_read_b128 v[182:185], v151 offset:55312
	s_add_i32 s16, s16, s86
	v_lshl_add_u64 v[24:25], s[66:67], 0, v[128:129]
	v_lshl_add_u64 v[24:25], v[24:25], 0, s[26:27]
	s_mov_b32 m0, s16
	v_mov_b32_e32 v128, v147
	global_load_lds_dwordx4 v[24:25], off
	s_add_i32 m0, s16, 0x2000
	v_lshl_add_u64 v[24:25], s[66:67], 0, v[128:129]
	v_lshl_add_u64 v[24:25], v[24:25], 0, s[26:27]
	s_add_u32 s60, s66, 0x20080
	global_load_lds_dwordx4 v[24:25], off
	s_addc_u32 s61, s67, 0
	v_mov_b32_e32 v24, v146
	s_add_i32 s16, s17, s86
	s_mov_b32 m0, s16
	v_mov_b32_e32 v128, v146
	global_load_lds_dwordx4 v24, s[60:61]
	v_mov_b32_e32 v24, v147
	s_add_i32 m0, s16, 0x2000
	s_nop 0
	global_load_lds_dwordx4 v24, s[60:61]
	s_mov_b32 m0, s92
	v_lshl_add_u64 v[24:25], s[64:65], 0, v[128:129]
	v_lshl_add_u64 v[24:25], v[24:25], 0, s[26:27]
	v_mov_b32_e32 v128, v147
	global_load_lds_dwordx4 v[24:25], off
	s_mov_b32 m0, s93
	v_lshl_add_u64 v[24:25], s[64:65], 0, v[128:129]
	v_lshl_add_u64 v[24:25], v[24:25], 0, s[26:27]
	global_load_lds_dwordx4 v[24:25], off
	s_waitcnt vmcnt(8)
	s_waitcnt lgkmcnt(0)
	s_setprio 1
	s_barrier
	v_mfma_scale_f32_16x16x128_f8f6f4 v[64:67], v[0:7], v[8:15], v[64:67], v152, v152 op_sel_hi:[0,0,0]
	v_mfma_scale_f32_16x16x128_f8f6f4 v[44:47], v[154:161], v[8:15], v[44:47], v152, v152 op_sel_hi:[0,0,0]
	v_mfma_scale_f32_16x16x128_f8f6f4 v[56:59], v[134:141], v[8:15], v[56:59], v152, v152 op_sel_hi:[0,0,0]
	v_mfma_scale_f32_16x16x128_f8f6f4 v[36:39], v[162:169], v[8:15], v[202:205], v152, v152 op_sel_hi:[0,0,0]
	s_setprio 0
	s_setprio 1
	v_mfma_scale_f32_16x16x128_f8f6f4 v[52:55], v[0:7], v[16:23], v[52:55], v152, v152 op_sel_hi:[0,0,0]
	v_mfma_scale_f32_16x16x128_f8f6f4 v[28:31], v[154:161], v[16:23], v[206:209], v152, v152 op_sel_hi:[0,0,0]
	v_mfma_scale_f32_16x16x128_f8f6f4 v[48:51], v[134:141], v[16:23], v[48:51], v152, v152 op_sel_hi:[0,0,0]
	v_mfma_scale_f32_16x16x128_f8f6f4 v[20:23], v[162:169], v[16:23], v[214:217], v152, v152 op_sel_hi:[0,0,0]
	s_setprio 0
	s_setprio 1
	v_mfma_scale_f32_16x16x128_f8f6f4 v[40:43], v[0:7], v[170:177], v[40:43], v152, v152 op_sel_hi:[0,0,0]
	v_mfma_scale_f32_16x16x128_f8f6f4 v[12:15], v[154:161], v[170:177], v[218:221], v152, v152 op_sel_hi:[0,0,0]
	v_mfma_scale_f32_16x16x128_f8f6f4 v[32:35], v[134:141], v[170:177], v[222:225], v152, v152 op_sel_hi:[0,0,0]
	v_mfma_scale_f32_16x16x128_f8f6f4 v[8:11], v[162:169], v[170:177], v[226:229], v152, v152 op_sel_hi:[0,0,0]
	s_setprio 0
	s_setprio 1
	v_mfma_scale_f32_16x16x128_f8f6f4 v[24:27], v[0:7], v[178:185], v[230:233], v152, v152 op_sel_hi:[0,0,0]
	v_mfma_scale_f32_16x16x128_f8f6f4 v[4:7], v[154:161], v[178:185], v[234:237], v152, v152 op_sel_hi:[0,0,0]
	v_mfma_scale_f32_16x16x128_f8f6f4 v[16:19], v[134:141], v[178:185], v[238:241], v152, v152 op_sel_hi:[0,0,0]
	v_mfma_scale_f32_16x16x128_f8f6f4 v[0:3], v[162:169], v[178:185], v[242:245], v152, v152 op_sel_hi:[0,0,0]
	s_barrier
	s_setprio 0
	s_add_u32 s52, s52, 0x100
	s_addc_u32 s53, s53, 0
	s_add_u32 s30, s30, 0x100
	s_addc_u32 s31, s31, 0
	s_cmp_ge_i32 s45, s20
	s_mov_b32 s47, s45
	s_cbranch_scc0 .LBB0_779

; #define PG8_LDA(dst, b, h) do { if constexpr (FP8) { _Pragma("unroll") for (int m = 0; m < 4; ++m) dst##8[m] = PG8_LD8(PG8_SA(b, h), aoff, aoff1, m); } \
;         else { _Pragma("unroll") for (int m = 0; m < 4; ++m) _Pragma("unroll") for (int k = 0; k < 2; ++k) dst[m][k] = *(const LAS bf16x8*)(lds + PG8_SA(b, h) + (k ? aoff1 : aoff) + m * 2048); } } while (0)
; #define PG8_LDB(dst, b, h) do { if constexpr (FP8) { dst##8[0] = PG8_LD8(PG8_SB(b, h), boff, boff1, 0); dst##8[1] = PG8_LD8(PG8_SB(b, h), boff, boff1, 1); } \
;         else { _Pragma("unroll") for (int n = 0; n < 2; ++n) _Pragma("unroll") for (int k = 0; k < 2; ++k) dst[n][k] = *(const LAS bf16x8*)(lds + PG8_SB(b, h) + (k ? boff1 : boff) + n * 2048); } } while (0)
; #define PG8_WAIT_V(n) asm volatile("s_waitcnt vmcnt(" #n ")" ::: "memory")
; #define PG8_WAIT_L(n) asm volatile("s_waitcnt lgkmcnt(" #n ")" ::: "memory")
; #define PG8_BAR __builtin_amdgcn_s_barrier()
; #define PG8_SCHED __builtin_amdgcn_sched_barrier(0)
; #define PG8_S1 PG8_STAGE(PG8_SA(1, 1), a1 + hstepA, voffA)
; template <class Epi, class SchedT, bool ALIGN_EPI, bool SP2, bool FP8 = false>
; __device__ __forceinline__ void gemm_phase(LAS unsigned char* lds, const Gemm g, const SchedT& S, const Epi& E, const int wid) {
;     ...
;     for (;;) {
;         const bool has_next = S.next(ui + 1, nxt);
;         const char* nA = has_next ? (const char*)g.A + (size_t)nxt.pm * tstepA + (size_t)nxt.aoff * 2 : cA; const char* nB = has_next ? (const char*)g.Bt + (size_t)nxt.pn * tstepB + (size_t)nxt.boff * 2 : cB;
;         const int nt = cur.nt;
;         for (int t = 0; t < nt; t += 2) {
;             const bool last = (t == nt - 2);
;             const char* a1 = cA + (size_t)(t + 1) * kstep;
;             const char* a2 = last ? nA : cA + (size_t)(t + 2) * kstep; const char* b2 = last ? nB : cB + (size_t)(t + 2) * kstep;
;             const char* a3 = a2 + kstep; const char* b3 = b2 + kstep;
;             if constexpr (SP2) {
;     ...
;             PG8_LDB(B0, 0, 0); PG8_LDB(B1, 0, 1); PG8_SCHED; PG8_LDA(At, 0, 0); PG8_S1;
;             PG8_WAIT_V(8); PG8_WAIT_L(0); PG8_BAR; PG8_MMAP(0, 0, 0); PG8_BAR; PG8_SCHED;
;             PG8_LDA(At, 0, 1); PG8_S2;
;             PG8_WAIT_V(8); PG8_WAIT_L(0); PG8_BAR; PG8_MMAP(1, 0, 1); PG8_BAR; PG8_SCHED;
.LBB0_897:
	s_ashr_i32 s27, s26, 31
	s_lshl_b64 s[24:25], s[26:27], 19
	s_add_u32 s40, s2, s24
	s_addc_u32 s41, s3, s25
	s_ashr_i32 s15, s14, 31
	s_lshl_b64 s[24:25], s[14:15], 19
	s_add_u32 s42, s18, s24
	s_addc_u32 s43, s19, s25
	s_cmp_lt_i32 s20, 1
	s_cbranch_scc1 .LBB0_893
	v_cmp_lt_i64_e32 vcc, s[52:53], v[146:147]
	s_and_b64 s[24:25], vcc, exec
	s_cselect_b32 s15, s41, s49
	s_cselect_b32 s21, s40, s48
	s_cselect_b32 s24, s43, s51
	s_cselect_b32 s25, s42, s50
	s_add_i32 s27, s20, -2
	s_add_u32 s48, s48, 0x40080
	s_addc_u32 s49, s49, 0
	s_add_u32 s30, s50, 0x100
	s_addc_u32 s31, s51, 0
	s_mov_b32 s34, 0
	ds_read_b128 v[128:131], v173
	ds_read_b128 v[132:135], v173 offset:1024
	ds_read_b128 v[136:139], v174
	ds_read_b128 v[140:143], v174 offset:1024
	ds_read_b128 v[150:153], v175
	ds_read_b128 v[154:157], v175 offset:1024
	ds_read_b128 v[158:161], v176
	ds_read_b128 v[162:165], v176 offset:1024
	s_add_i32 s35, s34, 2
	s_add_u32 s16, s48, 0xfffc0080
	s_addc_u32 s17, s49, -1
	s_cmp_eq_u32 s27, s34
	s_cselect_b32 s51, s15, s17
	s_cselect_b32 s50, s21, s16
	s_cselect_b32 s53, s24, s31
	s_cselect_b32 s52, s25, s30
	v_mov_b32_e32 v144, v168
	ds_read_b128 v[182:185], v177
	ds_read_b128 v[186:189], v177 offset:1024
	ds_read_b128 v[190:193], v177 offset:2048
	ds_read_b128 v[194:197], v177 offset:3072
	ds_read_b128 v[198:201], v177 offset:4096
	ds_read_b128 v[202:205], v177 offset:5120
	ds_read_b128 v[206:209], v177 offset:6144
	ds_read_b128 v[210:213], v177 offset:7168
	s_add_i32 m0, s87, 0xc000
	s_nop 0
	global_load_lds_dwordx4 v144, s[48:49]
	v_mov_b32_e32 v144, v170
	s_add_i32 m0, s87, 0xe000
	s_nop 0
	global_load_lds_dwordx4 v144, s[48:49]
	s_waitcnt vmcnt(8)
	s_waitcnt lgkmcnt(0)
	s_setprio 1
	s_barrier
	v_mfma_f32_16x16x32_bf16 v[124:127], v[128:131], v[182:185], 0
	v_mfma_f32_16x16x32_bf16 v[120:123], v[136:139], v[182:185], 0
	v_mfma_f32_16x16x32_bf16 v[104:107], v[136:139], v[190:193], 0
	v_mfma_f32_16x16x32_bf16 v[108:111], v[128:131], v[190:193], 0
	s_setprio 0
	s_setprio 1
	v_mfma_f32_16x16x32_bf16 v[92:95], v[128:131], v[198:201], 0
	v_mfma_f32_16x16x32_bf16 v[88:91], v[136:139], v[198:201], 0
	v_mfma_f32_16x16x32_bf16 v[72:75], v[136:139], v[206:209], 0
	v_mfma_f32_16x16x32_bf16 v[76:79], v[128:131], v[206:209], 0
	s_setprio 0
	s_setprio 1
	v_mfma_f32_16x16x32_bf16 v[124:127], v[132:135], v[186:189], v[124:127]
	v_mfma_f32_16x16x32_bf16 v[120:123], v[140:143], v[186:189], v[120:123]
	v_mfma_f32_16x16x32_bf16 v[104:107], v[140:143], v[194:197], v[104:107]
	v_mfma_f32_16x16x32_bf16 v[108:111], v[132:135], v[194:197], v[108:111]
	s_setprio 0
	s_setprio 1
	v_mfma_f32_16x16x32_bf16 v[92:95], v[132:135], v[202:205], v[92:95]
	v_mfma_f32_16x16x32_bf16 v[88:91], v[140:143], v[202:205], v[88:91]
	v_mfma_f32_16x16x32_bf16 v[72:75], v[140:143], v[210:213], v[72:75]
	v_mfma_f32_16x16x32_bf16 v[76:79], v[132:135], v[210:213], v[76:79]
	s_setprio 0
	s_setprio 1
	v_mfma_f32_16x16x32_bf16 v[116:119], v[150:153], v[182:185], 0
	v_mfma_f32_16x16x32_bf16 v[112:115], v[158:161], v[182:185], 0
	v_mfma_f32_16x16x32_bf16 v[96:99], v[158:161], v[190:193], 0
	v_mfma_f32_16x16x32_bf16 v[100:103], v[150:153], v[190:193], 0
	s_setprio 0
	s_setprio 1
	v_mfma_f32_16x16x32_bf16 v[84:87], v[150:153], v[198:201], 0
	v_mfma_f32_16x16x32_bf16 v[80:83], v[158:161], v[198:201], 0
	v_mfma_f32_16x16x32_bf16 v[64:67], v[158:161], v[206:209], 0
	v_mfma_f32_16x16x32_bf16 v[68:71], v[150:153], v[206:209], 0
	s_setprio 0
	s_setprio 1
	v_mfma_f32_16x16x32_bf16 v[116:119], v[154:157], v[186:189], v[116:119]
	v_mfma_f32_16x16x32_bf16 v[112:115], v[162:165], v[186:189], v[112:115]
	v_mfma_f32_16x16x32_bf16 v[96:99], v[162:165], v[194:197], v[96:99]
	v_mfma_f32_16x16x32_bf16 v[100:103], v[154:157], v[194:197], v[100:103]
	s_setprio 0
	s_setprio 1
	v_mfma_f32_16x16x32_bf16 v[84:87], v[154:157], v[202:205], v[84:87]
	v_mfma_f32_16x16x32_bf16 v[80:83], v[162:165], v[202:205], v[80:83]
	v_mfma_f32_16x16x32_bf16 v[64:67], v[162:165], v[210:213], v[64:67]
	v_mfma_f32_16x16x32_bf16 v[68:71], v[154:157], v[210:213], v[68:71]
	s_barrier
	s_setprio 0
	v_mov_b32_e32 v144, v169
	s_add_i32 s16, s94, s86
	ds_read_b128 v[182:185], v177 offset:16384
	ds_read_b128 v[186:189], v177 offset:17408
	ds_read_b128 v[190:193], v177 offset:18432
	ds_read_b128 v[194:197], v177 offset:19456
	ds_read_b128 v[198:201], v177 offset:20480
	ds_read_b128 v[202:205], v177 offset:21504
	ds_read_b128 v[206:209], v177 offset:22528
	ds_read_b128 v[210:213], v177 offset:23552
	s_mov_b32 m0, s16
	s_nop 0
	global_load_lds_dwordx4 v144, s[52:53]
	v_mov_b32_e32 v144, v171
	s_add_i32 m0, s16, 0x2000
	s_add_u32 s60, s52, 0x40000
	global_load_lds_dwordx4 v144, s[52:53]
	s_addc_u32 s61, s53, 0
	v_mov_b32_e32 v144, v169
	s_add_i32 s16, s95, s86
	s_mov_b32 m0, s16
	s_nop 0
	global_load_lds_dwordx4 v144, s[60:61]
	v_mov_b32_e32 v144, v171
	s_add_i32 m0, s16, 0x2000
	s_nop 0
	global_load_lds_dwordx4 v144, s[60:61]
	v_mov_b32_e32 v144, v168
	s_mov_b32 m0, s87
	s_nop 0
	global_load_lds_dwordx4 v144, s[50:51]
	v_mov_b32_e32 v144, v170
	s_mov_b32 m0, s88
	s_nop 0
	global_load_lds_dwordx4 v144, s[50:51]
	s_waitcnt vmcnt(8)
	s_waitcnt lgkmcnt(0)
	s_setprio 1
	s_barrier
; #define PG8_LDA(dst, b, h) do { if constexpr (FP8) { _Pragma("unroll") for (int m = 0; m < 4; ++m) dst##8[m] = PG8_LD8(PG8_SA(b, h), aoff, aoff1, m); } \
;         else { _Pragma("unroll") for (int m = 0; m < 4; ++m) _Pragma("unroll") for (int k = 0; k < 2; ++k) dst[m][k] = *(const LAS bf16x8*)(lds + PG8_SA(b, h) + (k ? aoff1 : aoff) + m * 2048); } } while (0)
; #define PG8_LDB(dst, b, h) do { if constexpr (FP8) { dst##8[0] = PG8_LD8(PG8_SB(b, h), boff, boff1, 0); dst##8[1] = PG8_LD8(PG8_SB(b, h), boff, boff1, 1); } \
;         else { _Pragma("unroll") for (int n = 0; n < 2; ++n) _Pragma("unroll") for (int k = 0; k < 2; ++k) dst[n][k] = *(const LAS bf16x8*)(lds + PG8_SB(b, h) + (k ? boff1 : boff) + n * 2048); } } while (0)
; #define PG8_WAIT_V(n) asm volatile("s_waitcnt vmcnt(" #n ")" ::: "memory")
; #define PG8_WAIT_L(n) asm volatile("s_waitcnt lgkmcnt(" #n ")" ::: "memory")
; #define PG8_BAR __builtin_amdgcn_s_barrier()
; #define PG8_SCHED __builtin_amdgcn_sched_barrier(0)
; #define PG8_S1 PG8_STAGE(PG8_SA(1, 1), a1 + hstepA, voffA)
; #define PG8_S2 do { PG8_STAGE(PG8_SB(0, 0), b2, voffB); PG8_STAGE(PG8_SB(0, 1), b2 + hstepB, voffB); PG8_STAGE(PG8_SA(0, 0), a2, voffA); } while (0)
; #define PG8_S3 PG8_STAGE(PG8_SA(0, 1), a2 + hstepA, voffA)
; template <class Epi, class SchedT, bool ALIGN_EPI, bool SP2, bool FP8 = false>
; __device__ __forceinline__ void gemm_phase(LAS unsigned char* lds, const Gemm g, const SchedT& S, const Epi& E, const int wid) {
;     ...
;             if constexpr (SP2) {
;     ...
;             PG8_LDB(B0, 0, 0); PG8_LDB(B1, 0, 1); PG8_SCHED; PG8_LDA(At, 0, 0); PG8_S1;
;             PG8_WAIT_V(8); PG8_WAIT_L(0); PG8_BAR; PG8_MMAP(0, 0, 0); PG8_BAR; PG8_SCHED;
;             PG8_LDA(At, 0, 1); PG8_S2;
;             PG8_WAIT_V(8); PG8_WAIT_L(0); PG8_BAR; PG8_MMAP(1, 0, 1); PG8_BAR; PG8_SCHED;
;             PG8_LDB(B0, 1, 0); PG8_LDB(B1, 1, 1); PG8_SCHED; PG8_LDA(At, 1, 0); PG8_S3;
;             PG8_WAIT_V(8); PG8_WAIT_L(0); PG8_BAR; PG8_MMAP(0, 1, 0); PG8_BAR; PG8_SCHED;
	v_mfma_f32_16x16x32_bf16 v[60:63], v[128:131], v[182:185], 0
	v_mfma_f32_16x16x32_bf16 v[56:59], v[136:139], v[182:185], 0
	v_mfma_f32_16x16x32_bf16 v[40:43], v[136:139], v[190:193], 0
	v_mfma_f32_16x16x32_bf16 v[44:47], v[128:131], v[190:193], 0
	s_setprio 0
	s_setprio 1
	v_mfma_f32_16x16x32_bf16 v[28:31], v[128:131], v[198:201], 0
	v_mfma_f32_16x16x32_bf16 v[24:27], v[136:139], v[198:201], 0
	v_mfma_f32_16x16x32_bf16 v[8:11], v[136:139], v[206:209], 0
	v_mfma_f32_16x16x32_bf16 v[12:15], v[128:131], v[206:209], 0
	s_setprio 0
	s_setprio 1
	v_mfma_f32_16x16x32_bf16 v[60:63], v[132:135], v[186:189], v[60:63]
	v_mfma_f32_16x16x32_bf16 v[56:59], v[140:143], v[186:189], v[56:59]
	v_mfma_f32_16x16x32_bf16 v[40:43], v[140:143], v[194:197], v[40:43]
	v_mfma_f32_16x16x32_bf16 v[44:47], v[132:135], v[194:197], v[44:47]
	s_setprio 0
	s_setprio 1
	v_mfma_f32_16x16x32_bf16 v[28:31], v[132:135], v[202:205], v[28:31]
	v_mfma_f32_16x16x32_bf16 v[24:27], v[140:143], v[202:205], v[24:27]
	v_mfma_f32_16x16x32_bf16 v[8:11], v[140:143], v[210:213], v[8:11]
	v_mfma_f32_16x16x32_bf16 v[12:15], v[132:135], v[210:213], v[12:15]
	s_setprio 0
	s_setprio 1
	v_mfma_f32_16x16x32_bf16 v[52:55], v[150:153], v[182:185], 0
	v_mfma_f32_16x16x32_bf16 v[48:51], v[158:161], v[182:185], 0
	v_mfma_f32_16x16x32_bf16 v[32:35], v[158:161], v[190:193], 0
	v_mfma_f32_16x16x32_bf16 v[36:39], v[150:153], v[190:193], 0
	s_setprio 0
	s_setprio 1
	v_mfma_f32_16x16x32_bf16 v[20:23], v[150:153], v[198:201], 0
	v_mfma_f32_16x16x32_bf16 v[16:19], v[158:161], v[198:201], 0
	v_mfma_f32_16x16x32_bf16 v[0:3], v[158:161], v[206:209], 0
	v_mfma_f32_16x16x32_bf16 v[4:7], v[150:153], v[206:209], 0
	s_setprio 0
	s_setprio 1
	v_mfma_f32_16x16x32_bf16 v[52:55], v[154:157], v[186:189], v[52:55]
	v_mfma_f32_16x16x32_bf16 v[48:51], v[162:165], v[186:189], v[48:51]
	v_mfma_f32_16x16x32_bf16 v[32:35], v[162:165], v[194:197], v[32:35]
	v_mfma_f32_16x16x32_bf16 v[36:39], v[154:157], v[194:197], v[36:39]
	s_setprio 0
	s_setprio 1
	v_mfma_f32_16x16x32_bf16 v[20:23], v[154:157], v[202:205], v[20:23]
	v_mfma_f32_16x16x32_bf16 v[16:19], v[162:165], v[202:205], v[16:19]
	v_mfma_f32_16x16x32_bf16 v[0:3], v[162:165], v[210:213], v[0:3]
	v_mfma_f32_16x16x32_bf16 v[4:7], v[154:157], v[210:213], v[4:7]
	s_barrier
	s_setprio 0
	s_add_i32 s16, 0, 0x18000
	s_add_i32 s17, 0, 0x1c000
	v_add_u32_e32 v132, s16, v172
	v_add_u32_e32 v144, s17, v172
	ds_read_b128 v[128:131], v132
	ds_read_b128 v[132:135], v132 offset:1024
	ds_read_b128 v[136:139], v178
	ds_read_b128 v[140:143], v178 offset:1024
	ds_read_b128 v[150:153], v144
	ds_read_b128 v[154:157], v144 offset:1024
	ds_read_b128 v[158:161], v179
	ds_read_b128 v[162:165], v179 offset:1024
	s_add_u32 s60, s50, 0x40000
	v_mov_b32_e32 v144, v168
	s_mov_b32 m0, s89
	ds_read_b128 v[182:185], v177 offset:32768
	ds_read_b128 v[186:189], v177 offset:33792
	ds_read_b128 v[190:193], v177 offset:34816
	ds_read_b128 v[194:197], v177 offset:35840
	ds_read_b128 v[198:201], v177 offset:36864
	ds_read_b128 v[202:205], v177 offset:37888
	ds_read_b128 v[206:209], v177 offset:38912
	ds_read_b128 v[210:213], v177 offset:39936
	s_addc_u32 s61, s51, 0
	s_nop 0
	global_load_lds_dwordx4 v144, s[60:61]
	v_mov_b32_e32 v144, v170
	s_mov_b32 m0, s90
	s_nop 0
	global_load_lds_dwordx4 v144, s[60:61]
	s_waitcnt vmcnt(8)
	s_waitcnt lgkmcnt(0)
	s_setprio 1
	s_barrier
	v_mfma_f32_16x16x32_bf16 v[124:127], v[128:131], v[182:185], v[124:127]
	v_mfma_f32_16x16x32_bf16 v[120:123], v[136:139], v[182:185], v[120:123]
	v_mfma_f32_16x16x32_bf16 v[104:107], v[136:139], v[190:193], v[104:107]
	v_mfma_f32_16x16x32_bf16 v[108:111], v[128:131], v[190:193], v[108:111]
	s_setprio 0
	s_setprio 1
	v_mfma_f32_16x16x32_bf16 v[92:95], v[128:131], v[198:201], v[92:95]
	v_mfma_f32_16x16x32_bf16 v[88:91], v[136:139], v[198:201], v[88:91]
	v_mfma_f32_16x16x32_bf16 v[72:75], v[136:139], v[206:209], v[72:75]
	v_mfma_f32_16x16x32_bf16 v[76:79], v[128:131], v[206:209], v[76:79]
	s_setprio 0
	s_setprio 1
	v_mfma_f32_16x16x32_bf16 v[124:127], v[132:135], v[186:189], v[124:127]
	v_mfma_f32_16x16x32_bf16 v[120:123], v[140:143], v[186:189], v[120:123]
	v_mfma_f32_16x16x32_bf16 v[104:107], v[140:143], v[194:197], v[104:107]
	v_mfma_f32_16x16x32_bf16 v[108:111], v[132:135], v[194:197], v[108:111]
	s_setprio 0
	s_setprio 1
	v_mfma_f32_16x16x32_bf16 v[92:95], v[132:135], v[202:205], v[92:95]
	v_mfma_f32_16x16x32_bf16 v[88:91], v[140:143], v[202:205], v[88:91]
	v_mfma_f32_16x16x32_bf16 v[72:75], v[140:143], v[210:213], v[72:75]
	v_mfma_f32_16x16x32_bf16 v[76:79], v[132:135], v[210:213], v[76:79]
	s_setprio 0
	s_setprio 1
	v_mfma_f32_16x16x32_bf16 v[116:119], v[150:153], v[182:185], v[116:119]
	v_mfma_f32_16x16x32_bf16 v[112:115], v[158:161], v[182:185], v[112:115]
	v_mfma_f32_16x16x32_bf16 v[96:99], v[158:161], v[190:193], v[96:99]
	v_mfma_f32_16x16x32_bf16 v[100:103], v[150:153], v[190:193], v[100:103]
	s_setprio 0
	s_setprio 1
	v_mfma_f32_16x16x32_bf16 v[84:87], v[150:153], v[198:201], v[84:87]
	v_mfma_f32_16x16x32_bf16 v[80:83], v[158:161], v[198:201], v[80:83]
	v_mfma_f32_16x16x32_bf16 v[64:67], v[158:161], v[206:209], v[64:67]
	v_mfma_f32_16x16x32_bf16 v[68:71], v[150:153], v[206:209], v[68:71]
	s_setprio 0
	s_setprio 1
	v_mfma_f32_16x16x32_bf16 v[116:119], v[154:157], v[186:189], v[116:119]
	v_mfma_f32_16x16x32_bf16 v[112:115], v[162:165], v[186:189], v[112:115]
	v_mfma_f32_16x16x32_bf16 v[96:99], v[162:165], v[194:197], v[96:99]
	v_mfma_f32_16x16x32_bf16 v[100:103], v[154:157], v[194:197], v[100:103]
	s_setprio 0
	s_setprio 1
	v_mfma_f32_16x16x32_bf16 v[84:87], v[154:157], v[202:205], v[84:87]
	v_mfma_f32_16x16x32_bf16 v[80:83], v[162:165], v[202:205], v[80:83]
	v_mfma_f32_16x16x32_bf16 v[64:67], v[162:165], v[210:213], v[64:67]
	v_mfma_f32_16x16x32_bf16 v[68:71], v[154:157], v[210:213], v[68:71]
	s_barrier
; #define PG8_LDA(dst, b, h) do { if constexpr (FP8) { _Pragma("unroll") for (int m = 0; m < 4; ++m) dst##8[m] = PG8_LD8(PG8_SA(b, h), aoff, aoff1, m); } \
;         else { _Pragma("unroll") for (int m = 0; m < 4; ++m) _Pragma("unroll") for (int k = 0; k < 2; ++k) dst[m][k] = *(const LAS bf16x8*)(lds + PG8_SA(b, h) + (k ? aoff1 : aoff) + m * 2048); } } while (0)
; #define PG8_LDB(dst, b, h) do { if constexpr (FP8) { dst##8[0] = PG8_LD8(PG8_SB(b, h), boff, boff1, 0); dst##8[1] = PG8_LD8(PG8_SB(b, h), boff, boff1, 1); } \
;         else { _Pragma("unroll") for (int n = 0; n < 2; ++n) _Pragma("unroll") for (int k = 0; k < 2; ++k) dst[n][k] = *(const LAS bf16x8*)(lds + PG8_SB(b, h) + (k ? boff1 : boff) + n * 2048); } } while (0)
; #define PG8_WAIT_V(n) asm volatile("s_waitcnt vmcnt(" #n ")" ::: "memory")
; #define PG8_WAIT_L(n) asm volatile("s_waitcnt lgkmcnt(" #n ")" ::: "memory")
; #define PG8_BAR __builtin_amdgcn_s_barrier()
; #define PG8_SCHED __builtin_amdgcn_sched_barrier(0)
; #define PG8_S1 PG8_STAGE(PG8_SA(1, 1), a1 + hstepA, voffA)
; #define PG8_S4 do { PG8_STAGE(PG8_SB(1, 0), b3, voffB); PG8_STAGE(PG8_SB(1, 1), b3 + hstepB, voffB); PG8_STAGE(PG8_SA(1, 0), a3, voffA); } while (0)
; template <class Epi, class SchedT, bool ALIGN_EPI, bool SP2, bool FP8 = false>
; __device__ __forceinline__ void gemm_phase(LAS unsigned char* lds, const Gemm g, const SchedT& S, const Epi& E, const int wid) {
;     ...
;         for (int t = 0; t < nt; t += 2) {
;             const bool last = (t == nt - 2);
;             const char* a1 = cA + (size_t)(t + 1) * kstep;
;             const char* a2 = last ? nA : cA + (size_t)(t + 2) * kstep; const char* b2 = last ? nB : cB + (size_t)(t + 2) * kstep;
;             const char* a3 = a2 + kstep; const char* b3 = b2 + kstep;
;             if constexpr (SP2) {
;     ...
;             PG8_LDB(B0, 0, 0); PG8_LDB(B1, 0, 1); PG8_SCHED; PG8_LDA(At, 0, 0); PG8_S1;
;             PG8_WAIT_V(8); PG8_WAIT_L(0); PG8_BAR; PG8_MMAP(0, 0, 0); PG8_BAR; PG8_SCHED;
;     ...
;             PG8_LDA(At, 1, 1); PG8_S4;
;             PG8_WAIT_V(8); PG8_WAIT_L(0); PG8_BAR; PG8_MMAP(1, 1, 1); PG8_BAR; PG8_SCHED;
	s_setprio 0
	v_mov_b32_e32 v144, v169
	ds_read_b128 v[182:185], v177 offset:49152
	ds_read_b128 v[186:189], v177 offset:50176
	ds_read_b128 v[190:193], v177 offset:51200
	ds_read_b128 v[194:197], v177 offset:52224
	ds_read_b128 v[198:201], v177 offset:53248
	ds_read_b128 v[202:205], v177 offset:54272
	ds_read_b128 v[206:209], v177 offset:55296
	ds_read_b128 v[210:213], v177 offset:56320
	s_add_i32 s16, s16, s86
	v_lshl_add_u64 v[166:167], s[52:53], 0, v[144:145]
	v_lshl_add_u64 v[166:167], v[166:167], 0, s[6:7]
	s_mov_b32 m0, s16
	v_mov_b32_e32 v144, v171
	global_load_lds_dwordx4 v[166:167], off
	s_add_i32 m0, s16, 0x2000
	s_nop 0
	v_lshl_add_u64 v[166:167], s[52:53], 0, v[144:145]
	s_add_u32 s52, s52, 0x40080
	v_lshl_add_u64 v[166:167], v[166:167], 0, s[6:7]
	s_addc_u32 s53, s53, 0
	v_mov_b32_e32 v144, v169
	s_add_i32 s16, s17, s86
	global_load_lds_dwordx4 v[166:167], off
	s_mov_b32 m0, s16
	s_nop 0
	global_load_lds_dwordx4 v144, s[52:53]
	v_mov_b32_e32 v144, v171
	s_add_i32 m0, s16, 0x2000
	s_nop 0
	global_load_lds_dwordx4 v144, s[52:53]
	v_mov_b32_e32 v144, v168
	s_mov_b32 m0, s92
	v_lshl_add_u64 v[166:167], s[50:51], 0, v[144:145]
	v_lshl_add_u64 v[166:167], v[166:167], 0, s[6:7]
	v_mov_b32_e32 v144, v170
	global_load_lds_dwordx4 v[166:167], off
	s_mov_b32 m0, s93
	v_lshl_add_u64 v[166:167], s[50:51], 0, v[144:145]
	v_lshl_add_u64 v[166:167], v[166:167], 0, s[6:7]
	global_load_lds_dwordx4 v[166:167], off
	s_waitcnt vmcnt(8)
	s_waitcnt lgkmcnt(0)
	s_setprio 1
	s_barrier
	v_mfma_f32_16x16x32_bf16 v[60:63], v[128:131], v[182:185], v[60:63]
	v_mfma_f32_16x16x32_bf16 v[56:59], v[136:139], v[182:185], v[56:59]
	v_mfma_f32_16x16x32_bf16 v[40:43], v[136:139], v[190:193], v[40:43]
	v_mfma_f32_16x16x32_bf16 v[44:47], v[128:131], v[190:193], v[44:47]
	s_setprio 0
	s_setprio 1
	v_mfma_f32_16x16x32_bf16 v[28:31], v[128:131], v[198:201], v[28:31]
	v_mfma_f32_16x16x32_bf16 v[24:27], v[136:139], v[198:201], v[24:27]
	v_mfma_f32_16x16x32_bf16 v[8:11], v[136:139], v[206:209], v[8:11]
	v_mfma_f32_16x16x32_bf16 v[12:15], v[128:131], v[206:209], v[12:15]
	s_setprio 0
	s_setprio 1
	v_mfma_f32_16x16x32_bf16 v[60:63], v[132:135], v[186:189], v[60:63]
	v_mfma_f32_16x16x32_bf16 v[56:59], v[140:143], v[186:189], v[56:59]
	v_mfma_f32_16x16x32_bf16 v[40:43], v[140:143], v[194:197], v[40:43]
	v_mfma_f32_16x16x32_bf16 v[44:47], v[132:135], v[194:197], v[44:47]
	s_setprio 0
	s_setprio 1
	v_mfma_f32_16x16x32_bf16 v[28:31], v[132:135], v[202:205], v[28:31]
	v_mfma_f32_16x16x32_bf16 v[24:27], v[140:143], v[202:205], v[24:27]
	v_mfma_f32_16x16x32_bf16 v[8:11], v[140:143], v[210:213], v[8:11]
	v_mfma_f32_16x16x32_bf16 v[12:15], v[132:135], v[210:213], v[12:15]
	s_setprio 0
	s_setprio 1
	v_mfma_f32_16x16x32_bf16 v[52:55], v[150:153], v[182:185], v[52:55]
	v_mfma_f32_16x16x32_bf16 v[48:51], v[158:161], v[182:185], v[48:51]
	v_mfma_f32_16x16x32_bf16 v[32:35], v[158:161], v[190:193], v[32:35]
	v_mfma_f32_16x16x32_bf16 v[36:39], v[150:153], v[190:193], v[36:39]
	s_setprio 0
	s_setprio 1
	v_mfma_f32_16x16x32_bf16 v[20:23], v[150:153], v[198:201], v[20:23]
	v_mfma_f32_16x16x32_bf16 v[16:19], v[158:161], v[198:201], v[16:19]
	v_mfma_f32_16x16x32_bf16 v[0:3], v[158:161], v[206:209], v[0:3]
	v_mfma_f32_16x16x32_bf16 v[4:7], v[150:153], v[206:209], v[4:7]
	s_setprio 0
	s_setprio 1
	v_mfma_f32_16x16x32_bf16 v[52:55], v[154:157], v[186:189], v[52:55]
	v_mfma_f32_16x16x32_bf16 v[48:51], v[162:165], v[186:189], v[48:51]
	v_mfma_f32_16x16x32_bf16 v[32:35], v[162:165], v[194:197], v[32:35]
	v_mfma_f32_16x16x32_bf16 v[36:39], v[154:157], v[194:197], v[36:39]
	s_setprio 0
	s_setprio 1
	v_mfma_f32_16x16x32_bf16 v[20:23], v[154:157], v[202:205], v[20:23]
	v_mfma_f32_16x16x32_bf16 v[16:19], v[162:165], v[202:205], v[16:19]
	v_mfma_f32_16x16x32_bf16 v[0:3], v[162:165], v[210:213], v[0:3]
	v_mfma_f32_16x16x32_bf16 v[4:7], v[154:157], v[210:213], v[4:7]
	s_barrier
	s_setprio 0
	s_add_u32 s48, s48, 0x100
	s_addc_u32 s49, s49, 0
	s_add_u32 s30, s30, 0x100
	s_addc_u32 s31, s31, 0
	s_cmp_ge_i32 s35, s20
	s_mov_b32 s34, s35
	s_cbranch_scc1 .Lpeel_exit_lbb0_899
.LBB0_899:
	ds_read_b128 v[128:131], v173
	ds_read_b128 v[132:135], v173 offset:1024
	ds_read_b128 v[136:139], v174
	ds_read_b128 v[140:143], v174 offset:1024
	ds_read_b128 v[150:153], v175
	ds_read_b128 v[154:157], v175 offset:1024
	ds_read_b128 v[158:161], v176
	ds_read_b128 v[162:165], v176 offset:1024
	s_add_i32 s35, s34, 2
	s_add_u32 s16, s48, 0xfffc0080
	s_addc_u32 s17, s49, -1
	s_cmp_eq_u32 s27, s34
	s_cselect_b32 s51, s15, s17
	s_cselect_b32 s50, s21, s16
	s_cselect_b32 s53, s24, s31
	s_cselect_b32 s52, s25, s30
	v_mov_b32_e32 v144, v168
	ds_read_b128 v[182:185], v177
	ds_read_b128 v[186:189], v177 offset:1024
	ds_read_b128 v[190:193], v177 offset:2048
	ds_read_b128 v[194:197], v177 offset:3072
	ds_read_b128 v[198:201], v177 offset:4096
	ds_read_b128 v[202:205], v177 offset:5120
	ds_read_b128 v[206:209], v177 offset:6144
	ds_read_b128 v[210:213], v177 offset:7168
	s_add_i32 m0, s87, 0xc000
	s_nop 0
	global_load_lds_dwordx4 v144, s[48:49]
	v_mov_b32_e32 v144, v170
	s_add_i32 m0, s87, 0xe000
	s_nop 0
	global_load_lds_dwordx4 v144, s[48:49]
	s_waitcnt vmcnt(8)
	s_waitcnt lgkmcnt(0)
	s_setprio 1
	s_barrier
; #define PG8_LDA(dst, b, h) do { if constexpr (FP8) { _Pragma("unroll") for (int m = 0; m < 4; ++m) dst##8[m] = PG8_LD8(PG8_SA(b, h), aoff, aoff1, m); } \
;         else { _Pragma("unroll") for (int m = 0; m < 4; ++m) _Pragma("unroll") for (int k = 0; k < 2; ++k) dst[m][k] = *(const LAS bf16x8*)(lds + PG8_SA(b, h) + (k ? aoff1 : aoff) + m * 2048); } } while (0)
; #define PG8_LDB(dst, b, h) do { if constexpr (FP8) { dst##8[0] = PG8_LD8(PG8_SB(b, h), boff, boff1, 0); dst##8[1] = PG8_LD8(PG8_SB(b, h), boff, boff1, 1); } \
;         else { _Pragma("unroll") for (int n = 0; n < 2; ++n) _Pragma("unroll") for (int k = 0; k < 2; ++k) dst[n][k] = *(const LAS bf16x8*)(lds + PG8_SB(b, h) + (k ? boff1 : boff) + n * 2048); } } while (0)
; #define PG8_WAIT_V(n) asm volatile("s_waitcnt vmcnt(" #n ")" ::: "memory")
; #define PG8_WAIT_L(n) asm volatile("s_waitcnt lgkmcnt(" #n ")" ::: "memory")
; #define PG8_BAR __builtin_amdgcn_s_barrier()
; #define PG8_SCHED __builtin_amdgcn_sched_barrier(0)
; #define PG8_S1 PG8_STAGE(PG8_SA(1, 1), a1 + hstepA, voffA)
; #define PG8_S2 do { PG8_STAGE(PG8_SB(0, 0), b2, voffB); PG8_STAGE(PG8_SB(0, 1), b2 + hstepB, voffB); PG8_STAGE(PG8_SA(0, 0), a2, voffA); } while (0)
; template <class Epi, class SchedT, bool ALIGN_EPI, bool SP2, bool FP8 = false>
; __device__ __forceinline__ void gemm_phase(LAS unsigned char* lds, const Gemm g, const SchedT& S, const Epi& E, const int wid) {
;     ...
;             PG8_LDB(B0, 0, 0); PG8_LDB(B1, 0, 1); PG8_SCHED; PG8_LDA(At, 0, 0); PG8_S1;
;             PG8_WAIT_V(8); PG8_WAIT_L(0); PG8_BAR; PG8_MMAP(0, 0, 0); PG8_BAR; PG8_SCHED;
;             PG8_LDA(At, 0, 1); PG8_S2;
;             PG8_WAIT_V(8); PG8_WAIT_L(0); PG8_BAR; PG8_MMAP(1, 0, 1); PG8_BAR; PG8_SCHED;
	v_mfma_f32_16x16x32_bf16 v[124:127], v[128:131], v[182:185], v[124:127]
	v_mfma_f32_16x16x32_bf16 v[120:123], v[136:139], v[182:185], v[120:123]
	v_mfma_f32_16x16x32_bf16 v[104:107], v[136:139], v[190:193], v[104:107]
	v_mfma_f32_16x16x32_bf16 v[108:111], v[128:131], v[190:193], v[108:111]
	s_setprio 0
	s_setprio 1
	v_mfma_f32_16x16x32_bf16 v[92:95], v[128:131], v[198:201], v[92:95]
	v_mfma_f32_16x16x32_bf16 v[88:91], v[136:139], v[198:201], v[88:91]
	v_mfma_f32_16x16x32_bf16 v[72:75], v[136:139], v[206:209], v[72:75]
	v_mfma_f32_16x16x32_bf16 v[76:79], v[128:131], v[206:209], v[76:79]
	s_setprio 0
	s_setprio 1
	v_mfma_f32_16x16x32_bf16 v[124:127], v[132:135], v[186:189], v[124:127]
	v_mfma_f32_16x16x32_bf16 v[120:123], v[140:143], v[186:189], v[120:123]
	v_mfma_f32_16x16x32_bf16 v[104:107], v[140:143], v[194:197], v[104:107]
	v_mfma_f32_16x16x32_bf16 v[108:111], v[132:135], v[194:197], v[108:111]
	s_setprio 0
	s_setprio 1
	v_mfma_f32_16x16x32_bf16 v[92:95], v[132:135], v[202:205], v[92:95]
	v_mfma_f32_16x16x32_bf16 v[88:91], v[140:143], v[202:205], v[88:91]
	v_mfma_f32_16x16x32_bf16 v[72:75], v[140:143], v[210:213], v[72:75]
	v_mfma_f32_16x16x32_bf16 v[76:79], v[132:135], v[210:213], v[76:79]
	s_setprio 0
	s_setprio 1
	v_mfma_f32_16x16x32_bf16 v[116:119], v[150:153], v[182:185], v[116:119]
	v_mfma_f32_16x16x32_bf16 v[112:115], v[158:161], v[182:185], v[112:115]
	v_mfma_f32_16x16x32_bf16 v[96:99], v[158:161], v[190:193], v[96:99]
	v_mfma_f32_16x16x32_bf16 v[100:103], v[150:153], v[190:193], v[100:103]
	s_setprio 0
	s_setprio 1
	v_mfma_f32_16x16x32_bf16 v[84:87], v[150:153], v[198:201], v[84:87]
	v_mfma_f32_16x16x32_bf16 v[80:83], v[158:161], v[198:201], v[80:83]
	v_mfma_f32_16x16x32_bf16 v[64:67], v[158:161], v[206:209], v[64:67]
	v_mfma_f32_16x16x32_bf16 v[68:71], v[150:153], v[206:209], v[68:71]
	s_setprio 0
	s_setprio 1
	v_mfma_f32_16x16x32_bf16 v[116:119], v[154:157], v[186:189], v[116:119]
	v_mfma_f32_16x16x32_bf16 v[112:115], v[162:165], v[186:189], v[112:115]
	v_mfma_f32_16x16x32_bf16 v[96:99], v[162:165], v[194:197], v[96:99]
	v_mfma_f32_16x16x32_bf16 v[100:103], v[154:157], v[194:197], v[100:103]
	s_setprio 0
	s_setprio 1
	v_mfma_f32_16x16x32_bf16 v[84:87], v[154:157], v[202:205], v[84:87]
	v_mfma_f32_16x16x32_bf16 v[80:83], v[162:165], v[202:205], v[80:83]
	v_mfma_f32_16x16x32_bf16 v[64:67], v[162:165], v[210:213], v[64:67]
	v_mfma_f32_16x16x32_bf16 v[68:71], v[154:157], v[210:213], v[68:71]
	s_barrier
	s_setprio 0
	v_mov_b32_e32 v144, v169
	s_add_i32 s16, s94, s86
	ds_read_b128 v[182:185], v177 offset:16384
	ds_read_b128 v[186:189], v177 offset:17408
	ds_read_b128 v[190:193], v177 offset:18432
	ds_read_b128 v[194:197], v177 offset:19456
	ds_read_b128 v[198:201], v177 offset:20480
	ds_read_b128 v[202:205], v177 offset:21504
	ds_read_b128 v[206:209], v177 offset:22528
	ds_read_b128 v[210:213], v177 offset:23552
	s_mov_b32 m0, s16
	s_nop 0
	global_load_lds_dwordx4 v144, s[52:53]
	v_mov_b32_e32 v144, v171
	s_add_i32 m0, s16, 0x2000
	s_add_u32 s60, s52, 0x40000
	global_load_lds_dwordx4 v144, s[52:53]
	s_addc_u32 s61, s53, 0
	v_mov_b32_e32 v144, v169
	s_add_i32 s16, s95, s86
	s_mov_b32 m0, s16
	s_nop 0
	global_load_lds_dwordx4 v144, s[60:61]
	v_mov_b32_e32 v144, v171
	s_add_i32 m0, s16, 0x2000
	s_nop 0
	global_load_lds_dwordx4 v144, s[60:61]
	v_mov_b32_e32 v144, v168
	s_mov_b32 m0, s87
	s_nop 0
	global_load_lds_dwordx4 v144, s[50:51]
	v_mov_b32_e32 v144, v170
	s_mov_b32 m0, s88
	s_nop 0
	global_load_lds_dwordx4 v144, s[50:51]
	s_waitcnt vmcnt(8)
	s_waitcnt lgkmcnt(0)
	s_setprio 1
	s_barrier
	v_mfma_f32_16x16x32_bf16 v[60:63], v[128:131], v[182:185], v[60:63]
	v_mfma_f32_16x16x32_bf16 v[56:59], v[136:139], v[182:185], v[56:59]
	v_mfma_f32_16x16x32_bf16 v[40:43], v[136:139], v[190:193], v[40:43]
	v_mfma_f32_16x16x32_bf16 v[44:47], v[128:131], v[190:193], v[44:47]
	s_setprio 0
	s_setprio 1
	v_mfma_f32_16x16x32_bf16 v[28:31], v[128:131], v[198:201], v[28:31]
	v_mfma_f32_16x16x32_bf16 v[24:27], v[136:139], v[198:201], v[24:27]
	v_mfma_f32_16x16x32_bf16 v[8:11], v[136:139], v[206:209], v[8:11]
	v_mfma_f32_16x16x32_bf16 v[12:15], v[128:131], v[206:209], v[12:15]
	s_setprio 0
	s_setprio 1
	v_mfma_f32_16x16x32_bf16 v[60:63], v[132:135], v[186:189], v[60:63]
	v_mfma_f32_16x16x32_bf16 v[56:59], v[140:143], v[186:189], v[56:59]
	v_mfma_f32_16x16x32_bf16 v[40:43], v[140:143], v[194:197], v[40:43]
	v_mfma_f32_16x16x32_bf16 v[44:47], v[132:135], v[194:197], v[44:47]
	s_setprio 0
	s_setprio 1
	v_mfma_f32_16x16x32_bf16 v[28:31], v[132:135], v[202:205], v[28:31]
	v_mfma_f32_16x16x32_bf16 v[24:27], v[140:143], v[202:205], v[24:27]
	v_mfma_f32_16x16x32_bf16 v[8:11], v[140:143], v[210:213], v[8:11]
	v_mfma_f32_16x16x32_bf16 v[12:15], v[132:135], v[210:213], v[12:15]
	s_setprio 0
	s_setprio 1
	v_mfma_f32_16x16x32_bf16 v[52:55], v[150:153], v[182:185], v[52:55]
	v_mfma_f32_16x16x32_bf16 v[48:51], v[158:161], v[182:185], v[48:51]
	v_mfma_f32_16x16x32_bf16 v[32:35], v[158:161], v[190:193], v[32:35]
	v_mfma_f32_16x16x32_bf16 v[36:39], v[150:153], v[190:193], v[36:39]
	s_setprio 0
	s_setprio 1
	v_mfma_f32_16x16x32_bf16 v[20:23], v[150:153], v[198:201], v[20:23]
	v_mfma_f32_16x16x32_bf16 v[16:19], v[158:161], v[198:201], v[16:19]
	v_mfma_f32_16x16x32_bf16 v[0:3], v[158:161], v[206:209], v[0:3]
	v_mfma_f32_16x16x32_bf16 v[4:7], v[150:153], v[206:209], v[4:7]
	s_setprio 0
	s_setprio 1
	v_mfma_f32_16x16x32_bf16 v[52:55], v[154:157], v[186:189], v[52:55]
	v_mfma_f32_16x16x32_bf16 v[48:51], v[162:165], v[186:189], v[48:51]
	v_mfma_f32_16x16x32_bf16 v[32:35], v[162:165], v[194:197], v[32:35]
	v_mfma_f32_16x16x32_bf16 v[36:39], v[154:157], v[194:197], v[36:39]
	s_setprio 0
	s_setprio 1
	v_mfma_f32_16x16x32_bf16 v[20:23], v[154:157], v[202:205], v[20:23]
	v_mfma_f32_16x16x32_bf16 v[16:19], v[162:165], v[202:205], v[16:19]
	v_mfma_f32_16x16x32_bf16 v[0:3], v[162:165], v[210:213], v[0:3]
	v_mfma_f32_16x16x32_bf16 v[4:7], v[154:157], v[210:213], v[4:7]
	s_barrier
; #define PG8_LDA(dst, b, h) do { if constexpr (FP8) { _Pragma("unroll") for (int m = 0; m < 4; ++m) dst##8[m] = PG8_LD8(PG8_SA(b, h), aoff, aoff1, m); } \
;         else { _Pragma("unroll") for (int m = 0; m < 4; ++m) _Pragma("unroll") for (int k = 0; k < 2; ++k) dst[m][k] = *(const LAS bf16x8*)(lds + PG8_SA(b, h) + (k ? aoff1 : aoff) + m * 2048); } } while (0)
; #define PG8_LDB(dst, b, h) do { if constexpr (FP8) { dst##8[0] = PG8_LD8(PG8_SB(b, h), boff, boff1, 0); dst##8[1] = PG8_LD8(PG8_SB(b, h), boff, boff1, 1); } \
;         else { _Pragma("unroll") for (int n = 0; n < 2; ++n) _Pragma("unroll") for (int k = 0; k < 2; ++k) dst[n][k] = *(const LAS bf16x8*)(lds + PG8_SB(b, h) + (k ? boff1 : boff) + n * 2048); } } while (0)
; #define PG8_WAIT_V(n) asm volatile("s_waitcnt vmcnt(" #n ")" ::: "memory")
; #define PG8_WAIT_L(n) asm volatile("s_waitcnt lgkmcnt(" #n ")" ::: "memory")
; #define PG8_BAR __builtin_amdgcn_s_barrier()
; #define PG8_SCHED __builtin_amdgcn_sched_barrier(0)
; #define PG8_S3 PG8_STAGE(PG8_SA(0, 1), a2 + hstepA, voffA)
; template <class Epi, class SchedT, bool ALIGN_EPI, bool SP2, bool FP8 = false>
; __device__ __forceinline__ void gemm_phase(LAS unsigned char* lds, const Gemm g, const SchedT& S, const Epi& E, const int wid) {
;     ...
;             PG8_LDB(B0, 1, 0); PG8_LDB(B1, 1, 1); PG8_SCHED; PG8_LDA(At, 1, 0); PG8_S3;
;             PG8_WAIT_V(8); PG8_WAIT_L(0); PG8_BAR; PG8_MMAP(0, 1, 0); PG8_BAR; PG8_SCHED;
	s_setprio 0
	s_add_i32 s16, 0, 0x18000
	s_add_i32 s17, 0, 0x1c000
	v_add_u32_e32 v132, s16, v172
	v_add_u32_e32 v144, s17, v172
	ds_read_b128 v[128:131], v132
	ds_read_b128 v[132:135], v132 offset:1024
	ds_read_b128 v[136:139], v178
	ds_read_b128 v[140:143], v178 offset:1024
	ds_read_b128 v[150:153], v144
	ds_read_b128 v[154:157], v144 offset:1024
	ds_read_b128 v[158:161], v179
	ds_read_b128 v[162:165], v179 offset:1024
	s_add_u32 s60, s50, 0x40000
	v_mov_b32_e32 v144, v168
	s_mov_b32 m0, s89
	ds_read_b128 v[182:185], v177 offset:32768
	ds_read_b128 v[186:189], v177 offset:33792
	ds_read_b128 v[190:193], v177 offset:34816
	ds_read_b128 v[194:197], v177 offset:35840
	ds_read_b128 v[198:201], v177 offset:36864
	ds_read_b128 v[202:205], v177 offset:37888
	ds_read_b128 v[206:209], v177 offset:38912
	ds_read_b128 v[210:213], v177 offset:39936
	s_addc_u32 s61, s51, 0
	s_nop 0
	global_load_lds_dwordx4 v144, s[60:61]
	v_mov_b32_e32 v144, v170
	s_mov_b32 m0, s90
	s_nop 0
	global_load_lds_dwordx4 v144, s[60:61]
	s_waitcnt vmcnt(8)
	s_waitcnt lgkmcnt(0)
	s_setprio 1
	s_barrier
	v_mfma_f32_16x16x32_bf16 v[124:127], v[128:131], v[182:185], v[124:127]
	v_mfma_f32_16x16x32_bf16 v[120:123], v[136:139], v[182:185], v[120:123]
	v_mfma_f32_16x16x32_bf16 v[104:107], v[136:139], v[190:193], v[104:107]
	v_mfma_f32_16x16x32_bf16 v[108:111], v[128:131], v[190:193], v[108:111]
	s_setprio 0
	s_setprio 1
	v_mfma_f32_16x16x32_bf16 v[92:95], v[128:131], v[198:201], v[92:95]
	v_mfma_f32_16x16x32_bf16 v[88:91], v[136:139], v[198:201], v[88:91]
	v_mfma_f32_16x16x32_bf16 v[72:75], v[136:139], v[206:209], v[72:75]
	v_mfma_f32_16x16x32_bf16 v[76:79], v[128:131], v[206:209], v[76:79]
	s_setprio 0
	s_setprio 1
	v_mfma_f32_16x16x32_bf16 v[124:127], v[132:135], v[186:189], v[124:127]
	v_mfma_f32_16x16x32_bf16 v[120:123], v[140:143], v[186:189], v[120:123]
	v_mfma_f32_16x16x32_bf16 v[104:107], v[140:143], v[194:197], v[104:107]
	v_mfma_f32_16x16x32_bf16 v[108:111], v[132:135], v[194:197], v[108:111]
	s_setprio 0
	s_setprio 1
	v_mfma_f32_16x16x32_bf16 v[92:95], v[132:135], v[202:205], v[92:95]
	v_mfma_f32_16x16x32_bf16 v[88:91], v[140:143], v[202:205], v[88:91]
	v_mfma_f32_16x16x32_bf16 v[72:75], v[140:143], v[210:213], v[72:75]
	v_mfma_f32_16x16x32_bf16 v[76:79], v[132:135], v[210:213], v[76:79]
	s_setprio 0
	s_setprio 1
	v_mfma_f32_16x16x32_bf16 v[116:119], v[150:153], v[182:185], v[116:119]
	v_mfma_f32_16x16x32_bf16 v[112:115], v[158:161], v[182:185], v[112:115]
	v_mfma_f32_16x16x32_bf16 v[96:99], v[158:161], v[190:193], v[96:99]
	v_mfma_f32_16x16x32_bf16 v[100:103], v[150:153], v[190:193], v[100:103]
	s_setprio 0
	s_setprio 1
	v_mfma_f32_16x16x32_bf16 v[84:87], v[150:153], v[198:201], v[84:87]
	v_mfma_f32_16x16x32_bf16 v[80:83], v[158:161], v[198:201], v[80:83]
	v_mfma_f32_16x16x32_bf16 v[64:67], v[158:161], v[206:209], v[64:67]
	v_mfma_f32_16x16x32_bf16 v[68:71], v[150:153], v[206:209], v[68:71]
	s_setprio 0
	s_setprio 1
	v_mfma_f32_16x16x32_bf16 v[116:119], v[154:157], v[186:189], v[116:119]
	v_mfma_f32_16x16x32_bf16 v[112:115], v[162:165], v[186:189], v[112:115]
	v_mfma_f32_16x16x32_bf16 v[96:99], v[162:165], v[194:197], v[96:99]
	v_mfma_f32_16x16x32_bf16 v[100:103], v[154:157], v[194:197], v[100:103]
	s_setprio 0
	s_setprio 1
	v_mfma_f32_16x16x32_bf16 v[84:87], v[154:157], v[202:205], v[84:87]
	v_mfma_f32_16x16x32_bf16 v[80:83], v[162:165], v[202:205], v[80:83]
	v_mfma_f32_16x16x32_bf16 v[64:67], v[162:165], v[210:213], v[64:67]
	v_mfma_f32_16x16x32_bf16 v[68:71], v[154:157], v[210:213], v[68:71]
	s_barrier
; #define PG8_LDA(dst, b, h) do { if constexpr (FP8) { _Pragma("unroll") for (int m = 0; m < 4; ++m) dst##8[m] = PG8_LD8(PG8_SA(b, h), aoff, aoff1, m); } \
;         else { _Pragma("unroll") for (int m = 0; m < 4; ++m) _Pragma("unroll") for (int k = 0; k < 2; ++k) dst[m][k] = *(const LAS bf16x8*)(lds + PG8_SA(b, h) + (k ? aoff1 : aoff) + m * 2048); } } while (0)
; #define PG8_WAIT_V(n) asm volatile("s_waitcnt vmcnt(" #n ")" ::: "memory")
; #define PG8_WAIT_L(n) asm volatile("s_waitcnt lgkmcnt(" #n ")" ::: "memory")
; #define PG8_BAR __builtin_amdgcn_s_barrier()
; #define PG8_SCHED __builtin_amdgcn_sched_barrier(0)
; #define PG8_S4 do { PG8_STAGE(PG8_SB(1, 0), b3, voffB); PG8_STAGE(PG8_SB(1, 1), b3 + hstepB, voffB); PG8_STAGE(PG8_SA(1, 0), a3, voffA); } while (0)
; template <class Epi, class SchedT, bool ALIGN_EPI, bool SP2, bool FP8 = false>
; __device__ __forceinline__ void gemm_phase(LAS unsigned char* lds, const Gemm g, const SchedT& S, const Epi& E, const int wid) {
;     ...
;             PG8_LDA(At, 1, 1); PG8_S4;
;             PG8_WAIT_V(8); PG8_WAIT_L(0); PG8_BAR; PG8_MMAP(1, 1, 1); PG8_BAR; PG8_SCHED;
	s_setprio 0
	v_mov_b32_e32 v144, v169
	ds_read_b128 v[182:185], v177 offset:49152
	ds_read_b128 v[186:189], v177 offset:50176
	ds_read_b128 v[190:193], v177 offset:51200
	ds_read_b128 v[194:197], v177 offset:52224
	ds_read_b128 v[198:201], v177 offset:53248
	ds_read_b128 v[202:205], v177 offset:54272
	ds_read_b128 v[206:209], v177 offset:55296
	ds_read_b128 v[210:213], v177 offset:56320
	s_add_i32 s16, s16, s86
	v_lshl_add_u64 v[166:167], s[52:53], 0, v[144:145]
	v_lshl_add_u64 v[166:167], v[166:167], 0, s[6:7]
	s_mov_b32 m0, s16
	v_mov_b32_e32 v144, v171
	global_load_lds_dwordx4 v[166:167], off
	s_add_i32 m0, s16, 0x2000
	s_nop 0
	v_lshl_add_u64 v[166:167], s[52:53], 0, v[144:145]
	s_add_u32 s52, s52, 0x40080
	v_lshl_add_u64 v[166:167], v[166:167], 0, s[6:7]
	s_addc_u32 s53, s53, 0
	v_mov_b32_e32 v144, v169
	s_add_i32 s16, s17, s86
	global_load_lds_dwordx4 v[166:167], off
	s_mov_b32 m0, s16
	s_nop 0
	global_load_lds_dwordx4 v144, s[52:53]
	v_mov_b32_e32 v144, v171
	s_add_i32 m0, s16, 0x2000
	s_nop 0
	global_load_lds_dwordx4 v144, s[52:53]
	v_mov_b32_e32 v144, v168
	s_mov_b32 m0, s92
	v_lshl_add_u64 v[166:167], s[50:51], 0, v[144:145]
	v_lshl_add_u64 v[166:167], v[166:167], 0, s[6:7]
	v_mov_b32_e32 v144, v170
	global_load_lds_dwordx4 v[166:167], off
	s_mov_b32 m0, s93
	v_lshl_add_u64 v[166:167], s[50:51], 0, v[144:145]
	v_lshl_add_u64 v[166:167], v[166:167], 0, s[6:7]
	global_load_lds_dwordx4 v[166:167], off
	s_waitcnt vmcnt(8)
	s_waitcnt lgkmcnt(0)
	s_setprio 1
	s_barrier
	v_mfma_f32_16x16x32_bf16 v[60:63], v[128:131], v[182:185], v[60:63]
	v_mfma_f32_16x16x32_bf16 v[56:59], v[136:139], v[182:185], v[56:59]
	v_mfma_f32_16x16x32_bf16 v[40:43], v[136:139], v[190:193], v[40:43]
	v_mfma_f32_16x16x32_bf16 v[44:47], v[128:131], v[190:193], v[44:47]
	s_setprio 0
	s_setprio 1
	v_mfma_f32_16x16x32_bf16 v[28:31], v[128:131], v[198:201], v[28:31]
	v_mfma_f32_16x16x32_bf16 v[24:27], v[136:139], v[198:201], v[24:27]
	v_mfma_f32_16x16x32_bf16 v[8:11], v[136:139], v[206:209], v[8:11]
	v_mfma_f32_16x16x32_bf16 v[12:15], v[128:131], v[206:209], v[12:15]
	s_setprio 0
	s_setprio 1
	v_mfma_f32_16x16x32_bf16 v[60:63], v[132:135], v[186:189], v[60:63]
	v_mfma_f32_16x16x32_bf16 v[56:59], v[140:143], v[186:189], v[56:59]
	v_mfma_f32_16x16x32_bf16 v[40:43], v[140:143], v[194:197], v[40:43]
	v_mfma_f32_16x16x32_bf16 v[44:47], v[132:135], v[194:197], v[44:47]
	s_setprio 0
	s_setprio 1
	v_mfma_f32_16x16x32_bf16 v[28:31], v[132:135], v[202:205], v[28:31]
	v_mfma_f32_16x16x32_bf16 v[24:27], v[140:143], v[202:205], v[24:27]
	v_mfma_f32_16x16x32_bf16 v[8:11], v[140:143], v[210:213], v[8:11]
	v_mfma_f32_16x16x32_bf16 v[12:15], v[132:135], v[210:213], v[12:15]
	s_setprio 0
	s_setprio 1
	v_mfma_f32_16x16x32_bf16 v[52:55], v[150:153], v[182:185], v[52:55]
	v_mfma_f32_16x16x32_bf16 v[48:51], v[158:161], v[182:185], v[48:51]
	v_mfma_f32_16x16x32_bf16 v[32:35], v[158:161], v[190:193], v[32:35]
	v_mfma_f32_16x16x32_bf16 v[36:39], v[150:153], v[190:193], v[36:39]
	s_setprio 0
	s_setprio 1
	v_mfma_f32_16x16x32_bf16 v[20:23], v[150:153], v[198:201], v[20:23]
	v_mfma_f32_16x16x32_bf16 v[16:19], v[158:161], v[198:201], v[16:19]
	v_mfma_f32_16x16x32_bf16 v[0:3], v[158:161], v[206:209], v[0:3]
	v_mfma_f32_16x16x32_bf16 v[4:7], v[150:153], v[206:209], v[4:7]
	s_setprio 0
	s_setprio 1
	v_mfma_f32_16x16x32_bf16 v[52:55], v[154:157], v[186:189], v[52:55]
	v_mfma_f32_16x16x32_bf16 v[48:51], v[162:165], v[186:189], v[48:51]
	v_mfma_f32_16x16x32_bf16 v[32:35], v[162:165], v[194:197], v[32:35]
	v_mfma_f32_16x16x32_bf16 v[36:39], v[154:157], v[194:197], v[36:39]
	s_setprio 0
	s_setprio 1
	v_mfma_f32_16x16x32_bf16 v[20:23], v[154:157], v[202:205], v[20:23]
	v_mfma_f32_16x16x32_bf16 v[16:19], v[162:165], v[202:205], v[16:19]
	v_mfma_f32_16x16x32_bf16 v[0:3], v[162:165], v[210:213], v[0:3]
	v_mfma_f32_16x16x32_bf16 v[4:7], v[154:157], v[210:213], v[4:7]
	s_barrier
	s_setprio 0
	s_add_u32 s48, s48, 0x100
	s_addc_u32 s49, s49, 0
	s_add_u32 s30, s30, 0x100
	s_addc_u32 s31, s31, 0
	s_cmp_ge_i32 s35, s20
	s_mov_b32 s34, s35
	s_cbranch_scc0 .LBB0_899

; #define PG8_LDA(dst, b, h) do { if constexpr (FP8) { _Pragma("unroll") for (int m = 0; m < 4; ++m) dst##8[m] = PG8_LD8(PG8_SA(b, h), aoff, aoff1, m); } \
;         else { _Pragma("unroll") for (int m = 0; m < 4; ++m) _Pragma("unroll") for (int k = 0; k < 2; ++k) dst[m][k] = *(const LAS bf16x8*)(lds + PG8_SA(b, h) + (k ? aoff1 : aoff) + m * 2048); } } while (0)
; #define PG8_LDB(dst, b, h) do { if constexpr (FP8) { dst##8[0] = PG8_LD8(PG8_SB(b, h), boff, boff1, 0); dst##8[1] = PG8_LD8(PG8_SB(b, h), boff, boff1, 1); } \
;         else { _Pragma("unroll") for (int n = 0; n < 2; ++n) _Pragma("unroll") for (int k = 0; k < 2; ++k) dst[n][k] = *(const LAS bf16x8*)(lds + PG8_SB(b, h) + (k ? boff1 : boff) + n * 2048); } } while (0)
; #define PG8_WAIT_V(n) asm volatile("s_waitcnt vmcnt(" #n ")" ::: "memory")
; #define PG8_WAIT_L(n) asm volatile("s_waitcnt lgkmcnt(" #n ")" ::: "memory")
; #define PG8_BAR __builtin_amdgcn_s_barrier()
; #define PG8_SCHED __builtin_amdgcn_sched_barrier(0)
; #define PG8_S1 PG8_STAGE(PG8_SA(1, 1), a1 + hstepA, voffA)
; template <class Epi, class SchedT, bool ALIGN_EPI, bool SP2, bool FP8 = false>
; __device__ __forceinline__ void gemm_phase(LAS unsigned char* lds, const Gemm g, const SchedT& S, const Epi& E, const int wid) {
;     ...
;     for (;;) {
;         const bool has_next = S.next(ui + 1, nxt);
;         const char* nA = has_next ? (const char*)g.A + (size_t)nxt.pm * tstepA + (size_t)nxt.aoff * 2 : cA; const char* nB = has_next ? (const char*)g.Bt + (size_t)nxt.pn * tstepB + (size_t)nxt.boff * 2 : cB;
;         const int nt = cur.nt;
;         for (int t = 0; t < nt; t += 2) {
;             const bool last = (t == nt - 2);
;             const char* a1 = cA + (size_t)(t + 1) * kstep;
;             const char* a2 = last ? nA : cA + (size_t)(t + 2) * kstep; const char* b2 = last ? nB : cB + (size_t)(t + 2) * kstep;
;             const char* a3 = a2 + kstep; const char* b3 = b2 + kstep;
;             if constexpr (SP2) {
;     ...
;             PG8_LDB(B0, 0, 0); PG8_LDB(B1, 0, 1); PG8_SCHED; PG8_LDA(At, 0, 0); PG8_S1;
;             PG8_WAIT_V(8); PG8_WAIT_L(0); PG8_BAR; PG8_MMAP(0, 0, 0); PG8_BAR; PG8_SCHED;
;             PG8_LDA(At, 0, 1); PG8_S2;
;             PG8_WAIT_V(8); PG8_WAIT_L(0); PG8_BAR; PG8_MMAP(1, 0, 1); PG8_BAR; PG8_SCHED;
.LBB0_968:
	s_ashr_i32 s15, s14, 31
	s_lshl_b64 s[20:21], s[14:15], 21
	s_add_u32 s20, s36, s20
	s_addc_u32 s21, s37, s21
	s_ashr_i32 s13, s12, 31
	s_lshl_b64 s[22:23], s[12:13], 21
	s_add_u32 s22, s52, s22
	s_addc_u32 s23, s53, s23
	s_cmp_lt_i32 s30, 1
	s_cbranch_scc1 .LBB0_997
	s_and_b64 s[38:39], s[4:5], exec
	s_cselect_b32 s13, s21, s25
	s_cselect_b32 s15, s20, s24
	s_cselect_b32 s27, s23, s35
	s_cselect_b32 s31, s22, s34
	s_add_i32 s45, s30, -2
	s_add_u32 s24, s24, 0x100080
	s_addc_u32 s25, s25, 0
	s_add_u32 s46, s34, 0x100
	s_addc_u32 s47, s35, 0
	s_mov_b32 s34, 0
	ds_read_b128 v[134:137], v175
	ds_read_b128 v[138:141], v175 offset:1024
	ds_read_b128 v[142:145], v176
	ds_read_b128 v[146:149], v176 offset:1024
	ds_read_b128 v[150:153], v177
	ds_read_b128 v[154:157], v177 offset:1024
	ds_read_b128 v[158:161], v178
	ds_read_b128 v[162:165], v178 offset:1024
	s_add_i32 s48, s34, 2
	s_add_u32 s16, s24, 0xfff00080
	s_addc_u32 s17, s25, -1
	s_cmp_eq_u32 s45, s34
	s_cselect_b32 s34, s15, s16
	s_cselect_b32 s35, s13, s17
	s_cselect_b32 s39, s27, s47
	s_cselect_b32 s38, s31, s46
	v_mov_b32_e32 v128, v172
	ds_read_b128 v[166:169], v179
	ds_read_b128 v[184:187], v179 offset:1024
	ds_read_b128 v[188:191], v179 offset:2048
	ds_read_b128 v[192:195], v179 offset:3072
	ds_read_b128 v[196:199], v179 offset:4096
	ds_read_b128 v[200:203], v179 offset:5120
	ds_read_b128 v[204:207], v179 offset:6144
	ds_read_b128 v[208:211], v179 offset:7168
	s_add_i32 m0, s87, 0xc000
	s_nop 0
	global_load_lds_dwordx4 v128, s[24:25]
	v_mov_b32_e32 v128, v173
	s_add_i32 m0, s87, 0xe000
	s_nop 0
	global_load_lds_dwordx4 v128, s[24:25]
	s_waitcnt vmcnt(8)
	s_waitcnt lgkmcnt(0)
	s_setprio 1
	s_barrier
	v_mfma_f32_16x16x32_bf16 v[124:127], v[134:137], v[166:169], 0
	v_mfma_f32_16x16x32_bf16 v[120:123], v[142:145], v[166:169], 0
	v_mfma_f32_16x16x32_bf16 v[104:107], v[142:145], v[188:191], 0
	v_mfma_f32_16x16x32_bf16 v[108:111], v[134:137], v[188:191], 0
	s_setprio 0
	s_setprio 1
	v_mfma_f32_16x16x32_bf16 v[92:95], v[134:137], v[196:199], 0
	v_mfma_f32_16x16x32_bf16 v[88:91], v[142:145], v[196:199], 0
	v_mfma_f32_16x16x32_bf16 v[72:75], v[142:145], v[204:207], 0
	v_mfma_f32_16x16x32_bf16 v[76:79], v[134:137], v[204:207], 0
	s_setprio 0
	s_setprio 1
	v_mfma_f32_16x16x32_bf16 v[124:127], v[138:141], v[184:187], v[124:127]
	v_mfma_f32_16x16x32_bf16 v[120:123], v[146:149], v[184:187], v[120:123]
	v_mfma_f32_16x16x32_bf16 v[104:107], v[146:149], v[192:195], v[104:107]
	v_mfma_f32_16x16x32_bf16 v[108:111], v[138:141], v[192:195], v[108:111]
	s_setprio 0
	s_setprio 1
	v_mfma_f32_16x16x32_bf16 v[92:95], v[138:141], v[200:203], v[92:95]
	v_mfma_f32_16x16x32_bf16 v[88:91], v[146:149], v[200:203], v[88:91]
	v_mfma_f32_16x16x32_bf16 v[72:75], v[146:149], v[208:211], v[72:75]
	v_mfma_f32_16x16x32_bf16 v[76:79], v[138:141], v[208:211], v[76:79]
	s_setprio 0
	s_setprio 1
	v_mfma_f32_16x16x32_bf16 v[116:119], v[150:153], v[166:169], 0
	v_mfma_f32_16x16x32_bf16 v[112:115], v[158:161], v[166:169], 0
	v_mfma_f32_16x16x32_bf16 v[96:99], v[158:161], v[188:191], 0
	v_mfma_f32_16x16x32_bf16 v[100:103], v[150:153], v[188:191], 0
	s_setprio 0
	s_setprio 1
	v_mfma_f32_16x16x32_bf16 v[84:87], v[150:153], v[196:199], 0
	v_mfma_f32_16x16x32_bf16 v[80:83], v[158:161], v[196:199], 0
	v_mfma_f32_16x16x32_bf16 v[64:67], v[158:161], v[204:207], 0
	v_mfma_f32_16x16x32_bf16 v[68:71], v[150:153], v[204:207], 0
	s_setprio 0
	s_setprio 1
	v_mfma_f32_16x16x32_bf16 v[116:119], v[154:157], v[184:187], v[116:119]
	v_mfma_f32_16x16x32_bf16 v[112:115], v[162:165], v[184:187], v[112:115]
	v_mfma_f32_16x16x32_bf16 v[96:99], v[162:165], v[192:195], v[96:99]
	v_mfma_f32_16x16x32_bf16 v[100:103], v[154:157], v[192:195], v[100:103]
	s_setprio 0
	s_setprio 1
	v_mfma_f32_16x16x32_bf16 v[84:87], v[154:157], v[200:203], v[84:87]
	v_mfma_f32_16x16x32_bf16 v[80:83], v[162:165], v[200:203], v[80:83]
	v_mfma_f32_16x16x32_bf16 v[64:67], v[162:165], v[208:211], v[64:67]
	v_mfma_f32_16x16x32_bf16 v[68:71], v[154:157], v[208:211], v[68:71]
	s_barrier
	s_setprio 0
	v_mov_b32_e32 v128, v172
	s_add_i32 s16, s94, s86
	ds_read_b128 v[166:169], v179 offset:16384
	ds_read_b128 v[184:187], v179 offset:17408
	ds_read_b128 v[188:191], v179 offset:18432
	ds_read_b128 v[192:195], v179 offset:19456
	ds_read_b128 v[196:199], v179 offset:20480
	ds_read_b128 v[200:203], v179 offset:21504
	ds_read_b128 v[204:207], v179 offset:22528
	ds_read_b128 v[208:211], v179 offset:23552
	s_mov_b32 m0, s16
	s_nop 0
	global_load_lds_dwordx4 v128, s[38:39]
	v_mov_b32_e32 v128, v173
	s_add_i32 m0, s16, 0x2000
	s_add_u32 s50, s38, 0x100000
	global_load_lds_dwordx4 v128, s[38:39]
	s_addc_u32 s51, s39, 0
	v_mov_b32_e32 v128, v172
	s_add_i32 s16, s95, s86
	s_mov_b32 m0, s16
	s_nop 0
	global_load_lds_dwordx4 v128, s[50:51]
	v_mov_b32_e32 v128, v173
	s_add_i32 m0, s16, 0x2000
	s_nop 0
	global_load_lds_dwordx4 v128, s[50:51]
	v_mov_b32_e32 v128, v172
	s_mov_b32 m0, s87
	s_nop 0
	global_load_lds_dwordx4 v128, s[34:35]
	v_mov_b32_e32 v128, v173
	s_mov_b32 m0, s88
	s_nop 0
	global_load_lds_dwordx4 v128, s[34:35]
	s_waitcnt vmcnt(8)
	s_waitcnt lgkmcnt(0)
	s_setprio 1
	s_barrier
; #define PG8_LDA(dst, b, h) do { if constexpr (FP8) { _Pragma("unroll") for (int m = 0; m < 4; ++m) dst##8[m] = PG8_LD8(PG8_SA(b, h), aoff, aoff1, m); } \
;         else { _Pragma("unroll") for (int m = 0; m < 4; ++m) _Pragma("unroll") for (int k = 0; k < 2; ++k) dst[m][k] = *(const LAS bf16x8*)(lds + PG8_SA(b, h) + (k ? aoff1 : aoff) + m * 2048); } } while (0)
; #define PG8_LDB(dst, b, h) do { if constexpr (FP8) { dst##8[0] = PG8_LD8(PG8_SB(b, h), boff, boff1, 0); dst##8[1] = PG8_LD8(PG8_SB(b, h), boff, boff1, 1); } \
;         else { _Pragma("unroll") for (int n = 0; n < 2; ++n) _Pragma("unroll") for (int k = 0; k < 2; ++k) dst[n][k] = *(const LAS bf16x8*)(lds + PG8_SB(b, h) + (k ? boff1 : boff) + n * 2048); } } while (0)
; #define PG8_WAIT_V(n) asm volatile("s_waitcnt vmcnt(" #n ")" ::: "memory")
; #define PG8_WAIT_L(n) asm volatile("s_waitcnt lgkmcnt(" #n ")" ::: "memory")
; #define PG8_BAR __builtin_amdgcn_s_barrier()
; #define PG8_SCHED __builtin_amdgcn_sched_barrier(0)
; #define PG8_S1 PG8_STAGE(PG8_SA(1, 1), a1 + hstepA, voffA)
; #define PG8_S2 do { PG8_STAGE(PG8_SB(0, 0), b2, voffB); PG8_STAGE(PG8_SB(0, 1), b2 + hstepB, voffB); PG8_STAGE(PG8_SA(0, 0), a2, voffA); } while (0)
; #define PG8_S3 PG8_STAGE(PG8_SA(0, 1), a2 + hstepA, voffA)
; template <class Epi, class SchedT, bool ALIGN_EPI, bool SP2, bool FP8 = false>
; __device__ __forceinline__ void gemm_phase(LAS unsigned char* lds, const Gemm g, const SchedT& S, const Epi& E, const int wid) {
;     ...
;             if constexpr (SP2) {
;     ...
;             PG8_LDB(B0, 0, 0); PG8_LDB(B1, 0, 1); PG8_SCHED; PG8_LDA(At, 0, 0); PG8_S1;
;             PG8_WAIT_V(8); PG8_WAIT_L(0); PG8_BAR; PG8_MMAP(0, 0, 0); PG8_BAR; PG8_SCHED;
;             PG8_LDA(At, 0, 1); PG8_S2;
;             PG8_WAIT_V(8); PG8_WAIT_L(0); PG8_BAR; PG8_MMAP(1, 0, 1); PG8_BAR; PG8_SCHED;
;             PG8_LDB(B0, 1, 0); PG8_LDB(B1, 1, 1); PG8_SCHED; PG8_LDA(At, 1, 0); PG8_S3;
;             PG8_WAIT_V(8); PG8_WAIT_L(0); PG8_BAR; PG8_MMAP(0, 1, 0); PG8_BAR; PG8_SCHED;
	v_mfma_f32_16x16x32_bf16 v[60:63], v[134:137], v[166:169], 0
	v_mfma_f32_16x16x32_bf16 v[56:59], v[142:145], v[166:169], 0
	v_mfma_f32_16x16x32_bf16 v[40:43], v[142:145], v[188:191], 0
	v_mfma_f32_16x16x32_bf16 v[44:47], v[134:137], v[188:191], 0
	s_setprio 0
	s_setprio 1
	v_mfma_f32_16x16x32_bf16 v[28:31], v[134:137], v[196:199], 0
	v_mfma_f32_16x16x32_bf16 v[24:27], v[142:145], v[196:199], 0
	v_mfma_f32_16x16x32_bf16 v[8:11], v[142:145], v[204:207], 0
	v_mfma_f32_16x16x32_bf16 v[12:15], v[134:137], v[204:207], 0
	s_setprio 0
	s_setprio 1
	v_mfma_f32_16x16x32_bf16 v[60:63], v[138:141], v[184:187], v[60:63]
	v_mfma_f32_16x16x32_bf16 v[56:59], v[146:149], v[184:187], v[56:59]
	v_mfma_f32_16x16x32_bf16 v[40:43], v[146:149], v[192:195], v[40:43]
	v_mfma_f32_16x16x32_bf16 v[44:47], v[138:141], v[192:195], v[44:47]
	s_setprio 0
	s_setprio 1
	v_mfma_f32_16x16x32_bf16 v[28:31], v[138:141], v[200:203], v[28:31]
	v_mfma_f32_16x16x32_bf16 v[24:27], v[146:149], v[200:203], v[24:27]
	v_mfma_f32_16x16x32_bf16 v[8:11], v[146:149], v[208:211], v[8:11]
	v_mfma_f32_16x16x32_bf16 v[12:15], v[138:141], v[208:211], v[12:15]
	s_setprio 0
	s_setprio 1
	v_mfma_f32_16x16x32_bf16 v[52:55], v[150:153], v[166:169], 0
	v_mfma_f32_16x16x32_bf16 v[48:51], v[158:161], v[166:169], 0
	v_mfma_f32_16x16x32_bf16 v[32:35], v[158:161], v[188:191], 0
	v_mfma_f32_16x16x32_bf16 v[36:39], v[150:153], v[188:191], 0
	s_setprio 0
	s_setprio 1
	v_mfma_f32_16x16x32_bf16 v[20:23], v[150:153], v[196:199], 0
	v_mfma_f32_16x16x32_bf16 v[16:19], v[158:161], v[196:199], 0
	v_mfma_f32_16x16x32_bf16 v[0:3], v[158:161], v[204:207], 0
	v_mfma_f32_16x16x32_bf16 v[4:7], v[150:153], v[204:207], 0
	s_setprio 0
	s_setprio 1
	v_mfma_f32_16x16x32_bf16 v[52:55], v[154:157], v[184:187], v[52:55]
	v_mfma_f32_16x16x32_bf16 v[48:51], v[162:165], v[184:187], v[48:51]
	v_mfma_f32_16x16x32_bf16 v[32:35], v[162:165], v[192:195], v[32:35]
	v_mfma_f32_16x16x32_bf16 v[36:39], v[154:157], v[192:195], v[36:39]
	s_setprio 0
	s_setprio 1
	v_mfma_f32_16x16x32_bf16 v[20:23], v[154:157], v[200:203], v[20:23]
	v_mfma_f32_16x16x32_bf16 v[16:19], v[162:165], v[200:203], v[16:19]
	v_mfma_f32_16x16x32_bf16 v[0:3], v[162:165], v[208:211], v[0:3]
	v_mfma_f32_16x16x32_bf16 v[4:7], v[154:157], v[208:211], v[4:7]
	s_barrier
	s_setprio 0
	s_add_i32 s16, 0, 0x18000
	v_add_u32_e32 v128, s16, v174
	s_add_i32 s17, 0, 0x1c000
	ds_read_b128 v[134:137], v128
	ds_read_b128 v[138:141], v128 offset:1024
	ds_read_b128 v[142:145], v180
	ds_read_b128 v[146:149], v180 offset:1024
	v_add_u32_e32 v128, s17, v174
	ds_read_b128 v[150:153], v128
	ds_read_b128 v[154:157], v128 offset:1024
	ds_read_b128 v[158:161], v181
	ds_read_b128 v[162:165], v181 offset:1024
	s_add_u32 s50, s34, 0x100000
	v_mov_b32_e32 v128, v172
	s_mov_b32 m0, s89
	ds_read_b128 v[166:169], v179 offset:32768
	ds_read_b128 v[184:187], v179 offset:33792
	ds_read_b128 v[188:191], v179 offset:34816
	ds_read_b128 v[192:195], v179 offset:35840
	ds_read_b128 v[196:199], v179 offset:36864
	ds_read_b128 v[200:203], v179 offset:37888
	ds_read_b128 v[204:207], v179 offset:38912
	ds_read_b128 v[208:211], v179 offset:39936
	s_addc_u32 s51, s35, 0
	s_nop 0
	global_load_lds_dwordx4 v128, s[50:51]
	v_mov_b32_e32 v128, v173
	s_mov_b32 m0, s90
	s_nop 0
	global_load_lds_dwordx4 v128, s[50:51]
	s_waitcnt vmcnt(8)
	s_waitcnt lgkmcnt(0)
	s_setprio 1
	s_barrier
	v_mfma_f32_16x16x32_bf16 v[124:127], v[134:137], v[166:169], v[124:127]
	v_mfma_f32_16x16x32_bf16 v[120:123], v[142:145], v[166:169], v[120:123]
	v_mfma_f32_16x16x32_bf16 v[104:107], v[142:145], v[188:191], v[104:107]
	v_mfma_f32_16x16x32_bf16 v[108:111], v[134:137], v[188:191], v[108:111]
	s_setprio 0
	s_setprio 1
	v_mfma_f32_16x16x32_bf16 v[92:95], v[134:137], v[196:199], v[92:95]
	v_mfma_f32_16x16x32_bf16 v[88:91], v[142:145], v[196:199], v[88:91]
	v_mfma_f32_16x16x32_bf16 v[72:75], v[142:145], v[204:207], v[72:75]
	v_mfma_f32_16x16x32_bf16 v[76:79], v[134:137], v[204:207], v[76:79]
	s_setprio 0
	s_setprio 1
	v_mfma_f32_16x16x32_bf16 v[124:127], v[138:141], v[184:187], v[124:127]
	v_mfma_f32_16x16x32_bf16 v[120:123], v[146:149], v[184:187], v[120:123]
	v_mfma_f32_16x16x32_bf16 v[104:107], v[146:149], v[192:195], v[104:107]
	v_mfma_f32_16x16x32_bf16 v[108:111], v[138:141], v[192:195], v[108:111]
	s_setprio 0
	s_setprio 1
	v_mfma_f32_16x16x32_bf16 v[92:95], v[138:141], v[200:203], v[92:95]
	v_mfma_f32_16x16x32_bf16 v[88:91], v[146:149], v[200:203], v[88:91]
	v_mfma_f32_16x16x32_bf16 v[72:75], v[146:149], v[208:211], v[72:75]
	v_mfma_f32_16x16x32_bf16 v[76:79], v[138:141], v[208:211], v[76:79]
	s_setprio 0
	s_setprio 1
	v_mfma_f32_16x16x32_bf16 v[116:119], v[150:153], v[166:169], v[116:119]
	v_mfma_f32_16x16x32_bf16 v[112:115], v[158:161], v[166:169], v[112:115]
	v_mfma_f32_16x16x32_bf16 v[96:99], v[158:161], v[188:191], v[96:99]
	v_mfma_f32_16x16x32_bf16 v[100:103], v[150:153], v[188:191], v[100:103]
	s_setprio 0
	s_setprio 1
	v_mfma_f32_16x16x32_bf16 v[84:87], v[150:153], v[196:199], v[84:87]
	v_mfma_f32_16x16x32_bf16 v[80:83], v[158:161], v[196:199], v[80:83]
	v_mfma_f32_16x16x32_bf16 v[64:67], v[158:161], v[204:207], v[64:67]
	v_mfma_f32_16x16x32_bf16 v[68:71], v[150:153], v[204:207], v[68:71]
	s_setprio 0
	s_setprio 1
	v_mfma_f32_16x16x32_bf16 v[116:119], v[154:157], v[184:187], v[116:119]
	v_mfma_f32_16x16x32_bf16 v[112:115], v[162:165], v[184:187], v[112:115]
	v_mfma_f32_16x16x32_bf16 v[96:99], v[162:165], v[192:195], v[96:99]
	v_mfma_f32_16x16x32_bf16 v[100:103], v[154:157], v[192:195], v[100:103]
	s_setprio 0
	s_setprio 1
	v_mfma_f32_16x16x32_bf16 v[84:87], v[154:157], v[200:203], v[84:87]
	v_mfma_f32_16x16x32_bf16 v[80:83], v[162:165], v[200:203], v[80:83]
	v_mfma_f32_16x16x32_bf16 v[64:67], v[162:165], v[208:211], v[64:67]
	v_mfma_f32_16x16x32_bf16 v[68:71], v[154:157], v[208:211], v[68:71]
	s_barrier
; #define PG8_LDA(dst, b, h) do { if constexpr (FP8) { _Pragma("unroll") for (int m = 0; m < 4; ++m) dst##8[m] = PG8_LD8(PG8_SA(b, h), aoff, aoff1, m); } \
;         else { _Pragma("unroll") for (int m = 0; m < 4; ++m) _Pragma("unroll") for (int k = 0; k < 2; ++k) dst[m][k] = *(const LAS bf16x8*)(lds + PG8_SA(b, h) + (k ? aoff1 : aoff) + m * 2048); } } while (0)
; #define PG8_LDB(dst, b, h) do { if constexpr (FP8) { dst##8[0] = PG8_LD8(PG8_SB(b, h), boff, boff1, 0); dst##8[1] = PG8_LD8(PG8_SB(b, h), boff, boff1, 1); } \
;         else { _Pragma("unroll") for (int n = 0; n < 2; ++n) _Pragma("unroll") for (int k = 0; k < 2; ++k) dst[n][k] = *(const LAS bf16x8*)(lds + PG8_SB(b, h) + (k ? boff1 : boff) + n * 2048); } } while (0)
; #define PG8_WAIT_V(n) asm volatile("s_waitcnt vmcnt(" #n ")" ::: "memory")
; #define PG8_WAIT_L(n) asm volatile("s_waitcnt lgkmcnt(" #n ")" ::: "memory")
; #define PG8_BAR __builtin_amdgcn_s_barrier()
; #define PG8_SCHED __builtin_amdgcn_sched_barrier(0)
; #define PG8_S1 PG8_STAGE(PG8_SA(1, 1), a1 + hstepA, voffA)
; #define PG8_S4 do { PG8_STAGE(PG8_SB(1, 0), b3, voffB); PG8_STAGE(PG8_SB(1, 1), b3 + hstepB, voffB); PG8_STAGE(PG8_SA(1, 0), a3, voffA); } while (0)
; template <class Epi, class SchedT, bool ALIGN_EPI, bool SP2, bool FP8 = false>
; __device__ __forceinline__ void gemm_phase(LAS unsigned char* lds, const Gemm g, const SchedT& S, const Epi& E, const int wid) {
;     ...
;         for (int t = 0; t < nt; t += 2) {
;             const bool last = (t == nt - 2);
;             const char* a1 = cA + (size_t)(t + 1) * kstep;
;             const char* a2 = last ? nA : cA + (size_t)(t + 2) * kstep; const char* b2 = last ? nB : cB + (size_t)(t + 2) * kstep;
;             const char* a3 = a2 + kstep; const char* b3 = b2 + kstep;
;             if constexpr (SP2) {
;     ...
;             PG8_LDB(B0, 0, 0); PG8_LDB(B1, 0, 1); PG8_SCHED; PG8_LDA(At, 0, 0); PG8_S1;
;             PG8_WAIT_V(8); PG8_WAIT_L(0); PG8_BAR; PG8_MMAP(0, 0, 0); PG8_BAR; PG8_SCHED;
;     ...
;             PG8_LDA(At, 1, 1); PG8_S4;
;             PG8_WAIT_V(8); PG8_WAIT_L(0); PG8_BAR; PG8_MMAP(1, 1, 1); PG8_BAR; PG8_SCHED;
	s_setprio 0
	v_mov_b32_e32 v128, v172
	ds_read_b128 v[166:169], v179 offset:49152
	ds_read_b128 v[184:187], v179 offset:50176
	ds_read_b128 v[188:191], v179 offset:51200
	ds_read_b128 v[192:195], v179 offset:52224
	ds_read_b128 v[196:199], v179 offset:53248
	ds_read_b128 v[200:203], v179 offset:54272
	ds_read_b128 v[204:207], v179 offset:55296
	ds_read_b128 v[208:211], v179 offset:56320
	s_add_i32 s16, s16, s86
	v_lshl_add_u64 v[170:171], s[38:39], 0, v[128:129]
	v_lshl_add_u64 v[170:171], v[170:171], 0, s[8:9]
	s_mov_b32 m0, s16
	v_mov_b32_e32 v128, v173
	global_load_lds_dwordx4 v[170:171], off
	s_add_i32 m0, s16, 0x2000
	s_nop 0
	v_lshl_add_u64 v[170:171], s[38:39], 0, v[128:129]
	s_add_u32 s38, s38, 0x100080
	v_lshl_add_u64 v[170:171], v[170:171], 0, s[8:9]
	s_addc_u32 s39, s39, 0
	v_mov_b32_e32 v128, v172
	s_add_i32 s16, s17, s86
	global_load_lds_dwordx4 v[170:171], off
	s_mov_b32 m0, s16
	s_nop 0
	global_load_lds_dwordx4 v128, s[38:39]
	v_mov_b32_e32 v128, v173
	s_add_i32 m0, s16, 0x2000
	s_nop 0
	global_load_lds_dwordx4 v128, s[38:39]
	v_mov_b32_e32 v128, v172
	s_mov_b32 m0, s92
	v_lshl_add_u64 v[170:171], s[34:35], 0, v[128:129]
	v_lshl_add_u64 v[170:171], v[170:171], 0, s[8:9]
	v_mov_b32_e32 v128, v173
	global_load_lds_dwordx4 v[170:171], off
	s_mov_b32 m0, s93
	v_lshl_add_u64 v[170:171], s[34:35], 0, v[128:129]
	v_lshl_add_u64 v[170:171], v[170:171], 0, s[8:9]
	global_load_lds_dwordx4 v[170:171], off
	s_waitcnt vmcnt(8)
	s_waitcnt lgkmcnt(0)
	s_setprio 1
	s_barrier
	v_mfma_f32_16x16x32_bf16 v[60:63], v[134:137], v[166:169], v[60:63]
	v_mfma_f32_16x16x32_bf16 v[56:59], v[142:145], v[166:169], v[56:59]
	v_mfma_f32_16x16x32_bf16 v[40:43], v[142:145], v[188:191], v[40:43]
	v_mfma_f32_16x16x32_bf16 v[44:47], v[134:137], v[188:191], v[44:47]
	s_setprio 0
	s_setprio 1
	v_mfma_f32_16x16x32_bf16 v[28:31], v[134:137], v[196:199], v[28:31]
	v_mfma_f32_16x16x32_bf16 v[24:27], v[142:145], v[196:199], v[24:27]
	v_mfma_f32_16x16x32_bf16 v[8:11], v[142:145], v[204:207], v[8:11]
	v_mfma_f32_16x16x32_bf16 v[12:15], v[134:137], v[204:207], v[12:15]
	s_setprio 0
	s_setprio 1
	v_mfma_f32_16x16x32_bf16 v[60:63], v[138:141], v[184:187], v[60:63]
	v_mfma_f32_16x16x32_bf16 v[56:59], v[146:149], v[184:187], v[56:59]
	v_mfma_f32_16x16x32_bf16 v[40:43], v[146:149], v[192:195], v[40:43]
	v_mfma_f32_16x16x32_bf16 v[44:47], v[138:141], v[192:195], v[44:47]
	s_setprio 0
	s_setprio 1
	v_mfma_f32_16x16x32_bf16 v[28:31], v[138:141], v[200:203], v[28:31]
	v_mfma_f32_16x16x32_bf16 v[24:27], v[146:149], v[200:203], v[24:27]
	v_mfma_f32_16x16x32_bf16 v[8:11], v[146:149], v[208:211], v[8:11]
	v_mfma_f32_16x16x32_bf16 v[12:15], v[138:141], v[208:211], v[12:15]
	s_setprio 0
	s_setprio 1
	v_mfma_f32_16x16x32_bf16 v[52:55], v[150:153], v[166:169], v[52:55]
	v_mfma_f32_16x16x32_bf16 v[48:51], v[158:161], v[166:169], v[48:51]
	v_mfma_f32_16x16x32_bf16 v[32:35], v[158:161], v[188:191], v[32:35]
	v_mfma_f32_16x16x32_bf16 v[36:39], v[150:153], v[188:191], v[36:39]
	s_setprio 0
	s_setprio 1
	v_mfma_f32_16x16x32_bf16 v[20:23], v[150:153], v[196:199], v[20:23]
	v_mfma_f32_16x16x32_bf16 v[16:19], v[158:161], v[196:199], v[16:19]
	v_mfma_f32_16x16x32_bf16 v[0:3], v[158:161], v[204:207], v[0:3]
	v_mfma_f32_16x16x32_bf16 v[4:7], v[150:153], v[204:207], v[4:7]
	s_setprio 0
	s_setprio 1
	v_mfma_f32_16x16x32_bf16 v[52:55], v[154:157], v[184:187], v[52:55]
	v_mfma_f32_16x16x32_bf16 v[48:51], v[162:165], v[184:187], v[48:51]
	v_mfma_f32_16x16x32_bf16 v[32:35], v[162:165], v[192:195], v[32:35]
	v_mfma_f32_16x16x32_bf16 v[36:39], v[154:157], v[192:195], v[36:39]
	s_setprio 0
	s_setprio 1
	v_mfma_f32_16x16x32_bf16 v[20:23], v[154:157], v[200:203], v[20:23]
	v_mfma_f32_16x16x32_bf16 v[16:19], v[162:165], v[200:203], v[16:19]
	v_mfma_f32_16x16x32_bf16 v[0:3], v[162:165], v[208:211], v[0:3]
	v_mfma_f32_16x16x32_bf16 v[4:7], v[154:157], v[208:211], v[4:7]
	s_barrier
	s_setprio 0
	s_add_u32 s24, s24, 0x100
	s_addc_u32 s25, s25, 0
	s_add_u32 s46, s46, 0x100
	s_addc_u32 s47, s47, 0
	s_cmp_ge_i32 s48, s30
	s_mov_b32 s34, s48
	s_cbranch_scc1 .Lpeel_exit_lbb0_970
.LBB0_970:
	ds_read_b128 v[134:137], v175
	ds_read_b128 v[138:141], v175 offset:1024
	ds_read_b128 v[142:145], v176
	ds_read_b128 v[146:149], v176 offset:1024
	ds_read_b128 v[150:153], v177
	ds_read_b128 v[154:157], v177 offset:1024
	ds_read_b128 v[158:161], v178
	ds_read_b128 v[162:165], v178 offset:1024
	s_add_i32 s48, s34, 2
	s_add_u32 s16, s24, 0xfff00080
	s_addc_u32 s17, s25, -1
	s_cmp_eq_u32 s45, s34
	s_cselect_b32 s34, s15, s16
	s_cselect_b32 s35, s13, s17
	s_cselect_b32 s39, s27, s47
	s_cselect_b32 s38, s31, s46
	v_mov_b32_e32 v128, v172
	ds_read_b128 v[166:169], v179
	ds_read_b128 v[184:187], v179 offset:1024
	ds_read_b128 v[188:191], v179 offset:2048
	ds_read_b128 v[192:195], v179 offset:3072
	ds_read_b128 v[196:199], v179 offset:4096
	ds_read_b128 v[200:203], v179 offset:5120
	ds_read_b128 v[204:207], v179 offset:6144
	ds_read_b128 v[208:211], v179 offset:7168
	s_add_i32 m0, s87, 0xc000
	s_nop 0
	global_load_lds_dwordx4 v128, s[24:25]
	v_mov_b32_e32 v128, v173
	s_add_i32 m0, s87, 0xe000
	s_nop 0
	global_load_lds_dwordx4 v128, s[24:25]
	s_waitcnt vmcnt(8)
	s_waitcnt lgkmcnt(0)
	s_setprio 1
	s_barrier
; #define PG8_LDA(dst, b, h) do { if constexpr (FP8) { _Pragma("unroll") for (int m = 0; m < 4; ++m) dst##8[m] = PG8_LD8(PG8_SA(b, h), aoff, aoff1, m); } \
;         else { _Pragma("unroll") for (int m = 0; m < 4; ++m) _Pragma("unroll") for (int k = 0; k < 2; ++k) dst[m][k] = *(const LAS bf16x8*)(lds + PG8_SA(b, h) + (k ? aoff1 : aoff) + m * 2048); } } while (0)
; #define PG8_LDB(dst, b, h) do { if constexpr (FP8) { dst##8[0] = PG8_LD8(PG8_SB(b, h), boff, boff1, 0); dst##8[1] = PG8_LD8(PG8_SB(b, h), boff, boff1, 1); } \
;         else { _Pragma("unroll") for (int n = 0; n < 2; ++n) _Pragma("unroll") for (int k = 0; k < 2; ++k) dst[n][k] = *(const LAS bf16x8*)(lds + PG8_SB(b, h) + (k ? boff1 : boff) + n * 2048); } } while (0)
; #define PG8_WAIT_V(n) asm volatile("s_waitcnt vmcnt(" #n ")" ::: "memory")
; #define PG8_WAIT_L(n) asm volatile("s_waitcnt lgkmcnt(" #n ")" ::: "memory")
; #define PG8_BAR __builtin_amdgcn_s_barrier()
; #define PG8_SCHED __builtin_amdgcn_sched_barrier(0)
; #define PG8_S1 PG8_STAGE(PG8_SA(1, 1), a1 + hstepA, voffA)
; #define PG8_S2 do { PG8_STAGE(PG8_SB(0, 0), b2, voffB); PG8_STAGE(PG8_SB(0, 1), b2 + hstepB, voffB); PG8_STAGE(PG8_SA(0, 0), a2, voffA); } while (0)
; template <class Epi, class SchedT, bool ALIGN_EPI, bool SP2, bool FP8 = false>
; __device__ __forceinline__ void gemm_phase(LAS unsigned char* lds, const Gemm g, const SchedT& S, const Epi& E, const int wid) {
;     ...
;             PG8_LDB(B0, 0, 0); PG8_LDB(B1, 0, 1); PG8_SCHED; PG8_LDA(At, 0, 0); PG8_S1;
;             PG8_WAIT_V(8); PG8_WAIT_L(0); PG8_BAR; PG8_MMAP(0, 0, 0); PG8_BAR; PG8_SCHED;
;             PG8_LDA(At, 0, 1); PG8_S2;
;             PG8_WAIT_V(8); PG8_WAIT_L(0); PG8_BAR; PG8_MMAP(1, 0, 1); PG8_BAR; PG8_SCHED;
	v_mfma_f32_16x16x32_bf16 v[124:127], v[134:137], v[166:169], v[124:127]
	v_mfma_f32_16x16x32_bf16 v[120:123], v[142:145], v[166:169], v[120:123]
	v_mfma_f32_16x16x32_bf16 v[104:107], v[142:145], v[188:191], v[104:107]
	v_mfma_f32_16x16x32_bf16 v[108:111], v[134:137], v[188:191], v[108:111]
	s_setprio 0
	s_setprio 1
	v_mfma_f32_16x16x32_bf16 v[92:95], v[134:137], v[196:199], v[92:95]
	v_mfma_f32_16x16x32_bf16 v[88:91], v[142:145], v[196:199], v[88:91]
	v_mfma_f32_16x16x32_bf16 v[72:75], v[142:145], v[204:207], v[72:75]
	v_mfma_f32_16x16x32_bf16 v[76:79], v[134:137], v[204:207], v[76:79]
	s_setprio 0
	s_setprio 1
	v_mfma_f32_16x16x32_bf16 v[124:127], v[138:141], v[184:187], v[124:127]
	v_mfma_f32_16x16x32_bf16 v[120:123], v[146:149], v[184:187], v[120:123]
	v_mfma_f32_16x16x32_bf16 v[104:107], v[146:149], v[192:195], v[104:107]
	v_mfma_f32_16x16x32_bf16 v[108:111], v[138:141], v[192:195], v[108:111]
	s_setprio 0
	s_setprio 1
	v_mfma_f32_16x16x32_bf16 v[92:95], v[138:141], v[200:203], v[92:95]
	v_mfma_f32_16x16x32_bf16 v[88:91], v[146:149], v[200:203], v[88:91]
	v_mfma_f32_16x16x32_bf16 v[72:75], v[146:149], v[208:211], v[72:75]
	v_mfma_f32_16x16x32_bf16 v[76:79], v[138:141], v[208:211], v[76:79]
	s_setprio 0
	s_setprio 1
	v_mfma_f32_16x16x32_bf16 v[116:119], v[150:153], v[166:169], v[116:119]
	v_mfma_f32_16x16x32_bf16 v[112:115], v[158:161], v[166:169], v[112:115]
	v_mfma_f32_16x16x32_bf16 v[96:99], v[158:161], v[188:191], v[96:99]
	v_mfma_f32_16x16x32_bf16 v[100:103], v[150:153], v[188:191], v[100:103]
	s_setprio 0
	s_setprio 1
	v_mfma_f32_16x16x32_bf16 v[84:87], v[150:153], v[196:199], v[84:87]
	v_mfma_f32_16x16x32_bf16 v[80:83], v[158:161], v[196:199], v[80:83]
	v_mfma_f32_16x16x32_bf16 v[64:67], v[158:161], v[204:207], v[64:67]
	v_mfma_f32_16x16x32_bf16 v[68:71], v[150:153], v[204:207], v[68:71]
	s_setprio 0
	s_setprio 1
	v_mfma_f32_16x16x32_bf16 v[116:119], v[154:157], v[184:187], v[116:119]
	v_mfma_f32_16x16x32_bf16 v[112:115], v[162:165], v[184:187], v[112:115]
	v_mfma_f32_16x16x32_bf16 v[96:99], v[162:165], v[192:195], v[96:99]
	v_mfma_f32_16x16x32_bf16 v[100:103], v[154:157], v[192:195], v[100:103]
	s_setprio 0
	s_setprio 1
	v_mfma_f32_16x16x32_bf16 v[84:87], v[154:157], v[200:203], v[84:87]
	v_mfma_f32_16x16x32_bf16 v[80:83], v[162:165], v[200:203], v[80:83]
	v_mfma_f32_16x16x32_bf16 v[64:67], v[162:165], v[208:211], v[64:67]
	v_mfma_f32_16x16x32_bf16 v[68:71], v[154:157], v[208:211], v[68:71]
	s_barrier
	s_setprio 0
	v_mov_b32_e32 v128, v172
	s_add_i32 s16, s94, s86
	ds_read_b128 v[166:169], v179 offset:16384
	ds_read_b128 v[184:187], v179 offset:17408
	ds_read_b128 v[188:191], v179 offset:18432
	ds_read_b128 v[192:195], v179 offset:19456
	ds_read_b128 v[196:199], v179 offset:20480
	ds_read_b128 v[200:203], v179 offset:21504
	ds_read_b128 v[204:207], v179 offset:22528
	ds_read_b128 v[208:211], v179 offset:23552
	s_mov_b32 m0, s16
	s_nop 0
	global_load_lds_dwordx4 v128, s[38:39]
	v_mov_b32_e32 v128, v173
	s_add_i32 m0, s16, 0x2000
	s_add_u32 s50, s38, 0x100000
	global_load_lds_dwordx4 v128, s[38:39]
	s_addc_u32 s51, s39, 0
	v_mov_b32_e32 v128, v172
	s_add_i32 s16, s95, s86
	s_mov_b32 m0, s16
	s_nop 0
	global_load_lds_dwordx4 v128, s[50:51]
	v_mov_b32_e32 v128, v173
	s_add_i32 m0, s16, 0x2000
	s_nop 0
	global_load_lds_dwordx4 v128, s[50:51]
	v_mov_b32_e32 v128, v172
	s_mov_b32 m0, s87
	s_nop 0
	global_load_lds_dwordx4 v128, s[34:35]
	v_mov_b32_e32 v128, v173
	s_mov_b32 m0, s88
	s_nop 0
	global_load_lds_dwordx4 v128, s[34:35]
	s_waitcnt vmcnt(8)
	s_waitcnt lgkmcnt(0)
	s_setprio 1
	s_barrier
	v_mfma_f32_16x16x32_bf16 v[60:63], v[134:137], v[166:169], v[60:63]
	v_mfma_f32_16x16x32_bf16 v[56:59], v[142:145], v[166:169], v[56:59]
	v_mfma_f32_16x16x32_bf16 v[40:43], v[142:145], v[188:191], v[40:43]
	v_mfma_f32_16x16x32_bf16 v[44:47], v[134:137], v[188:191], v[44:47]
	s_setprio 0
	s_setprio 1
	v_mfma_f32_16x16x32_bf16 v[28:31], v[134:137], v[196:199], v[28:31]
	v_mfma_f32_16x16x32_bf16 v[24:27], v[142:145], v[196:199], v[24:27]
	v_mfma_f32_16x16x32_bf16 v[8:11], v[142:145], v[204:207], v[8:11]
	v_mfma_f32_16x16x32_bf16 v[12:15], v[134:137], v[204:207], v[12:15]
	s_setprio 0
	s_setprio 1
	v_mfma_f32_16x16x32_bf16 v[60:63], v[138:141], v[184:187], v[60:63]
	v_mfma_f32_16x16x32_bf16 v[56:59], v[146:149], v[184:187], v[56:59]
	v_mfma_f32_16x16x32_bf16 v[40:43], v[146:149], v[192:195], v[40:43]
	v_mfma_f32_16x16x32_bf16 v[44:47], v[138:141], v[192:195], v[44:47]
	s_setprio 0
	s_setprio 1
	v_mfma_f32_16x16x32_bf16 v[28:31], v[138:141], v[200:203], v[28:31]
	v_mfma_f32_16x16x32_bf16 v[24:27], v[146:149], v[200:203], v[24:27]
	v_mfma_f32_16x16x32_bf16 v[8:11], v[146:149], v[208:211], v[8:11]
	v_mfma_f32_16x16x32_bf16 v[12:15], v[138:141], v[208:211], v[12:15]
	s_setprio 0
	s_setprio 1
	v_mfma_f32_16x16x32_bf16 v[52:55], v[150:153], v[166:169], v[52:55]
	v_mfma_f32_16x16x32_bf16 v[48:51], v[158:161], v[166:169], v[48:51]
	v_mfma_f32_16x16x32_bf16 v[32:35], v[158:161], v[188:191], v[32:35]
	v_mfma_f32_16x16x32_bf16 v[36:39], v[150:153], v[188:191], v[36:39]
	s_setprio 0
	s_setprio 1
	v_mfma_f32_16x16x32_bf16 v[20:23], v[150:153], v[196:199], v[20:23]
	v_mfma_f32_16x16x32_bf16 v[16:19], v[158:161], v[196:199], v[16:19]
	v_mfma_f32_16x16x32_bf16 v[0:3], v[158:161], v[204:207], v[0:3]
	v_mfma_f32_16x16x32_bf16 v[4:7], v[150:153], v[204:207], v[4:7]
	s_setprio 0
	s_setprio 1
	v_mfma_f32_16x16x32_bf16 v[52:55], v[154:157], v[184:187], v[52:55]
	v_mfma_f32_16x16x32_bf16 v[48:51], v[162:165], v[184:187], v[48:51]
	v_mfma_f32_16x16x32_bf16 v[32:35], v[162:165], v[192:195], v[32:35]
	v_mfma_f32_16x16x32_bf16 v[36:39], v[154:157], v[192:195], v[36:39]
	s_setprio 0
	s_setprio 1
	v_mfma_f32_16x16x32_bf16 v[20:23], v[154:157], v[200:203], v[20:23]
	v_mfma_f32_16x16x32_bf16 v[16:19], v[162:165], v[200:203], v[16:19]
	v_mfma_f32_16x16x32_bf16 v[0:3], v[162:165], v[208:211], v[0:3]
	v_mfma_f32_16x16x32_bf16 v[4:7], v[154:157], v[208:211], v[4:7]
	s_barrier
; #define PG8_LDA(dst, b, h) do { if constexpr (FP8) { _Pragma("unroll") for (int m = 0; m < 4; ++m) dst##8[m] = PG8_LD8(PG8_SA(b, h), aoff, aoff1, m); } \
;         else { _Pragma("unroll") for (int m = 0; m < 4; ++m) _Pragma("unroll") for (int k = 0; k < 2; ++k) dst[m][k] = *(const LAS bf16x8*)(lds + PG8_SA(b, h) + (k ? aoff1 : aoff) + m * 2048); } } while (0)
; #define PG8_LDB(dst, b, h) do { if constexpr (FP8) { dst##8[0] = PG8_LD8(PG8_SB(b, h), boff, boff1, 0); dst##8[1] = PG8_LD8(PG8_SB(b, h), boff, boff1, 1); } \
;         else { _Pragma("unroll") for (int n = 0; n < 2; ++n) _Pragma("unroll") for (int k = 0; k < 2; ++k) dst[n][k] = *(const LAS bf16x8*)(lds + PG8_SB(b, h) + (k ? boff1 : boff) + n * 2048); } } while (0)
; #define PG8_WAIT_V(n) asm volatile("s_waitcnt vmcnt(" #n ")" ::: "memory")
; #define PG8_WAIT_L(n) asm volatile("s_waitcnt lgkmcnt(" #n ")" ::: "memory")
; #define PG8_BAR __builtin_amdgcn_s_barrier()
; #define PG8_SCHED __builtin_amdgcn_sched_barrier(0)
; #define PG8_S3 PG8_STAGE(PG8_SA(0, 1), a2 + hstepA, voffA)
; template <class Epi, class SchedT, bool ALIGN_EPI, bool SP2, bool FP8 = false>
; __device__ __forceinline__ void gemm_phase(LAS unsigned char* lds, const Gemm g, const SchedT& S, const Epi& E, const int wid) {
;     ...
;             PG8_LDB(B0, 1, 0); PG8_LDB(B1, 1, 1); PG8_SCHED; PG8_LDA(At, 1, 0); PG8_S3;
;             PG8_WAIT_V(8); PG8_WAIT_L(0); PG8_BAR; PG8_MMAP(0, 1, 0); PG8_BAR; PG8_SCHED;
	s_setprio 0
	s_add_i32 s16, 0, 0x18000
	v_add_u32_e32 v128, s16, v174
	s_add_i32 s17, 0, 0x1c000
	ds_read_b128 v[134:137], v128
	ds_read_b128 v[138:141], v128 offset:1024
	ds_read_b128 v[142:145], v180
	ds_read_b128 v[146:149], v180 offset:1024
	v_add_u32_e32 v128, s17, v174
	ds_read_b128 v[150:153], v128
	ds_read_b128 v[154:157], v128 offset:1024
	ds_read_b128 v[158:161], v181
	ds_read_b128 v[162:165], v181 offset:1024
	s_add_u32 s50, s34, 0x100000
	v_mov_b32_e32 v128, v172
	s_mov_b32 m0, s89
	ds_read_b128 v[166:169], v179 offset:32768
	ds_read_b128 v[184:187], v179 offset:33792
	ds_read_b128 v[188:191], v179 offset:34816
	ds_read_b128 v[192:195], v179 offset:35840
	ds_read_b128 v[196:199], v179 offset:36864
	ds_read_b128 v[200:203], v179 offset:37888
	ds_read_b128 v[204:207], v179 offset:38912
	ds_read_b128 v[208:211], v179 offset:39936
	s_addc_u32 s51, s35, 0
	s_nop 0
	global_load_lds_dwordx4 v128, s[50:51]
	v_mov_b32_e32 v128, v173
	s_mov_b32 m0, s90
	s_nop 0
	global_load_lds_dwordx4 v128, s[50:51]
	s_waitcnt vmcnt(8)
	s_waitcnt lgkmcnt(0)
	s_setprio 1
	s_barrier
	v_mfma_f32_16x16x32_bf16 v[124:127], v[134:137], v[166:169], v[124:127]
	v_mfma_f32_16x16x32_bf16 v[120:123], v[142:145], v[166:169], v[120:123]
	v_mfma_f32_16x16x32_bf16 v[104:107], v[142:145], v[188:191], v[104:107]
	v_mfma_f32_16x16x32_bf16 v[108:111], v[134:137], v[188:191], v[108:111]
	s_setprio 0
	s_setprio 1
	v_mfma_f32_16x16x32_bf16 v[92:95], v[134:137], v[196:199], v[92:95]
	v_mfma_f32_16x16x32_bf16 v[88:91], v[142:145], v[196:199], v[88:91]
	v_mfma_f32_16x16x32_bf16 v[72:75], v[142:145], v[204:207], v[72:75]
	v_mfma_f32_16x16x32_bf16 v[76:79], v[134:137], v[204:207], v[76:79]
	s_setprio 0
	s_setprio 1
	v_mfma_f32_16x16x32_bf16 v[124:127], v[138:141], v[184:187], v[124:127]
	v_mfma_f32_16x16x32_bf16 v[120:123], v[146:149], v[184:187], v[120:123]
	v_mfma_f32_16x16x32_bf16 v[104:107], v[146:149], v[192:195], v[104:107]
	v_mfma_f32_16x16x32_bf16 v[108:111], v[138:141], v[192:195], v[108:111]
	s_setprio 0
	s_setprio 1
	v_mfma_f32_16x16x32_bf16 v[92:95], v[138:141], v[200:203], v[92:95]
	v_mfma_f32_16x16x32_bf16 v[88:91], v[146:149], v[200:203], v[88:91]
	v_mfma_f32_16x16x32_bf16 v[72:75], v[146:149], v[208:211], v[72:75]
	v_mfma_f32_16x16x32_bf16 v[76:79], v[138:141], v[208:211], v[76:79]
	s_setprio 0
	s_setprio 1
	v_mfma_f32_16x16x32_bf16 v[116:119], v[150:153], v[166:169], v[116:119]
	v_mfma_f32_16x16x32_bf16 v[112:115], v[158:161], v[166:169], v[112:115]
	v_mfma_f32_16x16x32_bf16 v[96:99], v[158:161], v[188:191], v[96:99]
	v_mfma_f32_16x16x32_bf16 v[100:103], v[150:153], v[188:191], v[100:103]
	s_setprio 0
	s_setprio 1
	v_mfma_f32_16x16x32_bf16 v[84:87], v[150:153], v[196:199], v[84:87]
	v_mfma_f32_16x16x32_bf16 v[80:83], v[158:161], v[196:199], v[80:83]
	v_mfma_f32_16x16x32_bf16 v[64:67], v[158:161], v[204:207], v[64:67]
	v_mfma_f32_16x16x32_bf16 v[68:71], v[150:153], v[204:207], v[68:71]
	s_setprio 0
	s_setprio 1
	v_mfma_f32_16x16x32_bf16 v[116:119], v[154:157], v[184:187], v[116:119]
	v_mfma_f32_16x16x32_bf16 v[112:115], v[162:165], v[184:187], v[112:115]
	v_mfma_f32_16x16x32_bf16 v[96:99], v[162:165], v[192:195], v[96:99]
	v_mfma_f32_16x16x32_bf16 v[100:103], v[154:157], v[192:195], v[100:103]
	s_setprio 0
	s_setprio 1
	v_mfma_f32_16x16x32_bf16 v[84:87], v[154:157], v[200:203], v[84:87]
	v_mfma_f32_16x16x32_bf16 v[80:83], v[162:165], v[200:203], v[80:83]
	v_mfma_f32_16x16x32_bf16 v[64:67], v[162:165], v[208:211], v[64:67]
	v_mfma_f32_16x16x32_bf16 v[68:71], v[154:157], v[208:211], v[68:71]
	s_barrier
; #define PG8_LDA(dst, b, h) do { if constexpr (FP8) { _Pragma("unroll") for (int m = 0; m < 4; ++m) dst##8[m] = PG8_LD8(PG8_SA(b, h), aoff, aoff1, m); } \
;         else { _Pragma("unroll") for (int m = 0; m < 4; ++m) _Pragma("unroll") for (int k = 0; k < 2; ++k) dst[m][k] = *(const LAS bf16x8*)(lds + PG8_SA(b, h) + (k ? aoff1 : aoff) + m * 2048); } } while (0)
; #define PG8_WAIT_V(n) asm volatile("s_waitcnt vmcnt(" #n ")" ::: "memory")
; #define PG8_WAIT_L(n) asm volatile("s_waitcnt lgkmcnt(" #n ")" ::: "memory")
; #define PG8_BAR __builtin_amdgcn_s_barrier()
; #define PG8_SCHED __builtin_amdgcn_sched_barrier(0)
; #define PG8_S4 do { PG8_STAGE(PG8_SB(1, 0), b3, voffB); PG8_STAGE(PG8_SB(1, 1), b3 + hstepB, voffB); PG8_STAGE(PG8_SA(1, 0), a3, voffA); } while (0)
; template <class Epi, class SchedT, bool ALIGN_EPI, bool SP2, bool FP8 = false>
; __device__ __forceinline__ void gemm_phase(LAS unsigned char* lds, const Gemm g, const SchedT& S, const Epi& E, const int wid) {
;     ...
;             PG8_LDA(At, 1, 1); PG8_S4;
;             PG8_WAIT_V(8); PG8_WAIT_L(0); PG8_BAR; PG8_MMAP(1, 1, 1); PG8_BAR; PG8_SCHED;
	s_setprio 0
	v_mov_b32_e32 v128, v172
	ds_read_b128 v[166:169], v179 offset:49152
	ds_read_b128 v[184:187], v179 offset:50176
	ds_read_b128 v[188:191], v179 offset:51200
	ds_read_b128 v[192:195], v179 offset:52224
	ds_read_b128 v[196:199], v179 offset:53248
	ds_read_b128 v[200:203], v179 offset:54272
	ds_read_b128 v[204:207], v179 offset:55296
	ds_read_b128 v[208:211], v179 offset:56320
	s_add_i32 s16, s16, s86
	v_lshl_add_u64 v[170:171], s[38:39], 0, v[128:129]
	v_lshl_add_u64 v[170:171], v[170:171], 0, s[8:9]
	s_mov_b32 m0, s16
	v_mov_b32_e32 v128, v173
	global_load_lds_dwordx4 v[170:171], off
	s_add_i32 m0, s16, 0x2000
	s_nop 0
	v_lshl_add_u64 v[170:171], s[38:39], 0, v[128:129]
	s_add_u32 s38, s38, 0x100080
	v_lshl_add_u64 v[170:171], v[170:171], 0, s[8:9]
	s_addc_u32 s39, s39, 0
	v_mov_b32_e32 v128, v172
	s_add_i32 s16, s17, s86
	global_load_lds_dwordx4 v[170:171], off
	s_mov_b32 m0, s16
	s_nop 0
	global_load_lds_dwordx4 v128, s[38:39]
	v_mov_b32_e32 v128, v173
	s_add_i32 m0, s16, 0x2000
	s_nop 0
	global_load_lds_dwordx4 v128, s[38:39]
	v_mov_b32_e32 v128, v172
	s_mov_b32 m0, s92
	v_lshl_add_u64 v[170:171], s[34:35], 0, v[128:129]
	v_lshl_add_u64 v[170:171], v[170:171], 0, s[8:9]
	v_mov_b32_e32 v128, v173
	global_load_lds_dwordx4 v[170:171], off
	s_mov_b32 m0, s93
	v_lshl_add_u64 v[170:171], s[34:35], 0, v[128:129]
	v_lshl_add_u64 v[170:171], v[170:171], 0, s[8:9]
	global_load_lds_dwordx4 v[170:171], off
	s_waitcnt vmcnt(8)
	s_waitcnt lgkmcnt(0)
	s_setprio 1
	s_barrier
	v_mfma_f32_16x16x32_bf16 v[60:63], v[134:137], v[166:169], v[60:63]
	v_mfma_f32_16x16x32_bf16 v[56:59], v[142:145], v[166:169], v[56:59]
	v_mfma_f32_16x16x32_bf16 v[40:43], v[142:145], v[188:191], v[40:43]
	v_mfma_f32_16x16x32_bf16 v[44:47], v[134:137], v[188:191], v[44:47]
	s_setprio 0
	s_setprio 1
	v_mfma_f32_16x16x32_bf16 v[28:31], v[134:137], v[196:199], v[28:31]
	v_mfma_f32_16x16x32_bf16 v[24:27], v[142:145], v[196:199], v[24:27]
	v_mfma_f32_16x16x32_bf16 v[8:11], v[142:145], v[204:207], v[8:11]
	v_mfma_f32_16x16x32_bf16 v[12:15], v[134:137], v[204:207], v[12:15]
	s_setprio 0
	s_setprio 1
	v_mfma_f32_16x16x32_bf16 v[60:63], v[138:141], v[184:187], v[60:63]
	v_mfma_f32_16x16x32_bf16 v[56:59], v[146:149], v[184:187], v[56:59]
	v_mfma_f32_16x16x32_bf16 v[40:43], v[146:149], v[192:195], v[40:43]
	v_mfma_f32_16x16x32_bf16 v[44:47], v[138:141], v[192:195], v[44:47]
	s_setprio 0
	s_setprio 1
	v_mfma_f32_16x16x32_bf16 v[28:31], v[138:141], v[200:203], v[28:31]
	v_mfma_f32_16x16x32_bf16 v[24:27], v[146:149], v[200:203], v[24:27]
	v_mfma_f32_16x16x32_bf16 v[8:11], v[146:149], v[208:211], v[8:11]
	v_mfma_f32_16x16x32_bf16 v[12:15], v[138:141], v[208:211], v[12:15]
	s_setprio 0
	s_setprio 1
	v_mfma_f32_16x16x32_bf16 v[52:55], v[150:153], v[166:169], v[52:55]
	v_mfma_f32_16x16x32_bf16 v[48:51], v[158:161], v[166:169], v[48:51]
	v_mfma_f32_16x16x32_bf16 v[32:35], v[158:161], v[188:191], v[32:35]
	v_mfma_f32_16x16x32_bf16 v[36:39], v[150:153], v[188:191], v[36:39]
	s_setprio 0
	s_setprio 1
	v_mfma_f32_16x16x32_bf16 v[20:23], v[150:153], v[196:199], v[20:23]
	v_mfma_f32_16x16x32_bf16 v[16:19], v[158:161], v[196:199], v[16:19]
	v_mfma_f32_16x16x32_bf16 v[0:3], v[158:161], v[204:207], v[0:3]
	v_mfma_f32_16x16x32_bf16 v[4:7], v[150:153], v[204:207], v[4:7]
	s_setprio 0
	s_setprio 1
	v_mfma_f32_16x16x32_bf16 v[52:55], v[154:157], v[184:187], v[52:55]
	v_mfma_f32_16x16x32_bf16 v[48:51], v[162:165], v[184:187], v[48:51]
	v_mfma_f32_16x16x32_bf16 v[32:35], v[162:165], v[192:195], v[32:35]
	v_mfma_f32_16x16x32_bf16 v[36:39], v[154:157], v[192:195], v[36:39]
	s_setprio 0
	s_setprio 1
	v_mfma_f32_16x16x32_bf16 v[20:23], v[154:157], v[200:203], v[20:23]
	v_mfma_f32_16x16x32_bf16 v[16:19], v[162:165], v[200:203], v[16:19]
	v_mfma_f32_16x16x32_bf16 v[0:3], v[162:165], v[208:211], v[0:3]
	v_mfma_f32_16x16x32_bf16 v[4:7], v[154:157], v[208:211], v[4:7]
	s_barrier
	s_setprio 0
	s_add_u32 s24, s24, 0x100
	s_addc_u32 s25, s25, 0
	s_add_u32 s46, s46, 0x100
	s_addc_u32 s47, s47, 0
	s_cmp_ge_i32 s48, s30
	s_mov_b32 s34, s48
	s_cbranch_scc0 .LBB0_970
